# late ALIGN barrier variant plus the redundant post-barrier lgkmcnt(0) removed from the K-loops
# speedup vs baseline: 1.0045x; 1.0045x over previous
; #define PG8_STAGE(bufoff, gbase, voff) do { _Pragma("unroll") for (int _i = 0; _i < 2; ++_i) \
;         __builtin_amdgcn_global_load_lds((const unsigned*)((const char*)(gbase) + (voff)[_i]), (LAS unsigned*)(lds + (bufoff) + ldsw + _i * 8192), 16, 0, 0); } while (0)
; #define PG8_LDA(dst, b, h) do { _Pragma("unroll") for (int m = 0; m < 4; ++m) _Pragma("unroll") for (int k = 0; k < 2; ++k) dst[m][k] = *(const LAS bf16x8*)(lds + PG8_SA(b, h) + aoff + m * 2048 + k * 1024); } while (0)
; #define PG8_LDB(dst, b, h) do { _Pragma("unroll") for (int n = 0; n < 2; ++n) _Pragma("unroll") for (int k = 0; k < 2; ++k) dst[n][k] = *(const LAS bf16x8*)(lds + PG8_SB(b, h) + boff + n * 2048 + k * 1024); } while (0)
; #define PG8_MMA(ai, bj, At, Bt) do { __builtin_amdgcn_s_setprio(1); _Pragma("unroll") for (int m = 0; m < 4; ++m) _Pragma("unroll") for (int n = 0; n < 2; ++n) _Pragma("unroll") for (int k = 0; k < 2; ++k) \
;         acc[ai][bj][m][n] = __builtin_amdgcn_mfma_f32_16x16x32_bf16(Bt[n][k], At[m][k], acc[ai][bj][m][n], 0, 0, 0); __builtin_amdgcn_s_setprio(0); } while (0)
; #define PG8_WAIT_V(n) asm volatile("s_waitcnt vmcnt(" #n ")" ::: "memory")
; #define PG8_WAIT_L(n) asm volatile("s_waitcnt lgkmcnt(" #n ")" ::: "memory")
; #define PG8_BAR __builtin_amdgcn_s_barrier()
; #define PG8_SCHED __builtin_amdgcn_sched_barrier(0)
; template <class Epi, class Map>
; __device__ __forceinline__ void gemm_phase(LAS unsigned char* lds, const Gemm g, const Sched<Map>& S, const Epi& E) {
;     ...
;         for (int t = 0; t < nt; t += 2) {
;             const bool last = (t == nt - 2);
;             const char* a1 = cA + (size_t)(t + 1) * kstep;
;             const char* a2 = last ? nA : cA + (size_t)(t + 2) * kstep; const char* b2 = last ? nB : cB + (size_t)(t + 2) * kstep;
;             const char* a3 = a2 + kstep; const char* b3 = b2 + kstep;
;             PG8_LDB(B0, 0, 0); PG8_LDB(B1, 0, 1); PG8_SCHED; PG8_LDA(At, 0, 0); PG8_STAGE(PG8_SA(1, 1), a1 + hstepA, voffA);
;             PG8_WAIT_V(8); PG8_WAIT_L(0); PG8_BAR; PG8_MMA(0, 0, At, B0); PG8_MMA(0, 1, At, B1); PG8_BAR; PG8_SCHED;
.LBB0_223:
	s_add_u32 s48, s42, s46
	s_addc_u32 s49, s43, s47
	s_add_u32 s48, s48, 0x100
	s_addc_u32 s49, s49, 0
	s_add_u32 s62, s65, s46
	s_addc_u32 s63, s66, s47
	s_add_i32 s68, 0, 0x10000
	s_cmpk_eq_i32 s46, 0xf00
	s_cselect_b32 s51, s56, s49
	s_cselect_b32 s50, s57, s48
	v_add_u32_e32 v136, s68, v170
	s_cselect_b32 s49, s58, s63
	s_cselect_b32 s48, s59, s62
	s_add_i32 s62, 0, 0x14000
	ds_read_b128 v[132:135], v136
	ds_read_b128 v[162:165], v136 offset:1024
	ds_read_b128 v[172:175], v136 offset:2048
	ds_read_b128 v[176:179], v136 offset:3072
	v_add_u32_e32 v136, s62, v170
	ds_read_b128 v[192:195], v136
	ds_read_b128 v[196:199], v136 offset:1024
	ds_read_b128 v[200:203], v136 offset:2048
	ds_read_b128 v[204:207], v136 offset:3072
	v_lshl_add_u64 v[136:137], v[130:131], 0, s[46:47]
	s_add_i32 m0, s6, 0xc000
	ds_read_b128 v[208:211], v171
	ds_read_b128 v[212:215], v171 offset:1024
	ds_read_b128 v[216:219], v171 offset:2048
	ds_read_b128 v[220:223], v171 offset:3072
	ds_read_b128 v[224:227], v171 offset:4096
	ds_read_b128 v[228:231], v171 offset:5120
	ds_read_b128 v[232:235], v171 offset:6144
	ds_read_b128 v[236:239], v171 offset:7168
	global_load_lds_dwordx4 v[136:137], off
	v_lshl_add_u64 v[136:137], v[128:129], 0, s[46:47]
	s_add_i32 m0, s6, 0xe000
	s_nop 0
	global_load_lds_dwordx4 v[136:137], off
	s_waitcnt vmcnt(8)
	s_waitcnt lgkmcnt(0)
	s_barrier
	v_mfma_f32_16x16x32_bf16 v[124:127], v[132:135], v[208:211], v[124:127]
	v_mfma_f32_16x16x32_bf16 v[120:123], v[172:175], v[208:211], v[120:123]
	v_mfma_f32_16x16x32_bf16 v[108:111], v[132:135], v[216:219], v[108:111]
	v_mfma_f32_16x16x32_bf16 v[104:107], v[172:175], v[216:219], v[104:107]
	v_mfma_f32_16x16x32_bf16 v[92:95], v[132:135], v[224:227], v[92:95]
	v_mfma_f32_16x16x32_bf16 v[88:91], v[172:175], v[224:227], v[88:91]
	v_mfma_f32_16x16x32_bf16 v[76:79], v[132:135], v[232:235], v[76:79]
	v_mfma_f32_16x16x32_bf16 v[72:75], v[172:175], v[232:235], v[72:75]
	v_mfma_f32_16x16x32_bf16 v[124:127], v[162:165], v[212:215], v[124:127]
	v_mfma_f32_16x16x32_bf16 v[120:123], v[176:179], v[212:215], v[120:123]
	v_mfma_f32_16x16x32_bf16 v[108:111], v[162:165], v[220:223], v[108:111]
	v_mfma_f32_16x16x32_bf16 v[104:107], v[176:179], v[220:223], v[104:107]
	v_mfma_f32_16x16x32_bf16 v[92:95], v[162:165], v[228:231], v[92:95]
	v_mfma_f32_16x16x32_bf16 v[88:91], v[176:179], v[228:231], v[88:91]
	v_mfma_f32_16x16x32_bf16 v[76:79], v[162:165], v[236:239], v[76:79]
	v_mfma_f32_16x16x32_bf16 v[72:75], v[176:179], v[236:239], v[72:75]
	v_mfma_f32_16x16x32_bf16 v[116:119], v[192:195], v[208:211], v[116:119]
	v_mfma_f32_16x16x32_bf16 v[112:115], v[200:203], v[208:211], v[112:115]
	v_mfma_f32_16x16x32_bf16 v[100:103], v[192:195], v[216:219], v[100:103]
	v_mfma_f32_16x16x32_bf16 v[96:99], v[200:203], v[216:219], v[96:99]
	v_mfma_f32_16x16x32_bf16 v[84:87], v[192:195], v[224:227], v[84:87]
	v_mfma_f32_16x16x32_bf16 v[80:83], v[200:203], v[224:227], v[80:83]
	v_mfma_f32_16x16x32_bf16 v[68:71], v[192:195], v[232:235], v[68:71]
	v_mfma_f32_16x16x32_bf16 v[64:67], v[200:203], v[232:235], v[64:67]
	v_mfma_f32_16x16x32_bf16 v[116:119], v[196:199], v[212:215], v[116:119]
	v_mfma_f32_16x16x32_bf16 v[112:115], v[204:207], v[212:215], v[112:115]
	v_mfma_f32_16x16x32_bf16 v[100:103], v[196:199], v[220:223], v[100:103]
	v_mfma_f32_16x16x32_bf16 v[96:99], v[204:207], v[220:223], v[96:99]
	v_mfma_f32_16x16x32_bf16 v[84:87], v[196:199], v[228:231], v[84:87]
	v_mfma_f32_16x16x32_bf16 v[80:83], v[204:207], v[228:231], v[80:83]
	v_mfma_f32_16x16x32_bf16 v[68:71], v[196:199], v[236:239], v[68:71]
	v_mfma_f32_16x16x32_bf16 v[64:67], v[204:207], v[236:239], v[64:67]
	s_barrier
	s_add_i32 s63, s68, s5
	v_lshl_add_u64 v[136:137], s[48:49], 0, v[144:145]
	s_mov_b32 m0, s63
	ds_read_b128 v[208:211], v171 offset:16384
	ds_read_b128 v[212:215], v171 offset:17408
	ds_read_b128 v[216:219], v171 offset:18432
	ds_read_b128 v[220:223], v171 offset:19456
	ds_read_b128 v[224:227], v171 offset:20480
	ds_read_b128 v[228:231], v171 offset:21504
	ds_read_b128 v[232:235], v171 offset:22528
	ds_read_b128 v[236:239], v171 offset:23552
	global_load_lds_dwordx4 v[136:137], off
	s_add_i32 m0, s63, 0x2000
	s_add_u32 s68, s48, 0x80000
	v_lshl_add_u64 v[166:167], s[48:49], 0, v[142:143]
	s_addc_u32 s69, s49, 0
	s_add_i32 s62, s62, s5
	global_load_lds_dwordx4 v[166:167], off
	v_lshl_add_u64 v[180:181], s[68:69], 0, v[144:145]
	s_mov_b32 m0, s62
	v_lshl_add_u64 v[240:241], s[50:51], 0, v[140:141]
	global_load_lds_dwordx4 v[180:181], off
	v_lshl_add_u64 v[180:181], s[68:69], 0, v[142:143]
	s_add_i32 m0, s62, 0x2000
	s_nop 0
	global_load_lds_dwordx4 v[180:181], off
	v_lshl_add_u64 v[180:181], s[50:51], 0, v[138:139]
	s_mov_b32 m0, s6
	s_nop 0
	global_load_lds_dwordx4 v[180:181], off
	s_mov_b32 m0, s7
	s_nop 0
	global_load_lds_dwordx4 v[240:241], off
	s_waitcnt vmcnt(8)
	s_waitcnt lgkmcnt(0)
	s_barrier
; #define PG8_STAGE(bufoff, gbase, voff) do { _Pragma("unroll") for (int _i = 0; _i < 2; ++_i) \
;         __builtin_amdgcn_global_load_lds((const unsigned*)((const char*)(gbase) + (voff)[_i]), (LAS unsigned*)(lds + (bufoff) + ldsw + _i * 8192), 16, 0, 0); } while (0)
; #define PG8_LDA(dst, b, h) do { _Pragma("unroll") for (int m = 0; m < 4; ++m) _Pragma("unroll") for (int k = 0; k < 2; ++k) dst[m][k] = *(const LAS bf16x8*)(lds + PG8_SA(b, h) + aoff + m * 2048 + k * 1024); } while (0)
; #define PG8_LDB(dst, b, h) do { _Pragma("unroll") for (int n = 0; n < 2; ++n) _Pragma("unroll") for (int k = 0; k < 2; ++k) dst[n][k] = *(const LAS bf16x8*)(lds + PG8_SB(b, h) + boff + n * 2048 + k * 1024); } while (0)
; #define PG8_MMA(ai, bj, At, Bt) do { __builtin_amdgcn_s_setprio(1); _Pragma("unroll") for (int m = 0; m < 4; ++m) _Pragma("unroll") for (int n = 0; n < 2; ++n) _Pragma("unroll") for (int k = 0; k < 2; ++k) \
;         acc[ai][bj][m][n] = __builtin_amdgcn_mfma_f32_16x16x32_bf16(Bt[n][k], At[m][k], acc[ai][bj][m][n], 0, 0, 0); __builtin_amdgcn_s_setprio(0); } while (0)
; #define PG8_WAIT_V(n) asm volatile("s_waitcnt vmcnt(" #n ")" ::: "memory")
; #define PG8_WAIT_L(n) asm volatile("s_waitcnt lgkmcnt(" #n ")" ::: "memory")
; #define PG8_BAR __builtin_amdgcn_s_barrier()
; #define PG8_SCHED __builtin_amdgcn_sched_barrier(0)
; template <class Epi, class Map>
; __device__ __forceinline__ void gemm_phase(LAS unsigned char* lds, const Gemm g, const Sched<Map>& S, const Epi& E) {
;     ...
;             PG8_WAIT_V(8); PG8_WAIT_L(0); PG8_BAR; PG8_MMA(0, 0, At, B0); PG8_MMA(0, 1, At, B1); PG8_BAR; PG8_SCHED;
;             PG8_LDA(At, 0, 1); PG8_STAGE(PG8_SB(0, 0), b2, voffB); PG8_STAGE(PG8_SB(0, 1), b2 + hstepB, voffB); PG8_STAGE(PG8_SA(0, 0), a2, voffA);
;             PG8_WAIT_V(8); PG8_WAIT_L(0); PG8_BAR; PG8_MMA(1, 0, At, B0); PG8_MMA(1, 1, At, B1); PG8_BAR; PG8_SCHED;
;             PG8_LDB(B0, 1, 0); PG8_LDB(B1, 1, 1); PG8_SCHED; PG8_LDA(At, 1, 0); PG8_STAGE(PG8_SA(0, 1), a2 + hstepA, voffA);
;             PG8_WAIT_V(8); PG8_WAIT_L(0); PG8_BAR; PG8_MMA(0, 0, At, B0); PG8_MMA(0, 1, At, B1); PG8_BAR; PG8_SCHED;
	v_mfma_f32_16x16x32_bf16 v[60:63], v[132:135], v[208:211], v[60:63]
	v_mfma_f32_16x16x32_bf16 v[56:59], v[172:175], v[208:211], v[56:59]
	v_mfma_f32_16x16x32_bf16 v[44:47], v[132:135], v[216:219], v[44:47]
	v_mfma_f32_16x16x32_bf16 v[40:43], v[172:175], v[216:219], v[40:43]
	v_mfma_f32_16x16x32_bf16 v[28:31], v[132:135], v[224:227], v[28:31]
	v_mfma_f32_16x16x32_bf16 v[24:27], v[172:175], v[224:227], v[24:27]
	v_mfma_f32_16x16x32_bf16 v[12:15], v[132:135], v[232:235], v[12:15]
	v_mfma_f32_16x16x32_bf16 v[8:11], v[172:175], v[232:235], v[8:11]
	v_mfma_f32_16x16x32_bf16 v[60:63], v[162:165], v[212:215], v[60:63]
	v_mfma_f32_16x16x32_bf16 v[56:59], v[176:179], v[212:215], v[56:59]
	v_mfma_f32_16x16x32_bf16 v[44:47], v[162:165], v[220:223], v[44:47]
	v_mfma_f32_16x16x32_bf16 v[40:43], v[176:179], v[220:223], v[40:43]
	v_mfma_f32_16x16x32_bf16 v[28:31], v[162:165], v[228:231], v[28:31]
	v_mfma_f32_16x16x32_bf16 v[24:27], v[176:179], v[228:231], v[24:27]
	v_mfma_f32_16x16x32_bf16 v[12:15], v[162:165], v[236:239], v[12:15]
	v_mfma_f32_16x16x32_bf16 v[8:11], v[176:179], v[236:239], v[8:11]
	v_mfma_f32_16x16x32_bf16 v[52:55], v[192:195], v[208:211], v[52:55]
	v_mfma_f32_16x16x32_bf16 v[48:51], v[200:203], v[208:211], v[48:51]
	v_mfma_f32_16x16x32_bf16 v[36:39], v[192:195], v[216:219], v[36:39]
	v_mfma_f32_16x16x32_bf16 v[32:35], v[200:203], v[216:219], v[32:35]
	v_mfma_f32_16x16x32_bf16 v[20:23], v[192:195], v[224:227], v[20:23]
	v_mfma_f32_16x16x32_bf16 v[16:19], v[200:203], v[224:227], v[16:19]
	v_mfma_f32_16x16x32_bf16 v[4:7], v[192:195], v[232:235], v[4:7]
	v_mfma_f32_16x16x32_bf16 v[0:3], v[200:203], v[232:235], v[0:3]
	v_mfma_f32_16x16x32_bf16 v[52:55], v[196:199], v[212:215], v[52:55]
	v_mfma_f32_16x16x32_bf16 v[48:51], v[204:207], v[212:215], v[48:51]
	v_mfma_f32_16x16x32_bf16 v[36:39], v[196:199], v[220:223], v[36:39]
	v_mfma_f32_16x16x32_bf16 v[32:35], v[204:207], v[220:223], v[32:35]
	v_mfma_f32_16x16x32_bf16 v[20:23], v[196:199], v[228:231], v[20:23]
	v_mfma_f32_16x16x32_bf16 v[16:19], v[204:207], v[228:231], v[16:19]
	v_mfma_f32_16x16x32_bf16 v[4:7], v[196:199], v[236:239], v[4:7]
	v_mfma_f32_16x16x32_bf16 v[0:3], v[204:207], v[236:239], v[0:3]
	s_barrier
	s_add_i32 s62, 0, 0x18000
	s_add_i32 s63, 0, 0x1c000
	v_add_u32_e32 v176, s62, v170
	v_add_u32_e32 v204, s63, v170
	ds_read_b128 v[132:135], v176
	ds_read_b128 v[162:165], v176 offset:1024
	ds_read_b128 v[172:175], v176 offset:2048
	ds_read_b128 v[176:179], v176 offset:3072
	ds_read_b128 v[192:195], v204
	ds_read_b128 v[196:199], v204 offset:1024
	ds_read_b128 v[200:203], v204 offset:2048
	ds_read_b128 v[204:207], v204 offset:3072
	s_add_u32 s50, s50, s20
	s_addc_u32 s51, s51, 0
	s_mov_b32 m0, s8
	v_lshl_add_u64 v[242:243], s[50:51], 0, v[138:139]
	ds_read_b128 v[208:211], v171 offset:32768
	ds_read_b128 v[212:215], v171 offset:33792
	ds_read_b128 v[216:219], v171 offset:34816
	ds_read_b128 v[220:223], v171 offset:35840
	ds_read_b128 v[224:227], v171 offset:36864
	ds_read_b128 v[228:231], v171 offset:37888
	ds_read_b128 v[232:235], v171 offset:38912
	ds_read_b128 v[236:239], v171 offset:39936
	global_load_lds_dwordx4 v[242:243], off
	v_lshl_add_u64 v[242:243], s[50:51], 0, v[140:141]
	s_mov_b32 m0, s9
	s_nop 0
	global_load_lds_dwordx4 v[242:243], off
	s_waitcnt vmcnt(8)
	s_waitcnt lgkmcnt(0)
	s_barrier
	v_mfma_f32_16x16x32_bf16 v[124:127], v[132:135], v[208:211], v[124:127]
	v_mfma_f32_16x16x32_bf16 v[120:123], v[172:175], v[208:211], v[120:123]
	v_mfma_f32_16x16x32_bf16 v[108:111], v[132:135], v[216:219], v[108:111]
	v_mfma_f32_16x16x32_bf16 v[104:107], v[172:175], v[216:219], v[104:107]
	v_mfma_f32_16x16x32_bf16 v[92:95], v[132:135], v[224:227], v[92:95]
	v_mfma_f32_16x16x32_bf16 v[88:91], v[172:175], v[224:227], v[88:91]
	v_mfma_f32_16x16x32_bf16 v[76:79], v[132:135], v[232:235], v[76:79]
	v_mfma_f32_16x16x32_bf16 v[72:75], v[172:175], v[232:235], v[72:75]
	v_mfma_f32_16x16x32_bf16 v[124:127], v[162:165], v[212:215], v[124:127]
	v_mfma_f32_16x16x32_bf16 v[120:123], v[176:179], v[212:215], v[120:123]
	v_mfma_f32_16x16x32_bf16 v[108:111], v[162:165], v[220:223], v[108:111]
	v_mfma_f32_16x16x32_bf16 v[104:107], v[176:179], v[220:223], v[104:107]
	v_mfma_f32_16x16x32_bf16 v[92:95], v[162:165], v[228:231], v[92:95]
	v_mfma_f32_16x16x32_bf16 v[88:91], v[176:179], v[228:231], v[88:91]
	v_mfma_f32_16x16x32_bf16 v[76:79], v[162:165], v[236:239], v[76:79]
	v_mfma_f32_16x16x32_bf16 v[72:75], v[176:179], v[236:239], v[72:75]
	v_mfma_f32_16x16x32_bf16 v[116:119], v[192:195], v[208:211], v[116:119]
	v_mfma_f32_16x16x32_bf16 v[112:115], v[200:203], v[208:211], v[112:115]
	v_mfma_f32_16x16x32_bf16 v[100:103], v[192:195], v[216:219], v[100:103]
	v_mfma_f32_16x16x32_bf16 v[96:99], v[200:203], v[216:219], v[96:99]
	v_mfma_f32_16x16x32_bf16 v[84:87], v[192:195], v[224:227], v[84:87]
	v_mfma_f32_16x16x32_bf16 v[80:83], v[200:203], v[224:227], v[80:83]
	v_mfma_f32_16x16x32_bf16 v[68:71], v[192:195], v[232:235], v[68:71]
	v_mfma_f32_16x16x32_bf16 v[64:67], v[200:203], v[232:235], v[64:67]
	v_mfma_f32_16x16x32_bf16 v[116:119], v[196:199], v[212:215], v[116:119]
	v_mfma_f32_16x16x32_bf16 v[112:115], v[204:207], v[212:215], v[112:115]
	v_mfma_f32_16x16x32_bf16 v[100:103], v[196:199], v[220:223], v[100:103]
	v_mfma_f32_16x16x32_bf16 v[96:99], v[204:207], v[220:223], v[96:99]
	v_mfma_f32_16x16x32_bf16 v[84:87], v[196:199], v[228:231], v[84:87]
	v_mfma_f32_16x16x32_bf16 v[80:83], v[204:207], v[228:231], v[80:83]
	v_mfma_f32_16x16x32_bf16 v[68:71], v[196:199], v[236:239], v[68:71]
	v_mfma_f32_16x16x32_bf16 v[64:67], v[204:207], v[236:239], v[64:67]
	s_barrier
; #define PG8_STAGE(bufoff, gbase, voff) do { _Pragma("unroll") for (int _i = 0; _i < 2; ++_i) \
;         __builtin_amdgcn_global_load_lds((const unsigned*)((const char*)(gbase) + (voff)[_i]), (LAS unsigned*)(lds + (bufoff) + ldsw + _i * 8192), 16, 0, 0); } while (0)
; #define PG8_LDA(dst, b, h) do { _Pragma("unroll") for (int m = 0; m < 4; ++m) _Pragma("unroll") for (int k = 0; k < 2; ++k) dst[m][k] = *(const LAS bf16x8*)(lds + PG8_SA(b, h) + aoff + m * 2048 + k * 1024); } while (0)
; #define PG8_MMA(ai, bj, At, Bt) do { __builtin_amdgcn_s_setprio(1); _Pragma("unroll") for (int m = 0; m < 4; ++m) _Pragma("unroll") for (int n = 0; n < 2; ++n) _Pragma("unroll") for (int k = 0; k < 2; ++k) \
;         acc[ai][bj][m][n] = __builtin_amdgcn_mfma_f32_16x16x32_bf16(Bt[n][k], At[m][k], acc[ai][bj][m][n], 0, 0, 0); __builtin_amdgcn_s_setprio(0); } while (0)
; #define PG8_WAIT_V(n) asm volatile("s_waitcnt vmcnt(" #n ")" ::: "memory")
; #define PG8_WAIT_L(n) asm volatile("s_waitcnt lgkmcnt(" #n ")" ::: "memory")
; #define PG8_BAR __builtin_amdgcn_s_barrier()
; #define PG8_SCHED __builtin_amdgcn_sched_barrier(0)
; template <class Epi, class Map>
; __device__ __forceinline__ void gemm_phase(LAS unsigned char* lds, const Gemm g, const Sched<Map>& S, const Epi& E) {
;     ...
;             PG8_LDA(At, 1, 1); PG8_STAGE(PG8_SB(1, 0), b3, voffB); PG8_STAGE(PG8_SB(1, 1), b3 + hstepB, voffB); PG8_STAGE(PG8_SA(1, 0), a3, voffA);
;             PG8_WAIT_V(8); PG8_WAIT_L(0); PG8_BAR; PG8_MMA(1, 0, At, B0); PG8_MMA(1, 1, At, B1); PG8_BAR; PG8_SCHED;
;         }
	s_add_i32 s50, s62, s5
	v_lshl_add_u64 v[136:137], v[136:137], 0, s[82:83]
	s_mov_b32 m0, s50
	ds_read_b128 v[208:211], v171 offset:49152
	ds_read_b128 v[212:215], v171 offset:50176
	ds_read_b128 v[216:219], v171 offset:51200
	ds_read_b128 v[220:223], v171 offset:52224
	ds_read_b128 v[224:227], v171 offset:53248
	ds_read_b128 v[228:231], v171 offset:54272
	ds_read_b128 v[232:235], v171 offset:55296
	ds_read_b128 v[236:239], v171 offset:56320
	global_load_lds_dwordx4 v[136:137], off
	s_add_i32 m0, s50, 0x2000
	s_add_u32 s48, s48, 0x80080
	v_lshl_add_u64 v[136:137], v[166:167], 0, s[82:83]
	s_addc_u32 s49, s49, 0
	s_add_i32 s50, s63, s5
	global_load_lds_dwordx4 v[136:137], off
	v_lshl_add_u64 v[136:137], s[48:49], 0, v[144:145]
	s_mov_b32 m0, s50
	s_nop 0
	global_load_lds_dwordx4 v[136:137], off
	v_lshl_add_u64 v[136:137], s[48:49], 0, v[142:143]
	s_add_i32 m0, s50, 0x2000
	s_nop 0
	global_load_lds_dwordx4 v[136:137], off
	v_lshl_add_u64 v[136:137], v[180:181], 0, s[82:83]
	s_mov_b32 m0, s14
	s_nop 0
	global_load_lds_dwordx4 v[136:137], off
	v_lshl_add_u64 v[136:137], v[240:241], 0, s[82:83]
	s_mov_b32 m0, s15
	s_nop 0
	global_load_lds_dwordx4 v[136:137], off
	s_waitcnt vmcnt(8)
	s_waitcnt lgkmcnt(0)
	s_barrier
	v_mfma_f32_16x16x32_bf16 v[60:63], v[132:135], v[208:211], v[60:63]
	v_mfma_f32_16x16x32_bf16 v[56:59], v[172:175], v[208:211], v[56:59]
	v_mfma_f32_16x16x32_bf16 v[44:47], v[132:135], v[216:219], v[44:47]
	v_mfma_f32_16x16x32_bf16 v[40:43], v[172:175], v[216:219], v[40:43]
	v_mfma_f32_16x16x32_bf16 v[28:31], v[132:135], v[224:227], v[28:31]
	v_mfma_f32_16x16x32_bf16 v[24:27], v[172:175], v[224:227], v[24:27]
	v_mfma_f32_16x16x32_bf16 v[12:15], v[132:135], v[232:235], v[12:15]
	v_mfma_f32_16x16x32_bf16 v[8:11], v[172:175], v[232:235], v[8:11]
	v_mfma_f32_16x16x32_bf16 v[60:63], v[162:165], v[212:215], v[60:63]
	v_mfma_f32_16x16x32_bf16 v[56:59], v[176:179], v[212:215], v[56:59]
	v_mfma_f32_16x16x32_bf16 v[44:47], v[162:165], v[220:223], v[44:47]
	v_mfma_f32_16x16x32_bf16 v[40:43], v[176:179], v[220:223], v[40:43]
	v_mfma_f32_16x16x32_bf16 v[28:31], v[162:165], v[228:231], v[28:31]
	v_mfma_f32_16x16x32_bf16 v[24:27], v[176:179], v[228:231], v[24:27]
	v_mfma_f32_16x16x32_bf16 v[12:15], v[162:165], v[236:239], v[12:15]
	v_mfma_f32_16x16x32_bf16 v[8:11], v[176:179], v[236:239], v[8:11]
	v_mfma_f32_16x16x32_bf16 v[52:55], v[192:195], v[208:211], v[52:55]
	v_mfma_f32_16x16x32_bf16 v[48:51], v[200:203], v[208:211], v[48:51]
	v_mfma_f32_16x16x32_bf16 v[36:39], v[192:195], v[216:219], v[36:39]
	v_mfma_f32_16x16x32_bf16 v[32:35], v[200:203], v[216:219], v[32:35]
	v_mfma_f32_16x16x32_bf16 v[20:23], v[192:195], v[224:227], v[20:23]
	v_mfma_f32_16x16x32_bf16 v[16:19], v[200:203], v[224:227], v[16:19]
	v_mfma_f32_16x16x32_bf16 v[4:7], v[192:195], v[232:235], v[4:7]
	v_mfma_f32_16x16x32_bf16 v[0:3], v[200:203], v[232:235], v[0:3]
	v_mfma_f32_16x16x32_bf16 v[52:55], v[196:199], v[212:215], v[52:55]
	v_mfma_f32_16x16x32_bf16 v[48:51], v[204:207], v[212:215], v[48:51]
	v_mfma_f32_16x16x32_bf16 v[36:39], v[196:199], v[220:223], v[36:39]
	v_mfma_f32_16x16x32_bf16 v[32:35], v[204:207], v[220:223], v[32:35]
	v_mfma_f32_16x16x32_bf16 v[20:23], v[196:199], v[228:231], v[20:23]
	v_mfma_f32_16x16x32_bf16 v[16:19], v[204:207], v[228:231], v[16:19]
	v_mfma_f32_16x16x32_bf16 v[4:7], v[196:199], v[236:239], v[4:7]
	v_mfma_f32_16x16x32_bf16 v[0:3], v[204:207], v[236:239], v[0:3]
	s_barrier
	s_add_i32 s67, s67, 2
	s_add_u32 s46, s46, 0x100
	s_addc_u32 s47, s47, 0
	s_cmp_gt_u32 s67, 29
	s_cbranch_scc0 .LBB0_223
	s_and_b64 vcc, exec, s[28:29]
	s_cbranch_vccz .LBB0_226

; #define PG8_STAGE(bufoff, gbase, voff) do { _Pragma("unroll") for (int _i = 0; _i < 2; ++_i) \
;         __builtin_amdgcn_global_load_lds((const unsigned*)((const char*)(gbase) + (voff)[_i]), (LAS unsigned*)(lds + (bufoff) + ldsw + _i * 8192), 16, 0, 0); } while (0)
; #define PG8_LDA(dst, b, h) do { _Pragma("unroll") for (int m = 0; m < 4; ++m) _Pragma("unroll") for (int k = 0; k < 2; ++k) dst[m][k] = *(const LAS bf16x8*)(lds + PG8_SA(b, h) + aoff + m * 2048 + k * 1024); } while (0)
; #define PG8_LDB(dst, b, h) do { _Pragma("unroll") for (int n = 0; n < 2; ++n) _Pragma("unroll") for (int k = 0; k < 2; ++k) dst[n][k] = *(const LAS bf16x8*)(lds + PG8_SB(b, h) + boff + n * 2048 + k * 1024); } while (0)
; #define PG8_MMA(ai, bj, At, Bt) do { __builtin_amdgcn_s_setprio(1); _Pragma("unroll") for (int m = 0; m < 4; ++m) _Pragma("unroll") for (int n = 0; n < 2; ++n) _Pragma("unroll") for (int k = 0; k < 2; ++k) \
;         acc[ai][bj][m][n] = __builtin_amdgcn_mfma_f32_16x16x32_bf16(Bt[n][k], At[m][k], acc[ai][bj][m][n], 0, 0, 0); __builtin_amdgcn_s_setprio(0); } while (0)
; #define PG8_WAIT_V(n) asm volatile("s_waitcnt vmcnt(" #n ")" ::: "memory")
; #define PG8_WAIT_L(n) asm volatile("s_waitcnt lgkmcnt(" #n ")" ::: "memory")
; #define PG8_BAR __builtin_amdgcn_s_barrier()
; #define PG8_SCHED __builtin_amdgcn_sched_barrier(0)
; template <class Epi, class Map>
; __device__ __forceinline__ void gemm_phase(LAS unsigned char* lds, const Gemm g, const Sched<Map>& S, const Epi& E) {
;     ...
;         for (int t = 0; t < nt; t += 2) {
;             const bool last = (t == nt - 2);
;             const char* a1 = cA + (size_t)(t + 1) * kstep;
;             const char* a2 = last ? nA : cA + (size_t)(t + 2) * kstep; const char* b2 = last ? nB : cB + (size_t)(t + 2) * kstep;
;             const char* a3 = a2 + kstep; const char* b3 = b2 + kstep;
;             PG8_LDB(B0, 0, 0); PG8_LDB(B1, 0, 1); PG8_SCHED; PG8_LDA(At, 0, 0); PG8_STAGE(PG8_SA(1, 1), a1 + hstepA, voffA);
;             PG8_WAIT_V(8); PG8_WAIT_L(0); PG8_BAR; PG8_MMA(0, 0, At, B0); PG8_MMA(0, 1, At, B1); PG8_BAR; PG8_SCHED;
.LBB0_261:
	s_add_u32 s36, s34, 0xfff80080
	s_addc_u32 s37, s35, -1
	s_add_i32 s54, 0, 0x10000
	s_cmp_eq_u32 s51, 28
	s_cselect_b32 s37, s25, s37
	s_cselect_b32 s36, s46, s36
	v_add_u32_e32 v138, s54, v142
	s_cselect_b32 s53, s47, s50
	s_cselect_b32 s52, s48, s49
	s_add_i32 s55, 0, 0x14000
	ds_read_b128 v[158:161], v138
	ds_read_b128 v[162:165], v138 offset:1024
	ds_read_b128 v[166:169], v138 offset:2048
	ds_read_b128 v[170:173], v138 offset:3072
	v_add_u32_e32 v138, s55, v142
	ds_read_b128 v[174:177], v138
	ds_read_b128 v[178:181], v138 offset:1024
	ds_read_b128 v[192:195], v138 offset:2048
	ds_read_b128 v[196:199], v138 offset:3072
	v_lshl_add_u64 v[138:139], s[34:35], 0, v[134:135]
	s_add_i32 m0, s7, 0xc000
	ds_read_b128 v[200:203], v143
	ds_read_b128 v[204:207], v143 offset:1024
	ds_read_b128 v[208:211], v143 offset:2048
	ds_read_b128 v[212:215], v143 offset:3072
	ds_read_b128 v[216:219], v143 offset:4096
	ds_read_b128 v[220:223], v143 offset:5120
	ds_read_b128 v[224:227], v143 offset:6144
	ds_read_b128 v[228:231], v143 offset:7168
	global_load_lds_dwordx4 v[138:139], off
	v_lshl_add_u64 v[138:139], s[34:35], 0, v[136:137]
	s_add_i32 m0, s7, 0xe000
	s_nop 0
	global_load_lds_dwordx4 v[138:139], off
	s_waitcnt vmcnt(8)
	s_waitcnt lgkmcnt(0)
	s_barrier
	v_mfma_f32_16x16x32_bf16 v[124:127], v[158:161], v[200:203], v[124:127]
	v_mfma_f32_16x16x32_bf16 v[120:123], v[166:169], v[200:203], v[120:123]
	v_mfma_f32_16x16x32_bf16 v[116:119], v[158:161], v[208:211], v[116:119]
	v_mfma_f32_16x16x32_bf16 v[108:111], v[166:169], v[208:211], v[108:111]
	v_mfma_f32_16x16x32_bf16 v[100:103], v[158:161], v[216:219], v[100:103]
	v_mfma_f32_16x16x32_bf16 v[92:95], v[166:169], v[216:219], v[92:95]
	v_mfma_f32_16x16x32_bf16 v[84:87], v[158:161], v[224:227], v[84:87]
	v_mfma_f32_16x16x32_bf16 v[76:79], v[166:169], v[224:227], v[76:79]
	v_mfma_f32_16x16x32_bf16 v[124:127], v[162:165], v[204:207], v[124:127]
	v_mfma_f32_16x16x32_bf16 v[120:123], v[170:173], v[204:207], v[120:123]
	v_mfma_f32_16x16x32_bf16 v[116:119], v[162:165], v[212:215], v[116:119]
	v_mfma_f32_16x16x32_bf16 v[108:111], v[170:173], v[212:215], v[108:111]
	v_mfma_f32_16x16x32_bf16 v[100:103], v[162:165], v[220:223], v[100:103]
	v_mfma_f32_16x16x32_bf16 v[92:95], v[170:173], v[220:223], v[92:95]
	v_mfma_f32_16x16x32_bf16 v[84:87], v[162:165], v[228:231], v[84:87]
	v_mfma_f32_16x16x32_bf16 v[76:79], v[170:173], v[228:231], v[76:79]
	v_mfma_f32_16x16x32_bf16 v[112:115], v[174:177], v[200:203], v[112:115]
	v_mfma_f32_16x16x32_bf16 v[104:107], v[192:195], v[200:203], v[104:107]
	v_mfma_f32_16x16x32_bf16 v[96:99], v[174:177], v[208:211], v[96:99]
	v_mfma_f32_16x16x32_bf16 v[88:91], v[192:195], v[208:211], v[88:91]
	v_mfma_f32_16x16x32_bf16 v[80:83], v[174:177], v[216:219], v[80:83]
	v_mfma_f32_16x16x32_bf16 v[72:75], v[192:195], v[216:219], v[72:75]
	v_mfma_f32_16x16x32_bf16 v[68:71], v[174:177], v[224:227], v[68:71]
	v_mfma_f32_16x16x32_bf16 v[64:67], v[192:195], v[224:227], v[64:67]
	v_mfma_f32_16x16x32_bf16 v[112:115], v[178:181], v[204:207], v[112:115]
	v_mfma_f32_16x16x32_bf16 v[104:107], v[196:199], v[204:207], v[104:107]
	v_mfma_f32_16x16x32_bf16 v[96:99], v[178:181], v[212:215], v[96:99]
	v_mfma_f32_16x16x32_bf16 v[88:91], v[196:199], v[212:215], v[88:91]
	v_mfma_f32_16x16x32_bf16 v[80:83], v[178:181], v[220:223], v[80:83]
	v_mfma_f32_16x16x32_bf16 v[72:75], v[196:199], v[220:223], v[72:75]
	v_mfma_f32_16x16x32_bf16 v[68:71], v[178:181], v[228:231], v[68:71]
	v_mfma_f32_16x16x32_bf16 v[64:67], v[196:199], v[228:231], v[64:67]
	s_barrier
	s_add_i32 s54, s54, s6
	v_lshl_add_u64 v[138:139], s[52:53], 0, v[144:145]
	s_mov_b32 m0, s54
	ds_read_b128 v[200:203], v143 offset:16384
	ds_read_b128 v[204:207], v143 offset:17408
	ds_read_b128 v[208:211], v143 offset:18432
	ds_read_b128 v[212:215], v143 offset:19456
	ds_read_b128 v[216:219], v143 offset:20480
	ds_read_b128 v[220:223], v143 offset:21504
	ds_read_b128 v[224:227], v143 offset:22528
	ds_read_b128 v[228:231], v143 offset:23552
	global_load_lds_dwordx4 v[138:139], off
	s_add_i32 m0, s54, 0x2000
	v_lshl_add_u64 v[232:233], s[52:53], 0, v[128:129]
	s_add_u32 s52, s52, s5
	s_addc_u32 s53, s53, 0
	s_add_i32 s54, s55, s6
	global_load_lds_dwordx4 v[232:233], off
	v_lshl_add_u64 v[234:235], s[52:53], 0, v[144:145]
	s_mov_b32 m0, s54
	v_lshl_add_u64 v[236:237], s[52:53], 0, v[128:129]
	global_load_lds_dwordx4 v[234:235], off
	s_add_i32 m0, s54, 0x2000
	v_lshl_add_u64 v[238:239], s[36:37], 0, v[132:133]
	global_load_lds_dwordx4 v[236:237], off
	s_mov_b32 m0, s7
	v_lshl_add_u64 v[240:241], s[36:37], 0, v[130:131]
	global_load_lds_dwordx4 v[238:239], off
	s_mov_b32 m0, s8
	s_nop 0
	global_load_lds_dwordx4 v[240:241], off
	s_waitcnt vmcnt(8)
	s_waitcnt lgkmcnt(0)
	s_barrier
; #define PG8_STAGE(bufoff, gbase, voff) do { _Pragma("unroll") for (int _i = 0; _i < 2; ++_i) \
;         __builtin_amdgcn_global_load_lds((const unsigned*)((const char*)(gbase) + (voff)[_i]), (LAS unsigned*)(lds + (bufoff) + ldsw + _i * 8192), 16, 0, 0); } while (0)
; #define PG8_LDA(dst, b, h) do { _Pragma("unroll") for (int m = 0; m < 4; ++m) _Pragma("unroll") for (int k = 0; k < 2; ++k) dst[m][k] = *(const LAS bf16x8*)(lds + PG8_SA(b, h) + aoff + m * 2048 + k * 1024); } while (0)
; #define PG8_LDB(dst, b, h) do { _Pragma("unroll") for (int n = 0; n < 2; ++n) _Pragma("unroll") for (int k = 0; k < 2; ++k) dst[n][k] = *(const LAS bf16x8*)(lds + PG8_SB(b, h) + boff + n * 2048 + k * 1024); } while (0)
; #define PG8_MMA(ai, bj, At, Bt) do { __builtin_amdgcn_s_setprio(1); _Pragma("unroll") for (int m = 0; m < 4; ++m) _Pragma("unroll") for (int n = 0; n < 2; ++n) _Pragma("unroll") for (int k = 0; k < 2; ++k) \
;         acc[ai][bj][m][n] = __builtin_amdgcn_mfma_f32_16x16x32_bf16(Bt[n][k], At[m][k], acc[ai][bj][m][n], 0, 0, 0); __builtin_amdgcn_s_setprio(0); } while (0)
; #define PG8_WAIT_V(n) asm volatile("s_waitcnt vmcnt(" #n ")" ::: "memory")
; #define PG8_WAIT_L(n) asm volatile("s_waitcnt lgkmcnt(" #n ")" ::: "memory")
; #define PG8_BAR __builtin_amdgcn_s_barrier()
; #define PG8_SCHED __builtin_amdgcn_sched_barrier(0)
; template <class Epi, class Map>
; __device__ __forceinline__ void gemm_phase(LAS unsigned char* lds, const Gemm g, const Sched<Map>& S, const Epi& E) {
;     ...
;             PG8_WAIT_V(8); PG8_WAIT_L(0); PG8_BAR; PG8_MMA(0, 0, At, B0); PG8_MMA(0, 1, At, B1); PG8_BAR; PG8_SCHED;
;             PG8_LDA(At, 0, 1); PG8_STAGE(PG8_SB(0, 0), b2, voffB); PG8_STAGE(PG8_SB(0, 1), b2 + hstepB, voffB); PG8_STAGE(PG8_SA(0, 0), a2, voffA);
;             PG8_WAIT_V(8); PG8_WAIT_L(0); PG8_BAR; PG8_MMA(1, 0, At, B0); PG8_MMA(1, 1, At, B1); PG8_BAR; PG8_SCHED;
;             PG8_LDB(B0, 1, 0); PG8_LDB(B1, 1, 1); PG8_SCHED; PG8_LDA(At, 1, 0); PG8_STAGE(PG8_SA(0, 1), a2 + hstepA, voffA);
;             PG8_WAIT_V(8); PG8_WAIT_L(0); PG8_BAR; PG8_MMA(0, 0, At, B0); PG8_MMA(0, 1, At, B1); PG8_BAR; PG8_SCHED;
	v_mfma_f32_16x16x32_bf16 v[60:63], v[158:161], v[200:203], v[60:63]
	v_mfma_f32_16x16x32_bf16 v[56:59], v[166:169], v[200:203], v[56:59]
	v_mfma_f32_16x16x32_bf16 v[52:55], v[158:161], v[208:211], v[52:55]
	v_mfma_f32_16x16x32_bf16 v[44:47], v[166:169], v[208:211], v[44:47]
	v_mfma_f32_16x16x32_bf16 v[36:39], v[158:161], v[216:219], v[36:39]
	v_mfma_f32_16x16x32_bf16 v[28:31], v[166:169], v[216:219], v[28:31]
	v_mfma_f32_16x16x32_bf16 v[20:23], v[158:161], v[224:227], v[20:23]
	v_mfma_f32_16x16x32_bf16 v[12:15], v[166:169], v[224:227], v[12:15]
	v_mfma_f32_16x16x32_bf16 v[60:63], v[162:165], v[204:207], v[60:63]
	v_mfma_f32_16x16x32_bf16 v[56:59], v[170:173], v[204:207], v[56:59]
	v_mfma_f32_16x16x32_bf16 v[52:55], v[162:165], v[212:215], v[52:55]
	v_mfma_f32_16x16x32_bf16 v[44:47], v[170:173], v[212:215], v[44:47]
	v_mfma_f32_16x16x32_bf16 v[36:39], v[162:165], v[220:223], v[36:39]
	v_mfma_f32_16x16x32_bf16 v[28:31], v[170:173], v[220:223], v[28:31]
	v_mfma_f32_16x16x32_bf16 v[20:23], v[162:165], v[228:231], v[20:23]
	v_mfma_f32_16x16x32_bf16 v[12:15], v[170:173], v[228:231], v[12:15]
	v_mfma_f32_16x16x32_bf16 v[48:51], v[174:177], v[200:203], v[48:51]
	v_mfma_f32_16x16x32_bf16 v[40:43], v[192:195], v[200:203], v[40:43]
	v_mfma_f32_16x16x32_bf16 v[32:35], v[174:177], v[208:211], v[32:35]
	v_mfma_f32_16x16x32_bf16 v[24:27], v[192:195], v[208:211], v[24:27]
	v_mfma_f32_16x16x32_bf16 v[16:19], v[174:177], v[216:219], v[16:19]
	v_mfma_f32_16x16x32_bf16 v[8:11], v[192:195], v[216:219], v[8:11]
	v_mfma_f32_16x16x32_bf16 v[4:7], v[174:177], v[224:227], v[4:7]
	v_mfma_f32_16x16x32_bf16 v[0:3], v[192:195], v[224:227], v[0:3]
	v_mfma_f32_16x16x32_bf16 v[48:51], v[178:181], v[204:207], v[48:51]
	v_mfma_f32_16x16x32_bf16 v[40:43], v[196:199], v[204:207], v[40:43]
	v_mfma_f32_16x16x32_bf16 v[32:35], v[178:181], v[212:215], v[32:35]
	v_mfma_f32_16x16x32_bf16 v[24:27], v[196:199], v[212:215], v[24:27]
	v_mfma_f32_16x16x32_bf16 v[16:19], v[178:181], v[220:223], v[16:19]
	v_mfma_f32_16x16x32_bf16 v[8:11], v[196:199], v[220:223], v[8:11]
	v_mfma_f32_16x16x32_bf16 v[4:7], v[178:181], v[228:231], v[4:7]
	v_mfma_f32_16x16x32_bf16 v[0:3], v[196:199], v[228:231], v[0:3]
	s_barrier
	s_add_i32 s52, 0, 0x18000
	s_add_i32 s53, 0, 0x1c000
	v_add_u32_e32 v170, s52, v142
	v_add_u32_e32 v196, s53, v142
	ds_read_b128 v[158:161], v170
	ds_read_b128 v[162:165], v170 offset:1024
	ds_read_b128 v[166:169], v170 offset:2048
	ds_read_b128 v[170:173], v170 offset:3072
	ds_read_b128 v[174:177], v196
	ds_read_b128 v[178:181], v196 offset:1024
	ds_read_b128 v[192:195], v196 offset:2048
	ds_read_b128 v[196:199], v196 offset:3072
	s_add_u32 s36, s36, 0x80000
	s_addc_u32 s37, s37, 0
	s_mov_b32 m0, s9
	v_lshl_add_u64 v[242:243], s[36:37], 0, v[132:133]
	ds_read_b128 v[200:203], v143 offset:32768
	ds_read_b128 v[204:207], v143 offset:33792
	ds_read_b128 v[208:211], v143 offset:34816
	ds_read_b128 v[212:215], v143 offset:35840
	ds_read_b128 v[216:219], v143 offset:36864
	ds_read_b128 v[220:223], v143 offset:37888
	ds_read_b128 v[224:227], v143 offset:38912
	ds_read_b128 v[228:231], v143 offset:39936
	global_load_lds_dwordx4 v[242:243], off
	v_lshl_add_u64 v[242:243], s[36:37], 0, v[130:131]
	s_mov_b32 m0, s10
	s_nop 0
	global_load_lds_dwordx4 v[242:243], off
	s_waitcnt vmcnt(8)
	s_waitcnt lgkmcnt(0)
	s_barrier
	v_mfma_f32_16x16x32_bf16 v[124:127], v[158:161], v[200:203], v[124:127]
	v_mfma_f32_16x16x32_bf16 v[120:123], v[166:169], v[200:203], v[120:123]
	v_mfma_f32_16x16x32_bf16 v[116:119], v[158:161], v[208:211], v[116:119]
	v_mfma_f32_16x16x32_bf16 v[108:111], v[166:169], v[208:211], v[108:111]
	v_mfma_f32_16x16x32_bf16 v[100:103], v[158:161], v[216:219], v[100:103]
	v_mfma_f32_16x16x32_bf16 v[92:95], v[166:169], v[216:219], v[92:95]
	v_mfma_f32_16x16x32_bf16 v[84:87], v[158:161], v[224:227], v[84:87]
	v_mfma_f32_16x16x32_bf16 v[76:79], v[166:169], v[224:227], v[76:79]
	v_mfma_f32_16x16x32_bf16 v[124:127], v[162:165], v[204:207], v[124:127]
	v_mfma_f32_16x16x32_bf16 v[120:123], v[170:173], v[204:207], v[120:123]
	v_mfma_f32_16x16x32_bf16 v[116:119], v[162:165], v[212:215], v[116:119]
	v_mfma_f32_16x16x32_bf16 v[108:111], v[170:173], v[212:215], v[108:111]
	v_mfma_f32_16x16x32_bf16 v[100:103], v[162:165], v[220:223], v[100:103]
	v_mfma_f32_16x16x32_bf16 v[92:95], v[170:173], v[220:223], v[92:95]
	v_mfma_f32_16x16x32_bf16 v[84:87], v[162:165], v[228:231], v[84:87]
	v_mfma_f32_16x16x32_bf16 v[76:79], v[170:173], v[228:231], v[76:79]
	v_mfma_f32_16x16x32_bf16 v[112:115], v[174:177], v[200:203], v[112:115]
	v_mfma_f32_16x16x32_bf16 v[104:107], v[192:195], v[200:203], v[104:107]
	v_mfma_f32_16x16x32_bf16 v[96:99], v[174:177], v[208:211], v[96:99]
	v_mfma_f32_16x16x32_bf16 v[88:91], v[192:195], v[208:211], v[88:91]
	v_mfma_f32_16x16x32_bf16 v[80:83], v[174:177], v[216:219], v[80:83]
	v_mfma_f32_16x16x32_bf16 v[72:75], v[192:195], v[216:219], v[72:75]
	v_mfma_f32_16x16x32_bf16 v[68:71], v[174:177], v[224:227], v[68:71]
	v_mfma_f32_16x16x32_bf16 v[64:67], v[192:195], v[224:227], v[64:67]
	v_mfma_f32_16x16x32_bf16 v[112:115], v[178:181], v[204:207], v[112:115]
	v_mfma_f32_16x16x32_bf16 v[104:107], v[196:199], v[204:207], v[104:107]
	v_mfma_f32_16x16x32_bf16 v[96:99], v[178:181], v[212:215], v[96:99]
	v_mfma_f32_16x16x32_bf16 v[88:91], v[196:199], v[212:215], v[88:91]
	v_mfma_f32_16x16x32_bf16 v[80:83], v[178:181], v[220:223], v[80:83]
	v_mfma_f32_16x16x32_bf16 v[72:75], v[196:199], v[220:223], v[72:75]
	v_mfma_f32_16x16x32_bf16 v[68:71], v[178:181], v[228:231], v[68:71]
	v_mfma_f32_16x16x32_bf16 v[64:67], v[196:199], v[228:231], v[64:67]
	s_barrier
; #define PG8_STAGE(bufoff, gbase, voff) do { _Pragma("unroll") for (int _i = 0; _i < 2; ++_i) \
;         __builtin_amdgcn_global_load_lds((const unsigned*)((const char*)(gbase) + (voff)[_i]), (LAS unsigned*)(lds + (bufoff) + ldsw + _i * 8192), 16, 0, 0); } while (0)
; #define PG8_LDA(dst, b, h) do { _Pragma("unroll") for (int m = 0; m < 4; ++m) _Pragma("unroll") for (int k = 0; k < 2; ++k) dst[m][k] = *(const LAS bf16x8*)(lds + PG8_SA(b, h) + aoff + m * 2048 + k * 1024); } while (0)
; #define PG8_MMA(ai, bj, At, Bt) do { __builtin_amdgcn_s_setprio(1); _Pragma("unroll") for (int m = 0; m < 4; ++m) _Pragma("unroll") for (int n = 0; n < 2; ++n) _Pragma("unroll") for (int k = 0; k < 2; ++k) \
;         acc[ai][bj][m][n] = __builtin_amdgcn_mfma_f32_16x16x32_bf16(Bt[n][k], At[m][k], acc[ai][bj][m][n], 0, 0, 0); __builtin_amdgcn_s_setprio(0); } while (0)
; #define PG8_WAIT_V(n) asm volatile("s_waitcnt vmcnt(" #n ")" ::: "memory")
; #define PG8_WAIT_L(n) asm volatile("s_waitcnt lgkmcnt(" #n ")" ::: "memory")
; #define PG8_BAR __builtin_amdgcn_s_barrier()
; #define PG8_SCHED __builtin_amdgcn_sched_barrier(0)
; template <class Epi, class Map>
; __device__ __forceinline__ void gemm_phase(LAS unsigned char* lds, const Gemm g, const Sched<Map>& S, const Epi& E) {
;     ...
;             PG8_LDA(At, 1, 1); PG8_STAGE(PG8_SB(1, 0), b3, voffB); PG8_STAGE(PG8_SB(1, 1), b3 + hstepB, voffB); PG8_STAGE(PG8_SA(1, 0), a3, voffA);
;             PG8_WAIT_V(8); PG8_WAIT_L(0); PG8_BAR; PG8_MMA(1, 0, At, B0); PG8_MMA(1, 1, At, B1); PG8_BAR; PG8_SCHED;
;         }
	s_add_i32 s36, s52, s6
	v_lshl_add_u64 v[138:139], v[138:139], 0, s[82:83]
	s_mov_b32 m0, s36
	ds_read_b128 v[200:203], v143 offset:49152
	ds_read_b128 v[204:207], v143 offset:50176
	ds_read_b128 v[208:211], v143 offset:51200
	ds_read_b128 v[212:215], v143 offset:52224
	ds_read_b128 v[216:219], v143 offset:53248
	ds_read_b128 v[220:223], v143 offset:54272
	ds_read_b128 v[224:227], v143 offset:55296
	ds_read_b128 v[228:231], v143 offset:56320
	global_load_lds_dwordx4 v[138:139], off
	v_lshl_add_u64 v[138:139], v[232:233], 0, s[82:83]
	s_add_i32 m0, s36, 0x2000
	s_add_i32 s36, s53, s6
	global_load_lds_dwordx4 v[138:139], off
	v_lshl_add_u64 v[138:139], v[234:235], 0, s[82:83]
	s_mov_b32 m0, s36
	s_nop 0
	global_load_lds_dwordx4 v[138:139], off
	v_lshl_add_u64 v[138:139], v[236:237], 0, s[82:83]
	s_add_i32 m0, s36, 0x2000
	s_nop 0
	global_load_lds_dwordx4 v[138:139], off
	v_lshl_add_u64 v[138:139], v[238:239], 0, s[82:83]
	s_mov_b32 m0, s15
	s_nop 0
	global_load_lds_dwordx4 v[138:139], off
	v_lshl_add_u64 v[138:139], v[240:241], 0, s[82:83]
	s_mov_b32 m0, s33
	s_nop 0
	global_load_lds_dwordx4 v[138:139], off
	s_waitcnt vmcnt(8)
	s_waitcnt lgkmcnt(0)
	s_barrier
	v_mfma_f32_16x16x32_bf16 v[60:63], v[158:161], v[200:203], v[60:63]
	v_mfma_f32_16x16x32_bf16 v[56:59], v[166:169], v[200:203], v[56:59]
	v_mfma_f32_16x16x32_bf16 v[52:55], v[158:161], v[208:211], v[52:55]
	v_mfma_f32_16x16x32_bf16 v[44:47], v[166:169], v[208:211], v[44:47]
	v_mfma_f32_16x16x32_bf16 v[36:39], v[158:161], v[216:219], v[36:39]
	v_mfma_f32_16x16x32_bf16 v[28:31], v[166:169], v[216:219], v[28:31]
	v_mfma_f32_16x16x32_bf16 v[20:23], v[158:161], v[224:227], v[20:23]
	v_mfma_f32_16x16x32_bf16 v[12:15], v[166:169], v[224:227], v[12:15]
	v_mfma_f32_16x16x32_bf16 v[60:63], v[162:165], v[204:207], v[60:63]
	v_mfma_f32_16x16x32_bf16 v[56:59], v[170:173], v[204:207], v[56:59]
	v_mfma_f32_16x16x32_bf16 v[52:55], v[162:165], v[212:215], v[52:55]
	v_mfma_f32_16x16x32_bf16 v[44:47], v[170:173], v[212:215], v[44:47]
	v_mfma_f32_16x16x32_bf16 v[36:39], v[162:165], v[220:223], v[36:39]
	v_mfma_f32_16x16x32_bf16 v[28:31], v[170:173], v[220:223], v[28:31]
	v_mfma_f32_16x16x32_bf16 v[20:23], v[162:165], v[228:231], v[20:23]
	v_mfma_f32_16x16x32_bf16 v[12:15], v[170:173], v[228:231], v[12:15]
	v_mfma_f32_16x16x32_bf16 v[48:51], v[174:177], v[200:203], v[48:51]
	v_mfma_f32_16x16x32_bf16 v[40:43], v[192:195], v[200:203], v[40:43]
	v_mfma_f32_16x16x32_bf16 v[32:35], v[174:177], v[208:211], v[32:35]
	v_mfma_f32_16x16x32_bf16 v[24:27], v[192:195], v[208:211], v[24:27]
	v_mfma_f32_16x16x32_bf16 v[16:19], v[174:177], v[216:219], v[16:19]
	v_mfma_f32_16x16x32_bf16 v[8:11], v[192:195], v[216:219], v[8:11]
	v_mfma_f32_16x16x32_bf16 v[4:7], v[174:177], v[224:227], v[4:7]
	v_mfma_f32_16x16x32_bf16 v[0:3], v[192:195], v[224:227], v[0:3]
	v_mfma_f32_16x16x32_bf16 v[48:51], v[178:181], v[204:207], v[48:51]
	v_mfma_f32_16x16x32_bf16 v[40:43], v[196:199], v[204:207], v[40:43]
	v_mfma_f32_16x16x32_bf16 v[32:35], v[178:181], v[212:215], v[32:35]
	v_mfma_f32_16x16x32_bf16 v[24:27], v[196:199], v[212:215], v[24:27]
	v_mfma_f32_16x16x32_bf16 v[16:19], v[178:181], v[220:223], v[16:19]
	v_mfma_f32_16x16x32_bf16 v[8:11], v[196:199], v[220:223], v[8:11]
	v_mfma_f32_16x16x32_bf16 v[4:7], v[178:181], v[228:231], v[4:7]
	v_mfma_f32_16x16x32_bf16 v[0:3], v[196:199], v[228:231], v[0:3]
	s_barrier
	s_add_i32 s51, s51, 2
	s_add_u32 s34, s34, 0x100
	s_addc_u32 s35, s35, 0
	s_add_u32 s49, s49, 0x100
	s_addc_u32 s50, s50, 0
	s_cmp_gt_u32 s51, 29
	s_cbranch_scc0 .LBB0_261
	s_and_b64 vcc, exec, s[20:21]
	s_cbranch_vccz .LBB0_264

; #define PG8_STAGE(bufoff, gbase, voff) do { _Pragma("unroll") for (int _i = 0; _i < 2; ++_i) \
;         __builtin_amdgcn_global_load_lds((const unsigned*)((const char*)(gbase) + (voff)[_i]), (LAS unsigned*)(lds + (bufoff) + ldsw + _i * 8192), 16, 0, 0); } while (0)
; #define PG8_LDA(dst, b, h) do { _Pragma("unroll") for (int m = 0; m < 4; ++m) _Pragma("unroll") for (int k = 0; k < 2; ++k) dst[m][k] = *(const LAS bf16x8*)(lds + PG8_SA(b, h) + aoff + m * 2048 + k * 1024); } while (0)
; #define PG8_LDB(dst, b, h) do { _Pragma("unroll") for (int n = 0; n < 2; ++n) _Pragma("unroll") for (int k = 0; k < 2; ++k) dst[n][k] = *(const LAS bf16x8*)(lds + PG8_SB(b, h) + boff + n * 2048 + k * 1024); } while (0)
; #define PG8_MMA(ai, bj, At, Bt) do { __builtin_amdgcn_s_setprio(1); _Pragma("unroll") for (int m = 0; m < 4; ++m) _Pragma("unroll") for (int n = 0; n < 2; ++n) _Pragma("unroll") for (int k = 0; k < 2; ++k) \
;         acc[ai][bj][m][n] = __builtin_amdgcn_mfma_f32_16x16x32_bf16(Bt[n][k], At[m][k], acc[ai][bj][m][n], 0, 0, 0); __builtin_amdgcn_s_setprio(0); } while (0)
; #define PG8_WAIT_V(n) asm volatile("s_waitcnt vmcnt(" #n ")" ::: "memory")
; #define PG8_WAIT_L(n) asm volatile("s_waitcnt lgkmcnt(" #n ")" ::: "memory")
; #define PG8_BAR __builtin_amdgcn_s_barrier()
; #define PG8_SCHED __builtin_amdgcn_sched_barrier(0)
; template <class Epi, class Map>
; __device__ __forceinline__ void gemm_phase(LAS unsigned char* lds, const Gemm g, const Sched<Map>& S, const Epi& E) {
;     ...
;         for (int t = 0; t < nt; t += 2) {
;             const bool last = (t == nt - 2);
;             const char* a1 = cA + (size_t)(t + 1) * kstep;
;             const char* a2 = last ? nA : cA + (size_t)(t + 2) * kstep; const char* b2 = last ? nB : cB + (size_t)(t + 2) * kstep;
;             const char* a3 = a2 + kstep; const char* b3 = b2 + kstep;
;             PG8_LDB(B0, 0, 0); PG8_LDB(B1, 0, 1); PG8_SCHED; PG8_LDA(At, 0, 0); PG8_STAGE(PG8_SA(1, 1), a1 + hstepA, voffA);
;             PG8_WAIT_V(8); PG8_WAIT_L(0); PG8_BAR; PG8_MMA(0, 0, At, B0); PG8_MMA(0, 1, At, B1); PG8_BAR; PG8_SCHED;
.LBB0_405:
	s_add_u32 s30, s28, 0xfff80080
	s_addc_u32 s31, s29, -1
	s_add_i32 s47, 0, 0x10000
	s_cmp_eq_u32 s46, 28
	s_cselect_b32 s35, s40, s31
	s_cselect_b32 s34, s41, s30
	s_cselect_b32 s31, s42, s45
	s_cselect_b32 s30, s43, s44
	s_add_i32 s50, 0, 0x14000
	v_add_u32_e32 v108, s47, v173
	v_add_u32_e32 v170, s50, v173
	ds_read_b128 v[64:67], v108
	ds_read_b128 v[68:71], v108 offset:1024
	ds_read_b128 v[72:75], v108 offset:2048
	ds_read_b128 v[108:111], v108 offset:3072
	ds_read_b128 v[166:169], v170
	ds_read_b128 v[176:179], v170 offset:1024
	ds_read_b128 v[192:195], v170 offset:2048
	ds_read_b128 v[196:199], v170 offset:3072
	v_lshl_add_u64 v[170:171], s[28:29], 0, v[162:163]
	s_add_i32 m0, s1, 0xc000
	ds_read_b128 v[200:203], v174
	ds_read_b128 v[204:207], v174 offset:1024
	ds_read_b128 v[208:211], v174 offset:2048
	ds_read_b128 v[212:215], v174 offset:3072
	ds_read_b128 v[216:219], v174 offset:4096
	ds_read_b128 v[220:223], v174 offset:5120
	ds_read_b128 v[224:227], v174 offset:6144
	ds_read_b128 v[228:231], v174 offset:7168
	global_load_lds_dwordx4 v[170:171], off
	v_lshl_add_u64 v[170:171], s[28:29], 0, v[164:165]
	s_add_i32 m0, s1, 0xe000
	s_nop 0
	global_load_lds_dwordx4 v[170:171], off
	s_waitcnt vmcnt(8)
	s_waitcnt lgkmcnt(0)
	s_barrier
	v_mfma_f32_16x16x32_bf16 v[140:143], v[64:67], v[200:203], v[140:143]
	v_mfma_f32_16x16x32_bf16 v[136:139], v[72:75], v[200:203], v[136:139]
	v_mfma_f32_16x16x32_bf16 v[132:135], v[64:67], v[208:211], v[132:135]
	v_mfma_f32_16x16x32_bf16 v[128:131], v[72:75], v[208:211], v[128:131]
	v_mfma_f32_16x16x32_bf16 v[104:107], v[64:67], v[216:219], v[104:107]
	v_mfma_f32_16x16x32_bf16 v[100:103], v[72:75], v[216:219], v[100:103]
	v_mfma_f32_16x16x32_bf16 v[96:99], v[64:67], v[224:227], v[96:99]
	v_mfma_f32_16x16x32_bf16 v[92:95], v[72:75], v[224:227], v[92:95]
	v_mfma_f32_16x16x32_bf16 v[140:143], v[68:71], v[204:207], v[140:143]
	v_mfma_f32_16x16x32_bf16 v[136:139], v[108:111], v[204:207], v[136:139]
	v_mfma_f32_16x16x32_bf16 v[132:135], v[68:71], v[212:215], v[132:135]
	v_mfma_f32_16x16x32_bf16 v[128:131], v[108:111], v[212:215], v[128:131]
	v_mfma_f32_16x16x32_bf16 v[104:107], v[68:71], v[220:223], v[104:107]
	v_mfma_f32_16x16x32_bf16 v[100:103], v[108:111], v[220:223], v[100:103]
	v_mfma_f32_16x16x32_bf16 v[96:99], v[68:71], v[228:231], v[96:99]
	v_mfma_f32_16x16x32_bf16 v[92:95], v[108:111], v[228:231], v[92:95]
	v_mfma_f32_16x16x32_bf16 v[124:127], v[166:169], v[200:203], v[124:127]
	v_mfma_f32_16x16x32_bf16 v[120:123], v[192:195], v[200:203], v[120:123]
	v_mfma_f32_16x16x32_bf16 v[116:119], v[166:169], v[208:211], v[116:119]
	v_mfma_f32_16x16x32_bf16 v[112:115], v[192:195], v[208:211], v[112:115]
	v_mfma_f32_16x16x32_bf16 v[88:91], v[166:169], v[216:219], v[88:91]
	v_mfma_f32_16x16x32_bf16 v[84:87], v[192:195], v[216:219], v[84:87]
	v_mfma_f32_16x16x32_bf16 v[80:83], v[166:169], v[224:227], v[80:83]
	v_mfma_f32_16x16x32_bf16 v[76:79], v[192:195], v[224:227], v[76:79]
	v_mfma_f32_16x16x32_bf16 v[124:127], v[176:179], v[204:207], v[124:127]
	v_mfma_f32_16x16x32_bf16 v[120:123], v[196:199], v[204:207], v[120:123]
	v_mfma_f32_16x16x32_bf16 v[116:119], v[176:179], v[212:215], v[116:119]
	v_mfma_f32_16x16x32_bf16 v[112:115], v[196:199], v[212:215], v[112:115]
	v_mfma_f32_16x16x32_bf16 v[88:91], v[176:179], v[220:223], v[88:91]
	v_mfma_f32_16x16x32_bf16 v[84:87], v[196:199], v[220:223], v[84:87]
	v_mfma_f32_16x16x32_bf16 v[80:83], v[176:179], v[228:231], v[80:83]
	v_mfma_f32_16x16x32_bf16 v[76:79], v[196:199], v[228:231], v[76:79]
	s_barrier
	s_add_i32 s47, s47, s0
	v_lshl_add_u64 v[170:171], s[30:31], 0, v[144:145]
	s_mov_b32 m0, s47
	ds_read_b128 v[200:203], v174 offset:16384
	ds_read_b128 v[204:207], v174 offset:17408
	ds_read_b128 v[208:211], v174 offset:18432
	ds_read_b128 v[212:215], v174 offset:19456
	ds_read_b128 v[216:219], v174 offset:20480
	ds_read_b128 v[220:223], v174 offset:21504
	ds_read_b128 v[224:227], v174 offset:22528
	ds_read_b128 v[228:231], v174 offset:23552
	global_load_lds_dwordx4 v[170:171], off
	s_add_i32 m0, s47, 0x2000
	s_add_u32 s48, s30, 0x80000
	v_lshl_add_u64 v[180:181], s[30:31], 0, v[160:161]
	s_addc_u32 s49, s31, 0
	s_add_i32 s47, s50, s0
	global_load_lds_dwordx4 v[180:181], off
	v_lshl_add_u64 v[232:233], s[48:49], 0, v[144:145]
	s_mov_b32 m0, s47
	v_lshl_add_u64 v[234:235], s[34:35], 0, v[160:161]
	global_load_lds_dwordx4 v[232:233], off
	v_lshl_add_u64 v[232:233], s[48:49], 0, v[160:161]
	s_add_i32 m0, s47, 0x2000
	s_nop 0
	global_load_lds_dwordx4 v[232:233], off
	v_lshl_add_u64 v[232:233], s[34:35], 0, v[144:145]
	s_mov_b32 m0, s1
	s_nop 0
	global_load_lds_dwordx4 v[232:233], off
	s_mov_b32 m0, s2
	s_nop 0
	global_load_lds_dwordx4 v[234:235], off
	s_waitcnt vmcnt(8)
	s_waitcnt lgkmcnt(0)
	s_barrier
; #define PG8_STAGE(bufoff, gbase, voff) do { _Pragma("unroll") for (int _i = 0; _i < 2; ++_i) \
;         __builtin_amdgcn_global_load_lds((const unsigned*)((const char*)(gbase) + (voff)[_i]), (LAS unsigned*)(lds + (bufoff) + ldsw + _i * 8192), 16, 0, 0); } while (0)
; #define PG8_LDA(dst, b, h) do { _Pragma("unroll") for (int m = 0; m < 4; ++m) _Pragma("unroll") for (int k = 0; k < 2; ++k) dst[m][k] = *(const LAS bf16x8*)(lds + PG8_SA(b, h) + aoff + m * 2048 + k * 1024); } while (0)
; #define PG8_LDB(dst, b, h) do { _Pragma("unroll") for (int n = 0; n < 2; ++n) _Pragma("unroll") for (int k = 0; k < 2; ++k) dst[n][k] = *(const LAS bf16x8*)(lds + PG8_SB(b, h) + boff + n * 2048 + k * 1024); } while (0)
; #define PG8_MMA(ai, bj, At, Bt) do { __builtin_amdgcn_s_setprio(1); _Pragma("unroll") for (int m = 0; m < 4; ++m) _Pragma("unroll") for (int n = 0; n < 2; ++n) _Pragma("unroll") for (int k = 0; k < 2; ++k) \
;         acc[ai][bj][m][n] = __builtin_amdgcn_mfma_f32_16x16x32_bf16(Bt[n][k], At[m][k], acc[ai][bj][m][n], 0, 0, 0); __builtin_amdgcn_s_setprio(0); } while (0)
; #define PG8_WAIT_V(n) asm volatile("s_waitcnt vmcnt(" #n ")" ::: "memory")
; #define PG8_WAIT_L(n) asm volatile("s_waitcnt lgkmcnt(" #n ")" ::: "memory")
; #define PG8_BAR __builtin_amdgcn_s_barrier()
; #define PG8_SCHED __builtin_amdgcn_sched_barrier(0)
; template <class Epi, class Map>
; __device__ __forceinline__ void gemm_phase(LAS unsigned char* lds, const Gemm g, const Sched<Map>& S, const Epi& E) {
;     ...
;             PG8_WAIT_V(8); PG8_WAIT_L(0); PG8_BAR; PG8_MMA(0, 0, At, B0); PG8_MMA(0, 1, At, B1); PG8_BAR; PG8_SCHED;
;             PG8_LDA(At, 0, 1); PG8_STAGE(PG8_SB(0, 0), b2, voffB); PG8_STAGE(PG8_SB(0, 1), b2 + hstepB, voffB); PG8_STAGE(PG8_SA(0, 0), a2, voffA);
;             PG8_WAIT_V(8); PG8_WAIT_L(0); PG8_BAR; PG8_MMA(1, 0, At, B0); PG8_MMA(1, 1, At, B1); PG8_BAR; PG8_SCHED;
;             PG8_LDB(B0, 1, 0); PG8_LDB(B1, 1, 1); PG8_SCHED; PG8_LDA(At, 1, 0); PG8_STAGE(PG8_SA(0, 1), a2 + hstepA, voffA);
;             PG8_WAIT_V(8); PG8_WAIT_L(0); PG8_BAR; PG8_MMA(0, 0, At, B0); PG8_MMA(0, 1, At, B1); PG8_BAR; PG8_SCHED;
;             PG8_LDA(At, 1, 1); PG8_STAGE(PG8_SB(1, 0), b3, voffB); PG8_STAGE(PG8_SB(1, 1), b3 + hstepB, voffB); PG8_STAGE(PG8_SA(1, 0), a3, voffA);
;             PG8_WAIT_V(8); PG8_WAIT_L(0); PG8_BAR; PG8_MMA(1, 0, At, B0); PG8_MMA(1, 1, At, B1); PG8_BAR; PG8_SCHED;
	v_mfma_f32_16x16x32_bf16 v[60:63], v[64:67], v[200:203], v[60:63]
	v_mfma_f32_16x16x32_bf16 v[56:59], v[72:75], v[200:203], v[56:59]
	v_mfma_f32_16x16x32_bf16 v[52:55], v[64:67], v[208:211], v[52:55]
	v_mfma_f32_16x16x32_bf16 v[48:51], v[72:75], v[208:211], v[48:51]
	v_mfma_f32_16x16x32_bf16 v[28:31], v[64:67], v[216:219], v[28:31]
	v_mfma_f32_16x16x32_bf16 v[24:27], v[72:75], v[216:219], v[24:27]
	v_mfma_f32_16x16x32_bf16 v[20:23], v[64:67], v[224:227], v[20:23]
	v_mfma_f32_16x16x32_bf16 v[8:11], v[72:75], v[224:227], v[8:11]
	v_mfma_f32_16x16x32_bf16 v[60:63], v[68:71], v[204:207], v[60:63]
	v_mfma_f32_16x16x32_bf16 v[56:59], v[108:111], v[204:207], v[56:59]
	v_mfma_f32_16x16x32_bf16 v[52:55], v[68:71], v[212:215], v[52:55]
	v_mfma_f32_16x16x32_bf16 v[48:51], v[108:111], v[212:215], v[48:51]
	v_mfma_f32_16x16x32_bf16 v[28:31], v[68:71], v[220:223], v[28:31]
	v_mfma_f32_16x16x32_bf16 v[24:27], v[108:111], v[220:223], v[24:27]
	v_mfma_f32_16x16x32_bf16 v[20:23], v[68:71], v[228:231], v[20:23]
	v_mfma_f32_16x16x32_bf16 v[8:11], v[108:111], v[228:231], v[8:11]
	v_mfma_f32_16x16x32_bf16 v[44:47], v[166:169], v[200:203], v[44:47]
	v_mfma_f32_16x16x32_bf16 v[40:43], v[192:195], v[200:203], v[40:43]
	v_mfma_f32_16x16x32_bf16 v[36:39], v[166:169], v[208:211], v[36:39]
	v_mfma_f32_16x16x32_bf16 v[32:35], v[192:195], v[208:211], v[32:35]
	v_mfma_f32_16x16x32_bf16 v[16:19], v[166:169], v[216:219], v[16:19]
	v_mfma_f32_16x16x32_bf16 v[12:15], v[192:195], v[216:219], v[12:15]
	v_mfma_f32_16x16x32_bf16 v[4:7], v[166:169], v[224:227], v[4:7]
	v_mfma_f32_16x16x32_bf16 v[0:3], v[192:195], v[224:227], v[0:3]
	v_mfma_f32_16x16x32_bf16 v[44:47], v[176:179], v[204:207], v[44:47]
	v_mfma_f32_16x16x32_bf16 v[40:43], v[196:199], v[204:207], v[40:43]
	v_mfma_f32_16x16x32_bf16 v[36:39], v[176:179], v[212:215], v[36:39]
	v_mfma_f32_16x16x32_bf16 v[32:35], v[196:199], v[212:215], v[32:35]
	v_mfma_f32_16x16x32_bf16 v[16:19], v[176:179], v[220:223], v[16:19]
	v_mfma_f32_16x16x32_bf16 v[12:15], v[196:199], v[220:223], v[12:15]
	v_mfma_f32_16x16x32_bf16 v[4:7], v[176:179], v[228:231], v[4:7]
	v_mfma_f32_16x16x32_bf16 v[0:3], v[196:199], v[228:231], v[0:3]
	s_barrier
	s_add_i32 s47, 0, 0x18000
	s_add_i32 s48, 0, 0x1c000
	v_add_u32_e32 v108, s47, v173
	v_add_u32_e32 v175, s48, v173
	ds_read_b128 v[64:67], v108
	ds_read_b128 v[68:71], v108 offset:1024
	ds_read_b128 v[72:75], v108 offset:2048
	ds_read_b128 v[108:111], v108 offset:3072
	ds_read_b128 v[166:169], v175
	ds_read_b128 v[176:179], v175 offset:1024
	ds_read_b128 v[192:195], v175 offset:2048
	ds_read_b128 v[196:199], v175 offset:3072
	s_add_u32 s34, s34, 0x80000
	s_addc_u32 s35, s35, 0
	s_mov_b32 m0, s3
	v_lshl_add_u64 v[236:237], s[34:35], 0, v[144:145]
	ds_read_b128 v[200:203], v174 offset:32768
	ds_read_b128 v[204:207], v174 offset:33792
	ds_read_b128 v[208:211], v174 offset:34816
	ds_read_b128 v[212:215], v174 offset:35840
	ds_read_b128 v[216:219], v174 offset:36864
	ds_read_b128 v[220:223], v174 offset:37888
	ds_read_b128 v[224:227], v174 offset:38912
	ds_read_b128 v[228:231], v174 offset:39936
	global_load_lds_dwordx4 v[236:237], off
	v_lshl_add_u64 v[236:237], s[34:35], 0, v[160:161]
	s_mov_b32 m0, s4
	s_nop 0
	global_load_lds_dwordx4 v[236:237], off
	s_waitcnt vmcnt(8)
	s_waitcnt lgkmcnt(0)
	s_barrier
	v_mfma_f32_16x16x32_bf16 v[140:143], v[64:67], v[200:203], v[140:143]
	v_mfma_f32_16x16x32_bf16 v[136:139], v[72:75], v[200:203], v[136:139]
	v_mfma_f32_16x16x32_bf16 v[132:135], v[64:67], v[208:211], v[132:135]
	v_mfma_f32_16x16x32_bf16 v[128:131], v[72:75], v[208:211], v[128:131]
	v_mfma_f32_16x16x32_bf16 v[104:107], v[64:67], v[216:219], v[104:107]
	v_mfma_f32_16x16x32_bf16 v[100:103], v[72:75], v[216:219], v[100:103]
	v_mfma_f32_16x16x32_bf16 v[96:99], v[64:67], v[224:227], v[96:99]
	v_mfma_f32_16x16x32_bf16 v[92:95], v[72:75], v[224:227], v[92:95]
	v_mfma_f32_16x16x32_bf16 v[140:143], v[68:71], v[204:207], v[140:143]
	v_mfma_f32_16x16x32_bf16 v[136:139], v[108:111], v[204:207], v[136:139]
	v_mfma_f32_16x16x32_bf16 v[132:135], v[68:71], v[212:215], v[132:135]
	v_mfma_f32_16x16x32_bf16 v[128:131], v[108:111], v[212:215], v[128:131]
	v_mfma_f32_16x16x32_bf16 v[104:107], v[68:71], v[220:223], v[104:107]
	v_mfma_f32_16x16x32_bf16 v[100:103], v[108:111], v[220:223], v[100:103]
	v_mfma_f32_16x16x32_bf16 v[96:99], v[68:71], v[228:231], v[96:99]
	v_mfma_f32_16x16x32_bf16 v[92:95], v[108:111], v[228:231], v[92:95]
	v_mfma_f32_16x16x32_bf16 v[124:127], v[166:169], v[200:203], v[124:127]
	v_mfma_f32_16x16x32_bf16 v[120:123], v[192:195], v[200:203], v[120:123]
	v_mfma_f32_16x16x32_bf16 v[116:119], v[166:169], v[208:211], v[116:119]
	v_mfma_f32_16x16x32_bf16 v[112:115], v[192:195], v[208:211], v[112:115]
	v_mfma_f32_16x16x32_bf16 v[88:91], v[166:169], v[216:219], v[88:91]
	v_mfma_f32_16x16x32_bf16 v[84:87], v[192:195], v[216:219], v[84:87]
	v_mfma_f32_16x16x32_bf16 v[80:83], v[166:169], v[224:227], v[80:83]
	v_mfma_f32_16x16x32_bf16 v[76:79], v[192:195], v[224:227], v[76:79]
	v_mfma_f32_16x16x32_bf16 v[124:127], v[176:179], v[204:207], v[124:127]
	v_mfma_f32_16x16x32_bf16 v[120:123], v[196:199], v[204:207], v[120:123]
	v_mfma_f32_16x16x32_bf16 v[116:119], v[176:179], v[212:215], v[116:119]
	v_mfma_f32_16x16x32_bf16 v[112:115], v[196:199], v[212:215], v[112:115]
	v_mfma_f32_16x16x32_bf16 v[88:91], v[176:179], v[220:223], v[88:91]
	v_mfma_f32_16x16x32_bf16 v[84:87], v[196:199], v[220:223], v[84:87]
	v_mfma_f32_16x16x32_bf16 v[80:83], v[176:179], v[228:231], v[80:83]
	v_mfma_f32_16x16x32_bf16 v[76:79], v[196:199], v[228:231], v[76:79]
	s_barrier
; #define PG8_STAGE(bufoff, gbase, voff) do { _Pragma("unroll") for (int _i = 0; _i < 2; ++_i) \
;         __builtin_amdgcn_global_load_lds((const unsigned*)((const char*)(gbase) + (voff)[_i]), (LAS unsigned*)(lds + (bufoff) + ldsw + _i * 8192), 16, 0, 0); } while (0)
; #define PG8_LDA(dst, b, h) do { _Pragma("unroll") for (int m = 0; m < 4; ++m) _Pragma("unroll") for (int k = 0; k < 2; ++k) dst[m][k] = *(const LAS bf16x8*)(lds + PG8_SA(b, h) + aoff + m * 2048 + k * 1024); } while (0)
; #define PG8_MMA(ai, bj, At, Bt) do { __builtin_amdgcn_s_setprio(1); _Pragma("unroll") for (int m = 0; m < 4; ++m) _Pragma("unroll") for (int n = 0; n < 2; ++n) _Pragma("unroll") for (int k = 0; k < 2; ++k) \
;         acc[ai][bj][m][n] = __builtin_amdgcn_mfma_f32_16x16x32_bf16(Bt[n][k], At[m][k], acc[ai][bj][m][n], 0, 0, 0); __builtin_amdgcn_s_setprio(0); } while (0)
; #define PG8_WAIT_V(n) asm volatile("s_waitcnt vmcnt(" #n ")" ::: "memory")
; #define PG8_WAIT_L(n) asm volatile("s_waitcnt lgkmcnt(" #n ")" ::: "memory")
; #define PG8_BAR __builtin_amdgcn_s_barrier()
; #define PG8_SCHED __builtin_amdgcn_sched_barrier(0)
; template <class Epi, class Map>
; __device__ __forceinline__ void gemm_phase(LAS unsigned char* lds, const Gemm g, const Sched<Map>& S, const Epi& E) {
;     ...
;             PG8_LDA(At, 1, 1); PG8_STAGE(PG8_SB(1, 0), b3, voffB); PG8_STAGE(PG8_SB(1, 1), b3 + hstepB, voffB); PG8_STAGE(PG8_SA(1, 0), a3, voffA);
;             PG8_WAIT_V(8); PG8_WAIT_L(0); PG8_BAR; PG8_MMA(1, 0, At, B0); PG8_MMA(1, 1, At, B1); PG8_BAR; PG8_SCHED;
;         }
	s_add_i32 s34, s47, s0
	v_lshl_add_u64 v[170:171], v[170:171], 0, s[82:83]
	s_mov_b32 m0, s34
	ds_read_b128 v[200:203], v174 offset:49152
	ds_read_b128 v[204:207], v174 offset:50176
	ds_read_b128 v[208:211], v174 offset:51200
	ds_read_b128 v[212:215], v174 offset:52224
	ds_read_b128 v[216:219], v174 offset:53248
	ds_read_b128 v[220:223], v174 offset:54272
	ds_read_b128 v[224:227], v174 offset:55296
	ds_read_b128 v[228:231], v174 offset:56320
	global_load_lds_dwordx4 v[170:171], off
	s_add_i32 m0, s34, 0x2000
	s_add_u32 s30, s30, 0x80080
	v_lshl_add_u64 v[170:171], v[180:181], 0, s[82:83]
	s_addc_u32 s31, s31, 0
	s_add_i32 s34, s48, s0
	global_load_lds_dwordx4 v[170:171], off
	v_lshl_add_u64 v[170:171], s[30:31], 0, v[144:145]
	s_mov_b32 m0, s34
	s_nop 0
	global_load_lds_dwordx4 v[170:171], off
	v_lshl_add_u64 v[170:171], s[30:31], 0, v[160:161]
	s_add_i32 m0, s34, 0x2000
	s_nop 0
	global_load_lds_dwordx4 v[170:171], off
	v_lshl_add_u64 v[170:171], v[232:233], 0, s[82:83]
	s_mov_b32 m0, s10
	s_nop 0
	global_load_lds_dwordx4 v[170:171], off
	v_lshl_add_u64 v[170:171], v[234:235], 0, s[82:83]
	s_mov_b32 m0, s11
	s_nop 0
	global_load_lds_dwordx4 v[170:171], off
	s_waitcnt vmcnt(8)
	s_waitcnt lgkmcnt(0)
	s_barrier
	v_mfma_f32_16x16x32_bf16 v[60:63], v[64:67], v[200:203], v[60:63]
	v_mfma_f32_16x16x32_bf16 v[56:59], v[72:75], v[200:203], v[56:59]
	v_mfma_f32_16x16x32_bf16 v[52:55], v[64:67], v[208:211], v[52:55]
	v_mfma_f32_16x16x32_bf16 v[48:51], v[72:75], v[208:211], v[48:51]
	v_mfma_f32_16x16x32_bf16 v[28:31], v[64:67], v[216:219], v[28:31]
	v_mfma_f32_16x16x32_bf16 v[24:27], v[72:75], v[216:219], v[24:27]
	v_mfma_f32_16x16x32_bf16 v[20:23], v[64:67], v[224:227], v[20:23]
	v_mfma_f32_16x16x32_bf16 v[8:11], v[72:75], v[224:227], v[8:11]
	v_mfma_f32_16x16x32_bf16 v[60:63], v[68:71], v[204:207], v[60:63]
	v_mfma_f32_16x16x32_bf16 v[56:59], v[108:111], v[204:207], v[56:59]
	v_mfma_f32_16x16x32_bf16 v[52:55], v[68:71], v[212:215], v[52:55]
	v_mfma_f32_16x16x32_bf16 v[48:51], v[108:111], v[212:215], v[48:51]
	v_mfma_f32_16x16x32_bf16 v[28:31], v[68:71], v[220:223], v[28:31]
	v_mfma_f32_16x16x32_bf16 v[24:27], v[108:111], v[220:223], v[24:27]
	v_mfma_f32_16x16x32_bf16 v[20:23], v[68:71], v[228:231], v[20:23]
	v_mfma_f32_16x16x32_bf16 v[8:11], v[108:111], v[228:231], v[8:11]
	v_mfma_f32_16x16x32_bf16 v[44:47], v[166:169], v[200:203], v[44:47]
	v_mfma_f32_16x16x32_bf16 v[40:43], v[192:195], v[200:203], v[40:43]
	v_mfma_f32_16x16x32_bf16 v[36:39], v[166:169], v[208:211], v[36:39]
	v_mfma_f32_16x16x32_bf16 v[32:35], v[192:195], v[208:211], v[32:35]
	v_mfma_f32_16x16x32_bf16 v[16:19], v[166:169], v[216:219], v[16:19]
	v_mfma_f32_16x16x32_bf16 v[12:15], v[192:195], v[216:219], v[12:15]
	v_mfma_f32_16x16x32_bf16 v[4:7], v[166:169], v[224:227], v[4:7]
	v_mfma_f32_16x16x32_bf16 v[0:3], v[192:195], v[224:227], v[0:3]
	v_mfma_f32_16x16x32_bf16 v[44:47], v[176:179], v[204:207], v[44:47]
	v_mfma_f32_16x16x32_bf16 v[40:43], v[196:199], v[204:207], v[40:43]
	v_mfma_f32_16x16x32_bf16 v[36:39], v[176:179], v[212:215], v[36:39]
	v_mfma_f32_16x16x32_bf16 v[32:35], v[196:199], v[212:215], v[32:35]
	v_mfma_f32_16x16x32_bf16 v[16:19], v[176:179], v[220:223], v[16:19]
	v_mfma_f32_16x16x32_bf16 v[12:15], v[196:199], v[220:223], v[12:15]
	v_mfma_f32_16x16x32_bf16 v[4:7], v[176:179], v[228:231], v[4:7]
	v_mfma_f32_16x16x32_bf16 v[0:3], v[196:199], v[228:231], v[0:3]
	s_barrier
	s_add_i32 s46, s46, 2
	s_add_u32 s28, s28, 0x100
	s_addc_u32 s29, s29, 0
	s_add_u32 s44, s44, 0x100
	s_addc_u32 s45, s45, 0
	s_cmp_gt_u32 s46, 29
	s_cbranch_scc0 .LBB0_405
	s_and_b64 vcc, exec, s[18:19]
	s_cbranch_vccz .LBB0_408

; #define PG8_STAGE(bufoff, gbase, voff) do { _Pragma("unroll") for (int _i = 0; _i < 2; ++_i) \
;         __builtin_amdgcn_global_load_lds((const unsigned*)((const char*)(gbase) + (voff)[_i]), (LAS unsigned*)(lds + (bufoff) + ldsw + _i * 8192), 16, 0, 0); } while (0)
; #define PG8_LDA(dst, b, h) do { _Pragma("unroll") for (int m = 0; m < 4; ++m) _Pragma("unroll") for (int k = 0; k < 2; ++k) dst[m][k] = *(const LAS bf16x8*)(lds + PG8_SA(b, h) + aoff + m * 2048 + k * 1024); } while (0)
; #define PG8_LDB(dst, b, h) do { _Pragma("unroll") for (int n = 0; n < 2; ++n) _Pragma("unroll") for (int k = 0; k < 2; ++k) dst[n][k] = *(const LAS bf16x8*)(lds + PG8_SB(b, h) + boff + n * 2048 + k * 1024); } while (0)
; #define PG8_MMA(ai, bj, At, Bt) do { __builtin_amdgcn_s_setprio(1); _Pragma("unroll") for (int m = 0; m < 4; ++m) _Pragma("unroll") for (int n = 0; n < 2; ++n) _Pragma("unroll") for (int k = 0; k < 2; ++k) \
;         acc[ai][bj][m][n] = __builtin_amdgcn_mfma_f32_16x16x32_bf16(Bt[n][k], At[m][k], acc[ai][bj][m][n], 0, 0, 0); __builtin_amdgcn_s_setprio(0); } while (0)
; #define PG8_WAIT_V(n) asm volatile("s_waitcnt vmcnt(" #n ")" ::: "memory")
; #define PG8_WAIT_L(n) asm volatile("s_waitcnt lgkmcnt(" #n ")" ::: "memory")
; #define PG8_BAR __builtin_amdgcn_s_barrier()
; #define PG8_SCHED __builtin_amdgcn_sched_barrier(0)
; template <class Epi, class Map>
; __device__ __forceinline__ void gemm_phase(LAS unsigned char* lds, const Gemm g, const Sched<Map>& S, const Epi& E) {
;     ...
;         for (int t = 0; t < nt; t += 2) {
;             const bool last = (t == nt - 2);
;             const char* a1 = cA + (size_t)(t + 1) * kstep;
;             const char* a2 = last ? nA : cA + (size_t)(t + 2) * kstep; const char* b2 = last ? nB : cB + (size_t)(t + 2) * kstep;
;             const char* a3 = a2 + kstep; const char* b3 = b2 + kstep;
;             PG8_LDB(B0, 0, 0); PG8_LDB(B1, 0, 1); PG8_SCHED; PG8_LDA(At, 0, 0); PG8_STAGE(PG8_SA(1, 1), a1 + hstepA, voffA);
;             PG8_WAIT_V(8); PG8_WAIT_L(0); PG8_BAR; PG8_MMA(0, 0, At, B0); PG8_MMA(0, 1, At, B1); PG8_BAR; PG8_SCHED;
;             PG8_LDA(At, 0, 1); PG8_STAGE(PG8_SB(0, 0), b2, voffB); PG8_STAGE(PG8_SB(0, 1), b2 + hstepB, voffB); PG8_STAGE(PG8_SA(0, 0), a2, voffA);
;             PG8_WAIT_V(8); PG8_WAIT_L(0); PG8_BAR; PG8_MMA(1, 0, At, B0); PG8_MMA(1, 1, At, B1); PG8_BAR; PG8_SCHED;
.LBB0_552:
	s_add_u32 s14, s24, 0xfff80080
	s_addc_u32 s15, s25, -1
	s_add_i32 s19, 0, 0x10000
	s_cmp_eq_u32 s13, 28
	s_cselect_b32 s31, s3, s15
	s_cselect_b32 s30, s8, s14
	v_add_u32_e32 v142, s19, v168
	s_cselect_b32 s29, s9, s12
	s_cselect_b32 s28, s10, s11
	s_add_i32 s21, 0, 0x14000
	ds_read_b128 v[128:131], v142
	ds_read_b128 v[160:163], v142 offset:1024
	ds_read_b128 v[170:173], v142 offset:2048
	ds_read_b128 v[174:177], v142 offset:3072
	v_add_u32_e32 v142, s21, v168
	ds_read_b128 v[178:181], v142
	ds_read_b128 v[192:195], v142 offset:1024
	ds_read_b128 v[196:199], v142 offset:2048
	ds_read_b128 v[200:203], v142 offset:3072
	v_lshl_add_u64 v[142:143], s[24:25], 0, v[138:139]
	s_add_i32 m0, s35, 0xc000
	ds_read_b128 v[204:207], v169
	ds_read_b128 v[208:211], v169 offset:1024
	ds_read_b128 v[212:215], v169 offset:2048
	ds_read_b128 v[216:219], v169 offset:3072
	ds_read_b128 v[220:223], v169 offset:4096
	ds_read_b128 v[224:227], v169 offset:5120
	ds_read_b128 v[228:231], v169 offset:6144
	ds_read_b128 v[232:235], v169 offset:7168
	global_load_lds_dwordx4 v[142:143], off
	v_lshl_add_u64 v[142:143], s[24:25], 0, v[140:141]
	s_add_i32 m0, s35, 0xe000
	s_nop 0
	global_load_lds_dwordx4 v[142:143], off
	s_waitcnt vmcnt(8)
	s_waitcnt lgkmcnt(0)
	s_barrier
	v_mfma_f32_16x16x32_bf16 v[124:127], v[128:131], v[204:207], v[124:127]
	v_mfma_f32_16x16x32_bf16 v[116:119], v[170:173], v[204:207], v[116:119]
	v_mfma_f32_16x16x32_bf16 v[108:111], v[128:131], v[212:215], v[108:111]
	v_mfma_f32_16x16x32_bf16 v[96:99], v[170:173], v[212:215], v[96:99]
	v_mfma_f32_16x16x32_bf16 v[92:95], v[128:131], v[220:223], v[92:95]
	v_mfma_f32_16x16x32_bf16 v[80:83], v[170:173], v[220:223], v[80:83]
	v_mfma_f32_16x16x32_bf16 v[76:79], v[128:131], v[228:231], v[76:79]
	v_mfma_f32_16x16x32_bf16 v[64:67], v[170:173], v[228:231], v[64:67]
	v_mfma_f32_16x16x32_bf16 v[124:127], v[160:163], v[208:211], v[124:127]
	v_mfma_f32_16x16x32_bf16 v[116:119], v[174:177], v[208:211], v[116:119]
	v_mfma_f32_16x16x32_bf16 v[108:111], v[160:163], v[216:219], v[108:111]
	v_mfma_f32_16x16x32_bf16 v[96:99], v[174:177], v[216:219], v[96:99]
	v_mfma_f32_16x16x32_bf16 v[92:95], v[160:163], v[224:227], v[92:95]
	v_mfma_f32_16x16x32_bf16 v[80:83], v[174:177], v[224:227], v[80:83]
	v_mfma_f32_16x16x32_bf16 v[76:79], v[160:163], v[232:235], v[76:79]
	v_mfma_f32_16x16x32_bf16 v[64:67], v[174:177], v[232:235], v[64:67]
	v_mfma_f32_16x16x32_bf16 v[120:123], v[178:181], v[204:207], v[120:123]
	v_mfma_f32_16x16x32_bf16 v[112:115], v[196:199], v[204:207], v[112:115]
	v_mfma_f32_16x16x32_bf16 v[104:107], v[178:181], v[212:215], v[104:107]
	v_mfma_f32_16x16x32_bf16 v[100:103], v[196:199], v[212:215], v[100:103]
	v_mfma_f32_16x16x32_bf16 v[88:91], v[178:181], v[220:223], v[88:91]
	v_mfma_f32_16x16x32_bf16 v[84:87], v[196:199], v[220:223], v[84:87]
	v_mfma_f32_16x16x32_bf16 v[72:75], v[178:181], v[228:231], v[72:75]
	v_mfma_f32_16x16x32_bf16 v[68:71], v[196:199], v[228:231], v[68:71]
	v_mfma_f32_16x16x32_bf16 v[120:123], v[192:195], v[208:211], v[120:123]
	v_mfma_f32_16x16x32_bf16 v[112:115], v[200:203], v[208:211], v[112:115]
	v_mfma_f32_16x16x32_bf16 v[104:107], v[192:195], v[216:219], v[104:107]
	v_mfma_f32_16x16x32_bf16 v[100:103], v[200:203], v[216:219], v[100:103]
	v_mfma_f32_16x16x32_bf16 v[88:91], v[192:195], v[224:227], v[88:91]
	v_mfma_f32_16x16x32_bf16 v[84:87], v[200:203], v[224:227], v[84:87]
	v_mfma_f32_16x16x32_bf16 v[72:75], v[192:195], v[232:235], v[72:75]
	v_mfma_f32_16x16x32_bf16 v[68:71], v[200:203], v[232:235], v[68:71]
	s_barrier
	s_add_i32 s14, s19, s34
	v_lshl_add_u64 v[142:143], s[28:29], 0, v[144:145]
	s_mov_b32 m0, s14
	ds_read_b128 v[204:207], v169 offset:16384
	ds_read_b128 v[208:211], v169 offset:17408
	ds_read_b128 v[212:215], v169 offset:18432
	ds_read_b128 v[216:219], v169 offset:19456
	ds_read_b128 v[220:223], v169 offset:20480
	ds_read_b128 v[224:227], v169 offset:21504
	ds_read_b128 v[228:231], v169 offset:22528
	ds_read_b128 v[232:235], v169 offset:23552
	global_load_lds_dwordx4 v[142:143], off
	s_add_i32 m0, s14, 0x2000
	s_add_u32 s14, s28, 0x80000
	v_lshl_add_u64 v[164:165], s[28:29], 0, v[136:137]
	s_addc_u32 s15, s29, 0
	s_add_i32 s19, s21, s34
	global_load_lds_dwordx4 v[164:165], off
	v_lshl_add_u64 v[236:237], s[14:15], 0, v[144:145]
	s_mov_b32 m0, s19
	v_lshl_add_u64 v[238:239], s[30:31], 0, v[134:135]
	global_load_lds_dwordx4 v[236:237], off
	v_lshl_add_u64 v[236:237], s[14:15], 0, v[136:137]
	s_add_i32 m0, s19, 0x2000
	s_nop 0
	global_load_lds_dwordx4 v[236:237], off
	v_lshl_add_u64 v[236:237], s[30:31], 0, v[132:133]
	s_mov_b32 m0, s35
	s_nop 0
	global_load_lds_dwordx4 v[236:237], off
	s_mov_b32 m0, s84
	s_nop 0
	global_load_lds_dwordx4 v[238:239], off
	s_waitcnt vmcnt(8)
	s_waitcnt lgkmcnt(0)
	s_barrier
; #define PG8_STAGE(bufoff, gbase, voff) do { _Pragma("unroll") for (int _i = 0; _i < 2; ++_i) \
;         __builtin_amdgcn_global_load_lds((const unsigned*)((const char*)(gbase) + (voff)[_i]), (LAS unsigned*)(lds + (bufoff) + ldsw + _i * 8192), 16, 0, 0); } while (0)
; #define PG8_LDA(dst, b, h) do { _Pragma("unroll") for (int m = 0; m < 4; ++m) _Pragma("unroll") for (int k = 0; k < 2; ++k) dst[m][k] = *(const LAS bf16x8*)(lds + PG8_SA(b, h) + aoff + m * 2048 + k * 1024); } while (0)
; #define PG8_LDB(dst, b, h) do { _Pragma("unroll") for (int n = 0; n < 2; ++n) _Pragma("unroll") for (int k = 0; k < 2; ++k) dst[n][k] = *(const LAS bf16x8*)(lds + PG8_SB(b, h) + boff + n * 2048 + k * 1024); } while (0)
; #define PG8_MMA(ai, bj, At, Bt) do { __builtin_amdgcn_s_setprio(1); _Pragma("unroll") for (int m = 0; m < 4; ++m) _Pragma("unroll") for (int n = 0; n < 2; ++n) _Pragma("unroll") for (int k = 0; k < 2; ++k) \
;         acc[ai][bj][m][n] = __builtin_amdgcn_mfma_f32_16x16x32_bf16(Bt[n][k], At[m][k], acc[ai][bj][m][n], 0, 0, 0); __builtin_amdgcn_s_setprio(0); } while (0)
; #define PG8_WAIT_V(n) asm volatile("s_waitcnt vmcnt(" #n ")" ::: "memory")
; #define PG8_WAIT_L(n) asm volatile("s_waitcnt lgkmcnt(" #n ")" ::: "memory")
; #define PG8_BAR __builtin_amdgcn_s_barrier()
; #define PG8_SCHED __builtin_amdgcn_sched_barrier(0)
; template <class Epi, class Map>
; __device__ __forceinline__ void gemm_phase(LAS unsigned char* lds, const Gemm g, const Sched<Map>& S, const Epi& E) {
;     ...
;             PG8_WAIT_V(8); PG8_WAIT_L(0); PG8_BAR; PG8_MMA(1, 0, At, B0); PG8_MMA(1, 1, At, B1); PG8_BAR; PG8_SCHED;
;             PG8_LDB(B0, 1, 0); PG8_LDB(B1, 1, 1); PG8_SCHED; PG8_LDA(At, 1, 0); PG8_STAGE(PG8_SA(0, 1), a2 + hstepA, voffA);
;             PG8_WAIT_V(8); PG8_WAIT_L(0); PG8_BAR; PG8_MMA(0, 0, At, B0); PG8_MMA(0, 1, At, B1); PG8_BAR; PG8_SCHED;
	v_mfma_f32_16x16x32_bf16 v[60:63], v[128:131], v[204:207], v[60:63]
	v_mfma_f32_16x16x32_bf16 v[48:51], v[170:173], v[204:207], v[48:51]
	v_mfma_f32_16x16x32_bf16 v[44:47], v[128:131], v[212:215], v[44:47]
	v_mfma_f32_16x16x32_bf16 v[32:35], v[170:173], v[212:215], v[32:35]
	v_mfma_f32_16x16x32_bf16 v[28:31], v[128:131], v[220:223], v[28:31]
	v_mfma_f32_16x16x32_bf16 v[16:19], v[170:173], v[220:223], v[16:19]
	v_mfma_f32_16x16x32_bf16 v[12:15], v[128:131], v[228:231], v[12:15]
	v_mfma_f32_16x16x32_bf16 v[0:3], v[170:173], v[228:231], v[0:3]
	v_mfma_f32_16x16x32_bf16 v[60:63], v[160:163], v[208:211], v[60:63]
	v_mfma_f32_16x16x32_bf16 v[48:51], v[174:177], v[208:211], v[48:51]
	v_mfma_f32_16x16x32_bf16 v[44:47], v[160:163], v[216:219], v[44:47]
	v_mfma_f32_16x16x32_bf16 v[32:35], v[174:177], v[216:219], v[32:35]
	v_mfma_f32_16x16x32_bf16 v[28:31], v[160:163], v[224:227], v[28:31]
	v_mfma_f32_16x16x32_bf16 v[16:19], v[174:177], v[224:227], v[16:19]
	v_mfma_f32_16x16x32_bf16 v[12:15], v[160:163], v[232:235], v[12:15]
	v_mfma_f32_16x16x32_bf16 v[0:3], v[174:177], v[232:235], v[0:3]
	v_mfma_f32_16x16x32_bf16 v[56:59], v[178:181], v[204:207], v[56:59]
	v_mfma_f32_16x16x32_bf16 v[52:55], v[196:199], v[204:207], v[52:55]
	v_mfma_f32_16x16x32_bf16 v[40:43], v[178:181], v[212:215], v[40:43]
	v_mfma_f32_16x16x32_bf16 v[36:39], v[196:199], v[212:215], v[36:39]
	v_mfma_f32_16x16x32_bf16 v[24:27], v[178:181], v[220:223], v[24:27]
	v_mfma_f32_16x16x32_bf16 v[20:23], v[196:199], v[220:223], v[20:23]
	v_mfma_f32_16x16x32_bf16 v[8:11], v[178:181], v[228:231], v[8:11]
	v_mfma_f32_16x16x32_bf16 v[4:7], v[196:199], v[228:231], v[4:7]
	v_mfma_f32_16x16x32_bf16 v[56:59], v[192:195], v[208:211], v[56:59]
	v_mfma_f32_16x16x32_bf16 v[52:55], v[200:203], v[208:211], v[52:55]
	v_mfma_f32_16x16x32_bf16 v[40:43], v[192:195], v[216:219], v[40:43]
	v_mfma_f32_16x16x32_bf16 v[36:39], v[200:203], v[216:219], v[36:39]
	v_mfma_f32_16x16x32_bf16 v[24:27], v[192:195], v[224:227], v[24:27]
	v_mfma_f32_16x16x32_bf16 v[20:23], v[200:203], v[224:227], v[20:23]
	v_mfma_f32_16x16x32_bf16 v[8:11], v[192:195], v[232:235], v[8:11]
	v_mfma_f32_16x16x32_bf16 v[4:7], v[200:203], v[232:235], v[4:7]
	s_barrier
	s_add_i32 s19, 0, 0x18000
	s_add_i32 s21, 0, 0x1c000
	v_add_u32_e32 v174, s19, v168
	v_add_u32_e32 v200, s21, v168
	ds_read_b128 v[128:131], v174
	ds_read_b128 v[160:163], v174 offset:1024
	ds_read_b128 v[170:173], v174 offset:2048
	ds_read_b128 v[174:177], v174 offset:3072
	ds_read_b128 v[178:181], v200
	ds_read_b128 v[192:195], v200 offset:1024
	ds_read_b128 v[196:199], v200 offset:2048
	ds_read_b128 v[200:203], v200 offset:3072
	s_add_u32 s14, s30, 0x80000
	s_addc_u32 s15, s31, 0
	s_mov_b32 m0, s85
	v_lshl_add_u64 v[240:241], s[14:15], 0, v[132:133]
	ds_read_b128 v[204:207], v169 offset:32768
	ds_read_b128 v[208:211], v169 offset:33792
	ds_read_b128 v[212:215], v169 offset:34816
	ds_read_b128 v[216:219], v169 offset:35840
	ds_read_b128 v[220:223], v169 offset:36864
	ds_read_b128 v[224:227], v169 offset:37888
	ds_read_b128 v[228:231], v169 offset:38912
	ds_read_b128 v[232:235], v169 offset:39936
	global_load_lds_dwordx4 v[240:241], off
	v_lshl_add_u64 v[240:241], s[14:15], 0, v[134:135]
	s_mov_b32 m0, s90
	s_nop 0
	global_load_lds_dwordx4 v[240:241], off
	s_waitcnt vmcnt(8)
	s_waitcnt lgkmcnt(0)
	s_barrier
	v_mfma_f32_16x16x32_bf16 v[124:127], v[128:131], v[204:207], v[124:127]
	v_mfma_f32_16x16x32_bf16 v[116:119], v[170:173], v[204:207], v[116:119]
	v_mfma_f32_16x16x32_bf16 v[108:111], v[128:131], v[212:215], v[108:111]
	v_mfma_f32_16x16x32_bf16 v[96:99], v[170:173], v[212:215], v[96:99]
	v_mfma_f32_16x16x32_bf16 v[92:95], v[128:131], v[220:223], v[92:95]
	v_mfma_f32_16x16x32_bf16 v[80:83], v[170:173], v[220:223], v[80:83]
	v_mfma_f32_16x16x32_bf16 v[76:79], v[128:131], v[228:231], v[76:79]
	v_mfma_f32_16x16x32_bf16 v[64:67], v[170:173], v[228:231], v[64:67]
	v_mfma_f32_16x16x32_bf16 v[124:127], v[160:163], v[208:211], v[124:127]
	v_mfma_f32_16x16x32_bf16 v[116:119], v[174:177], v[208:211], v[116:119]
	v_mfma_f32_16x16x32_bf16 v[108:111], v[160:163], v[216:219], v[108:111]
	v_mfma_f32_16x16x32_bf16 v[96:99], v[174:177], v[216:219], v[96:99]
	v_mfma_f32_16x16x32_bf16 v[92:95], v[160:163], v[224:227], v[92:95]
	v_mfma_f32_16x16x32_bf16 v[80:83], v[174:177], v[224:227], v[80:83]
	v_mfma_f32_16x16x32_bf16 v[76:79], v[160:163], v[232:235], v[76:79]
	v_mfma_f32_16x16x32_bf16 v[64:67], v[174:177], v[232:235], v[64:67]
	v_mfma_f32_16x16x32_bf16 v[120:123], v[178:181], v[204:207], v[120:123]
	v_mfma_f32_16x16x32_bf16 v[112:115], v[196:199], v[204:207], v[112:115]
	v_mfma_f32_16x16x32_bf16 v[104:107], v[178:181], v[212:215], v[104:107]
	v_mfma_f32_16x16x32_bf16 v[100:103], v[196:199], v[212:215], v[100:103]
	v_mfma_f32_16x16x32_bf16 v[88:91], v[178:181], v[220:223], v[88:91]
	v_mfma_f32_16x16x32_bf16 v[84:87], v[196:199], v[220:223], v[84:87]
	v_mfma_f32_16x16x32_bf16 v[72:75], v[178:181], v[228:231], v[72:75]
	v_mfma_f32_16x16x32_bf16 v[68:71], v[196:199], v[228:231], v[68:71]
	v_mfma_f32_16x16x32_bf16 v[120:123], v[192:195], v[208:211], v[120:123]
	v_mfma_f32_16x16x32_bf16 v[112:115], v[200:203], v[208:211], v[112:115]
	v_mfma_f32_16x16x32_bf16 v[104:107], v[192:195], v[216:219], v[104:107]
	v_mfma_f32_16x16x32_bf16 v[100:103], v[200:203], v[216:219], v[100:103]
	v_mfma_f32_16x16x32_bf16 v[88:91], v[192:195], v[224:227], v[88:91]
	v_mfma_f32_16x16x32_bf16 v[84:87], v[200:203], v[224:227], v[84:87]
	v_mfma_f32_16x16x32_bf16 v[72:75], v[192:195], v[232:235], v[72:75]
	v_mfma_f32_16x16x32_bf16 v[68:71], v[200:203], v[232:235], v[68:71]
	s_barrier
; #define PG8_STAGE(bufoff, gbase, voff) do { _Pragma("unroll") for (int _i = 0; _i < 2; ++_i) \
;         __builtin_amdgcn_global_load_lds((const unsigned*)((const char*)(gbase) + (voff)[_i]), (LAS unsigned*)(lds + (bufoff) + ldsw + _i * 8192), 16, 0, 0); } while (0)
; #define PG8_LDA(dst, b, h) do { _Pragma("unroll") for (int m = 0; m < 4; ++m) _Pragma("unroll") for (int k = 0; k < 2; ++k) dst[m][k] = *(const LAS bf16x8*)(lds + PG8_SA(b, h) + aoff + m * 2048 + k * 1024); } while (0)
; #define PG8_MMA(ai, bj, At, Bt) do { __builtin_amdgcn_s_setprio(1); _Pragma("unroll") for (int m = 0; m < 4; ++m) _Pragma("unroll") for (int n = 0; n < 2; ++n) _Pragma("unroll") for (int k = 0; k < 2; ++k) \
;         acc[ai][bj][m][n] = __builtin_amdgcn_mfma_f32_16x16x32_bf16(Bt[n][k], At[m][k], acc[ai][bj][m][n], 0, 0, 0); __builtin_amdgcn_s_setprio(0); } while (0)
; #define PG8_WAIT_V(n) asm volatile("s_waitcnt vmcnt(" #n ")" ::: "memory")
; #define PG8_WAIT_L(n) asm volatile("s_waitcnt lgkmcnt(" #n ")" ::: "memory")
; #define PG8_BAR __builtin_amdgcn_s_barrier()
; #define PG8_SCHED __builtin_amdgcn_sched_barrier(0)
; template <class Epi, class Map>
; __device__ __forceinline__ void gemm_phase(LAS unsigned char* lds, const Gemm g, const Sched<Map>& S, const Epi& E) {
;     ...
;             PG8_LDA(At, 1, 1); PG8_STAGE(PG8_SB(1, 0), b3, voffB); PG8_STAGE(PG8_SB(1, 1), b3 + hstepB, voffB); PG8_STAGE(PG8_SA(1, 0), a3, voffA);
;             PG8_WAIT_V(8); PG8_WAIT_L(0); PG8_BAR; PG8_MMA(1, 0, At, B0); PG8_MMA(1, 1, At, B1); PG8_BAR; PG8_SCHED;
;         }
	s_add_i32 s14, s19, s34
	v_lshl_add_u64 v[142:143], v[142:143], 0, s[82:83]
	s_mov_b32 m0, s14
	ds_read_b128 v[204:207], v169 offset:49152
	ds_read_b128 v[208:211], v169 offset:50176
	ds_read_b128 v[212:215], v169 offset:51200
	ds_read_b128 v[216:219], v169 offset:52224
	ds_read_b128 v[220:223], v169 offset:53248
	ds_read_b128 v[224:227], v169 offset:54272
	ds_read_b128 v[228:231], v169 offset:55296
	ds_read_b128 v[232:235], v169 offset:56320
	global_load_lds_dwordx4 v[142:143], off
	s_add_i32 m0, s14, 0x2000
	s_add_u32 s14, s28, 0x80080
	v_lshl_add_u64 v[142:143], v[164:165], 0, s[82:83]
	s_addc_u32 s15, s29, 0
	s_add_i32 s19, s21, s34
	global_load_lds_dwordx4 v[142:143], off
	v_lshl_add_u64 v[142:143], s[14:15], 0, v[144:145]
	s_mov_b32 m0, s19
	s_nop 0
	global_load_lds_dwordx4 v[142:143], off
	v_lshl_add_u64 v[142:143], s[14:15], 0, v[136:137]
	s_add_i32 m0, s19, 0x2000
	s_nop 0
	global_load_lds_dwordx4 v[142:143], off
	v_lshl_add_u64 v[142:143], v[236:237], 0, s[82:83]
	s_mov_b32 m0, s97
	s_nop 0
	global_load_lds_dwordx4 v[142:143], off
	v_lshl_add_u64 v[142:143], v[238:239], 0, s[82:83]
	s_mov_b32 m0, s56
	s_nop 0
	global_load_lds_dwordx4 v[142:143], off
	s_waitcnt vmcnt(8)
	s_waitcnt lgkmcnt(0)
	s_barrier
	v_mfma_f32_16x16x32_bf16 v[60:63], v[128:131], v[204:207], v[60:63]
	v_mfma_f32_16x16x32_bf16 v[48:51], v[170:173], v[204:207], v[48:51]
	v_mfma_f32_16x16x32_bf16 v[44:47], v[128:131], v[212:215], v[44:47]
	v_mfma_f32_16x16x32_bf16 v[32:35], v[170:173], v[212:215], v[32:35]
	v_mfma_f32_16x16x32_bf16 v[28:31], v[128:131], v[220:223], v[28:31]
	v_mfma_f32_16x16x32_bf16 v[16:19], v[170:173], v[220:223], v[16:19]
	v_mfma_f32_16x16x32_bf16 v[12:15], v[128:131], v[228:231], v[12:15]
	v_mfma_f32_16x16x32_bf16 v[0:3], v[170:173], v[228:231], v[0:3]
	v_mfma_f32_16x16x32_bf16 v[60:63], v[160:163], v[208:211], v[60:63]
	v_mfma_f32_16x16x32_bf16 v[48:51], v[174:177], v[208:211], v[48:51]
	v_mfma_f32_16x16x32_bf16 v[44:47], v[160:163], v[216:219], v[44:47]
	v_mfma_f32_16x16x32_bf16 v[32:35], v[174:177], v[216:219], v[32:35]
	v_mfma_f32_16x16x32_bf16 v[28:31], v[160:163], v[224:227], v[28:31]
	v_mfma_f32_16x16x32_bf16 v[16:19], v[174:177], v[224:227], v[16:19]
	v_mfma_f32_16x16x32_bf16 v[12:15], v[160:163], v[232:235], v[12:15]
	v_mfma_f32_16x16x32_bf16 v[0:3], v[174:177], v[232:235], v[0:3]
	v_mfma_f32_16x16x32_bf16 v[56:59], v[178:181], v[204:207], v[56:59]
	v_mfma_f32_16x16x32_bf16 v[52:55], v[196:199], v[204:207], v[52:55]
	v_mfma_f32_16x16x32_bf16 v[40:43], v[178:181], v[212:215], v[40:43]
	v_mfma_f32_16x16x32_bf16 v[36:39], v[196:199], v[212:215], v[36:39]
	v_mfma_f32_16x16x32_bf16 v[24:27], v[178:181], v[220:223], v[24:27]
	v_mfma_f32_16x16x32_bf16 v[20:23], v[196:199], v[220:223], v[20:23]
	v_mfma_f32_16x16x32_bf16 v[8:11], v[178:181], v[228:231], v[8:11]
	v_mfma_f32_16x16x32_bf16 v[4:7], v[196:199], v[228:231], v[4:7]
	v_mfma_f32_16x16x32_bf16 v[56:59], v[192:195], v[208:211], v[56:59]
	v_mfma_f32_16x16x32_bf16 v[52:55], v[200:203], v[208:211], v[52:55]
	v_mfma_f32_16x16x32_bf16 v[40:43], v[192:195], v[216:219], v[40:43]
	v_mfma_f32_16x16x32_bf16 v[36:39], v[200:203], v[216:219], v[36:39]
	v_mfma_f32_16x16x32_bf16 v[24:27], v[192:195], v[224:227], v[24:27]
	v_mfma_f32_16x16x32_bf16 v[20:23], v[200:203], v[224:227], v[20:23]
	v_mfma_f32_16x16x32_bf16 v[8:11], v[192:195], v[232:235], v[8:11]
	v_mfma_f32_16x16x32_bf16 v[4:7], v[200:203], v[232:235], v[4:7]
	s_barrier
	s_add_i32 s13, s13, 2
	s_add_u32 s24, s24, 0x100
	s_addc_u32 s25, s25, 0
	s_add_u32 s11, s11, 0x100
	s_addc_u32 s12, s12, 0
	s_cmp_gt_u32 s13, 29
	s_cbranch_scc0 .LBB0_552
	s_and_b64 vcc, exec, s[52:53]
	s_cbranch_vccz .LBB0_555

; #define PG8_STAGE(bufoff, gbase, voff) do { _Pragma("unroll") for (int _i = 0; _i < 2; ++_i) \
;         __builtin_amdgcn_global_load_lds((const unsigned*)((const char*)(gbase) + (voff)[_i]), (LAS unsigned*)(lds + (bufoff) + ldsw + _i * 8192), 16, 0, 0); } while (0)
; #define PG8_LDA(dst, b, h) do { _Pragma("unroll") for (int m = 0; m < 4; ++m) _Pragma("unroll") for (int k = 0; k < 2; ++k) dst[m][k] = *(const LAS bf16x8*)(lds + PG8_SA(b, h) + aoff + m * 2048 + k * 1024); } while (0)
; #define PG8_LDB(dst, b, h) do { _Pragma("unroll") for (int n = 0; n < 2; ++n) _Pragma("unroll") for (int k = 0; k < 2; ++k) dst[n][k] = *(const LAS bf16x8*)(lds + PG8_SB(b, h) + boff + n * 2048 + k * 1024); } while (0)
; #define PG8_MMA(ai, bj, At, Bt) do { __builtin_amdgcn_s_setprio(1); _Pragma("unroll") for (int m = 0; m < 4; ++m) _Pragma("unroll") for (int n = 0; n < 2; ++n) _Pragma("unroll") for (int k = 0; k < 2; ++k) \
;         acc[ai][bj][m][n] = __builtin_amdgcn_mfma_f32_16x16x32_bf16(Bt[n][k], At[m][k], acc[ai][bj][m][n], 0, 0, 0); __builtin_amdgcn_s_setprio(0); } while (0)
; #define PG8_WAIT_V(n) asm volatile("s_waitcnt vmcnt(" #n ")" ::: "memory")
; #define PG8_WAIT_L(n) asm volatile("s_waitcnt lgkmcnt(" #n ")" ::: "memory")
; #define PG8_BAR __builtin_amdgcn_s_barrier()
; #define PG8_SCHED __builtin_amdgcn_sched_barrier(0)
; template <class Epi, class Map>
; __device__ __forceinline__ void gemm_phase(LAS unsigned char* lds, const Gemm g, const Sched<Map>& S, const Epi& E) {
;     ...
;         for (int t = 0; t < nt; t += 2) {
;             const bool last = (t == nt - 2);
;             const char* a1 = cA + (size_t)(t + 1) * kstep;
;             const char* a2 = last ? nA : cA + (size_t)(t + 2) * kstep; const char* b2 = last ? nB : cB + (size_t)(t + 2) * kstep;
;             const char* a3 = a2 + kstep; const char* b3 = b2 + kstep;
;             PG8_LDB(B0, 0, 0); PG8_LDB(B1, 0, 1); PG8_SCHED; PG8_LDA(At, 0, 0); PG8_STAGE(PG8_SA(1, 1), a1 + hstepA, voffA);
;             PG8_WAIT_V(8); PG8_WAIT_L(0); PG8_BAR; PG8_MMA(0, 0, At, B0); PG8_MMA(0, 1, At, B1); PG8_BAR; PG8_SCHED;
;             PG8_LDA(At, 0, 1); PG8_STAGE(PG8_SB(0, 0), b2, voffB); PG8_STAGE(PG8_SB(0, 1), b2 + hstepB, voffB); PG8_STAGE(PG8_SA(0, 0), a2, voffA);
;             PG8_WAIT_V(8); PG8_WAIT_L(0); PG8_BAR; PG8_MMA(1, 0, At, B0); PG8_MMA(1, 1, At, B1); PG8_BAR; PG8_SCHED;
.LBB0_587:
	s_add_u32 s34, s30, 0xfff80080
	s_addc_u32 s35, s31, -1
	s_add_i32 s39, 0, 0x10000
	s_cmp_eq_u32 s38, 28
	s_cselect_b32 s37, s12, s35
	s_cselect_b32 s36, s13, s34
	v_add_u32_e32 v138, s39, v142
	s_cselect_b32 s35, s14, s33
	s_cselect_b32 s34, s15, s21
	s_add_i32 s46, 0, 0x14000
	ds_read_b128 v[160:163], v138
	ds_read_b128 v[164:167], v138 offset:1024
	ds_read_b128 v[168:171], v138 offset:2048
	ds_read_b128 v[172:175], v138 offset:3072
	v_add_u32_e32 v138, s46, v142
	ds_read_b128 v[176:179], v138
	ds_read_b128 v[192:195], v138 offset:1024
	ds_read_b128 v[196:199], v138 offset:2048
	ds_read_b128 v[200:203], v138 offset:3072
	v_lshl_add_u64 v[138:139], s[30:31], 0, v[134:135]
	s_add_i32 m0, s1, 0xc000
	ds_read_b128 v[204:207], v143
	ds_read_b128 v[208:211], v143 offset:1024
	ds_read_b128 v[212:215], v143 offset:2048
	ds_read_b128 v[216:219], v143 offset:3072
	ds_read_b128 v[220:223], v143 offset:4096
	ds_read_b128 v[224:227], v143 offset:5120
	ds_read_b128 v[228:231], v143 offset:6144
	ds_read_b128 v[232:235], v143 offset:7168
	global_load_lds_dwordx4 v[138:139], off
	v_lshl_add_u64 v[138:139], s[30:31], 0, v[136:137]
	s_add_i32 m0, s1, 0xe000
	s_nop 0
	global_load_lds_dwordx4 v[138:139], off
	s_waitcnt vmcnt(8)
	s_waitcnt lgkmcnt(0)
	s_barrier
	v_mfma_f32_16x16x32_bf16 v[124:127], v[160:163], v[204:207], v[124:127]
	v_mfma_f32_16x16x32_bf16 v[120:123], v[168:171], v[204:207], v[120:123]
	v_mfma_f32_16x16x32_bf16 v[116:119], v[160:163], v[212:215], v[116:119]
	v_mfma_f32_16x16x32_bf16 v[108:111], v[168:171], v[212:215], v[108:111]
	v_mfma_f32_16x16x32_bf16 v[100:103], v[160:163], v[220:223], v[100:103]
	v_mfma_f32_16x16x32_bf16 v[92:95], v[168:171], v[220:223], v[92:95]
	v_mfma_f32_16x16x32_bf16 v[84:87], v[160:163], v[228:231], v[84:87]
	v_mfma_f32_16x16x32_bf16 v[76:79], v[168:171], v[228:231], v[76:79]
	v_mfma_f32_16x16x32_bf16 v[124:127], v[164:167], v[208:211], v[124:127]
	v_mfma_f32_16x16x32_bf16 v[120:123], v[172:175], v[208:211], v[120:123]
	v_mfma_f32_16x16x32_bf16 v[116:119], v[164:167], v[216:219], v[116:119]
	v_mfma_f32_16x16x32_bf16 v[108:111], v[172:175], v[216:219], v[108:111]
	v_mfma_f32_16x16x32_bf16 v[100:103], v[164:167], v[224:227], v[100:103]
	v_mfma_f32_16x16x32_bf16 v[92:95], v[172:175], v[224:227], v[92:95]
	v_mfma_f32_16x16x32_bf16 v[84:87], v[164:167], v[232:235], v[84:87]
	v_mfma_f32_16x16x32_bf16 v[76:79], v[172:175], v[232:235], v[76:79]
	v_mfma_f32_16x16x32_bf16 v[112:115], v[176:179], v[204:207], v[112:115]
	v_mfma_f32_16x16x32_bf16 v[104:107], v[196:199], v[204:207], v[104:107]
	v_mfma_f32_16x16x32_bf16 v[96:99], v[176:179], v[212:215], v[96:99]
	v_mfma_f32_16x16x32_bf16 v[88:91], v[196:199], v[212:215], v[88:91]
	v_mfma_f32_16x16x32_bf16 v[80:83], v[176:179], v[220:223], v[80:83]
	v_mfma_f32_16x16x32_bf16 v[72:75], v[196:199], v[220:223], v[72:75]
	v_mfma_f32_16x16x32_bf16 v[68:71], v[176:179], v[228:231], v[68:71]
	v_mfma_f32_16x16x32_bf16 v[64:67], v[196:199], v[228:231], v[64:67]
	v_mfma_f32_16x16x32_bf16 v[112:115], v[192:195], v[208:211], v[112:115]
	v_mfma_f32_16x16x32_bf16 v[104:107], v[200:203], v[208:211], v[104:107]
	v_mfma_f32_16x16x32_bf16 v[96:99], v[192:195], v[216:219], v[96:99]
	v_mfma_f32_16x16x32_bf16 v[88:91], v[200:203], v[216:219], v[88:91]
	v_mfma_f32_16x16x32_bf16 v[80:83], v[192:195], v[224:227], v[80:83]
	v_mfma_f32_16x16x32_bf16 v[72:75], v[200:203], v[224:227], v[72:75]
	v_mfma_f32_16x16x32_bf16 v[68:71], v[192:195], v[232:235], v[68:71]
	v_mfma_f32_16x16x32_bf16 v[64:67], v[200:203], v[232:235], v[64:67]
	s_barrier
	s_add_i32 s39, s39, s0
	v_lshl_add_u64 v[138:139], s[34:35], 0, v[144:145]
	s_mov_b32 m0, s39
	ds_read_b128 v[204:207], v143 offset:16384
	ds_read_b128 v[208:211], v143 offset:17408
	ds_read_b128 v[212:215], v143 offset:18432
	ds_read_b128 v[216:219], v143 offset:19456
	ds_read_b128 v[220:223], v143 offset:20480
	ds_read_b128 v[224:227], v143 offset:21504
	ds_read_b128 v[228:231], v143 offset:22528
	ds_read_b128 v[232:235], v143 offset:23552
	global_load_lds_dwordx4 v[138:139], off
	s_add_i32 m0, s39, 0x2000
	s_add_u32 s44, s34, 0x80000
	v_lshl_add_u64 v[180:181], s[34:35], 0, v[128:129]
	s_addc_u32 s45, s35, 0
	s_add_i32 s39, s46, s0
	global_load_lds_dwordx4 v[180:181], off
	v_lshl_add_u64 v[236:237], s[44:45], 0, v[144:145]
	s_mov_b32 m0, s39
	v_lshl_add_u64 v[238:239], s[36:37], 0, v[130:131]
	global_load_lds_dwordx4 v[236:237], off
	v_lshl_add_u64 v[236:237], s[44:45], 0, v[128:129]
	s_add_i32 m0, s39, 0x2000
	s_nop 0
	global_load_lds_dwordx4 v[236:237], off
	v_lshl_add_u64 v[236:237], s[36:37], 0, v[132:133]
	s_mov_b32 m0, s1
	s_nop 0
	global_load_lds_dwordx4 v[236:237], off
	s_mov_b32 m0, s2
	s_nop 0
	global_load_lds_dwordx4 v[238:239], off
	s_waitcnt vmcnt(8)
	s_waitcnt lgkmcnt(0)
	s_barrier
; #define PG8_STAGE(bufoff, gbase, voff) do { _Pragma("unroll") for (int _i = 0; _i < 2; ++_i) \
;         __builtin_amdgcn_global_load_lds((const unsigned*)((const char*)(gbase) + (voff)[_i]), (LAS unsigned*)(lds + (bufoff) + ldsw + _i * 8192), 16, 0, 0); } while (0)
; #define PG8_LDA(dst, b, h) do { _Pragma("unroll") for (int m = 0; m < 4; ++m) _Pragma("unroll") for (int k = 0; k < 2; ++k) dst[m][k] = *(const LAS bf16x8*)(lds + PG8_SA(b, h) + aoff + m * 2048 + k * 1024); } while (0)
; #define PG8_LDB(dst, b, h) do { _Pragma("unroll") for (int n = 0; n < 2; ++n) _Pragma("unroll") for (int k = 0; k < 2; ++k) dst[n][k] = *(const LAS bf16x8*)(lds + PG8_SB(b, h) + boff + n * 2048 + k * 1024); } while (0)
; #define PG8_MMA(ai, bj, At, Bt) do { __builtin_amdgcn_s_setprio(1); _Pragma("unroll") for (int m = 0; m < 4; ++m) _Pragma("unroll") for (int n = 0; n < 2; ++n) _Pragma("unroll") for (int k = 0; k < 2; ++k) \
;         acc[ai][bj][m][n] = __builtin_amdgcn_mfma_f32_16x16x32_bf16(Bt[n][k], At[m][k], acc[ai][bj][m][n], 0, 0, 0); __builtin_amdgcn_s_setprio(0); } while (0)
; #define PG8_WAIT_V(n) asm volatile("s_waitcnt vmcnt(" #n ")" ::: "memory")
; #define PG8_WAIT_L(n) asm volatile("s_waitcnt lgkmcnt(" #n ")" ::: "memory")
; #define PG8_BAR __builtin_amdgcn_s_barrier()
; #define PG8_SCHED __builtin_amdgcn_sched_barrier(0)
; template <class Epi, class Map>
; __device__ __forceinline__ void gemm_phase(LAS unsigned char* lds, const Gemm g, const Sched<Map>& S, const Epi& E) {
;     ...
;             PG8_WAIT_V(8); PG8_WAIT_L(0); PG8_BAR; PG8_MMA(1, 0, At, B0); PG8_MMA(1, 1, At, B1); PG8_BAR; PG8_SCHED;
;             PG8_LDB(B0, 1, 0); PG8_LDB(B1, 1, 1); PG8_SCHED; PG8_LDA(At, 1, 0); PG8_STAGE(PG8_SA(0, 1), a2 + hstepA, voffA);
;             PG8_WAIT_V(8); PG8_WAIT_L(0); PG8_BAR; PG8_MMA(0, 0, At, B0); PG8_MMA(0, 1, At, B1); PG8_BAR; PG8_SCHED;
	v_mfma_f32_16x16x32_bf16 v[60:63], v[160:163], v[204:207], v[60:63]
	v_mfma_f32_16x16x32_bf16 v[56:59], v[168:171], v[204:207], v[56:59]
	v_mfma_f32_16x16x32_bf16 v[52:55], v[160:163], v[212:215], v[52:55]
	v_mfma_f32_16x16x32_bf16 v[44:47], v[168:171], v[212:215], v[44:47]
	v_mfma_f32_16x16x32_bf16 v[36:39], v[160:163], v[220:223], v[36:39]
	v_mfma_f32_16x16x32_bf16 v[28:31], v[168:171], v[220:223], v[28:31]
	v_mfma_f32_16x16x32_bf16 v[20:23], v[160:163], v[228:231], v[20:23]
	v_mfma_f32_16x16x32_bf16 v[12:15], v[168:171], v[228:231], v[12:15]
	v_mfma_f32_16x16x32_bf16 v[60:63], v[164:167], v[208:211], v[60:63]
	v_mfma_f32_16x16x32_bf16 v[56:59], v[172:175], v[208:211], v[56:59]
	v_mfma_f32_16x16x32_bf16 v[52:55], v[164:167], v[216:219], v[52:55]
	v_mfma_f32_16x16x32_bf16 v[44:47], v[172:175], v[216:219], v[44:47]
	v_mfma_f32_16x16x32_bf16 v[36:39], v[164:167], v[224:227], v[36:39]
	v_mfma_f32_16x16x32_bf16 v[28:31], v[172:175], v[224:227], v[28:31]
	v_mfma_f32_16x16x32_bf16 v[20:23], v[164:167], v[232:235], v[20:23]
	v_mfma_f32_16x16x32_bf16 v[12:15], v[172:175], v[232:235], v[12:15]
	v_mfma_f32_16x16x32_bf16 v[48:51], v[176:179], v[204:207], v[48:51]
	v_mfma_f32_16x16x32_bf16 v[40:43], v[196:199], v[204:207], v[40:43]
	v_mfma_f32_16x16x32_bf16 v[32:35], v[176:179], v[212:215], v[32:35]
	v_mfma_f32_16x16x32_bf16 v[24:27], v[196:199], v[212:215], v[24:27]
	v_mfma_f32_16x16x32_bf16 v[16:19], v[176:179], v[220:223], v[16:19]
	v_mfma_f32_16x16x32_bf16 v[8:11], v[196:199], v[220:223], v[8:11]
	v_mfma_f32_16x16x32_bf16 v[4:7], v[176:179], v[228:231], v[4:7]
	v_mfma_f32_16x16x32_bf16 v[0:3], v[196:199], v[228:231], v[0:3]
	v_mfma_f32_16x16x32_bf16 v[48:51], v[192:195], v[208:211], v[48:51]
	v_mfma_f32_16x16x32_bf16 v[40:43], v[200:203], v[208:211], v[40:43]
	v_mfma_f32_16x16x32_bf16 v[32:35], v[192:195], v[216:219], v[32:35]
	v_mfma_f32_16x16x32_bf16 v[24:27], v[200:203], v[216:219], v[24:27]
	v_mfma_f32_16x16x32_bf16 v[16:19], v[192:195], v[224:227], v[16:19]
	v_mfma_f32_16x16x32_bf16 v[8:11], v[200:203], v[224:227], v[8:11]
	v_mfma_f32_16x16x32_bf16 v[4:7], v[192:195], v[232:235], v[4:7]
	v_mfma_f32_16x16x32_bf16 v[0:3], v[200:203], v[232:235], v[0:3]
	s_barrier
	s_add_i32 s39, 0, 0x18000
	s_add_i32 s44, 0, 0x1c000
	v_add_u32_e32 v172, s39, v142
	v_add_u32_e32 v200, s44, v142
	ds_read_b128 v[160:163], v172
	ds_read_b128 v[164:167], v172 offset:1024
	ds_read_b128 v[168:171], v172 offset:2048
	ds_read_b128 v[172:175], v172 offset:3072
	ds_read_b128 v[176:179], v200
	ds_read_b128 v[192:195], v200 offset:1024
	ds_read_b128 v[196:199], v200 offset:2048
	ds_read_b128 v[200:203], v200 offset:3072
	s_add_u32 s36, s36, 0x80000
	s_addc_u32 s37, s37, 0
	s_mov_b32 m0, s3
	v_lshl_add_u64 v[240:241], s[36:37], 0, v[132:133]
	ds_read_b128 v[204:207], v143 offset:32768
	ds_read_b128 v[208:211], v143 offset:33792
	ds_read_b128 v[212:215], v143 offset:34816
	ds_read_b128 v[216:219], v143 offset:35840
	ds_read_b128 v[220:223], v143 offset:36864
	ds_read_b128 v[224:227], v143 offset:37888
	ds_read_b128 v[228:231], v143 offset:38912
	ds_read_b128 v[232:235], v143 offset:39936
	global_load_lds_dwordx4 v[240:241], off
	v_lshl_add_u64 v[240:241], s[36:37], 0, v[130:131]
	s_mov_b32 m0, s4
	s_nop 0
	global_load_lds_dwordx4 v[240:241], off
	s_waitcnt vmcnt(8)
	s_waitcnt lgkmcnt(0)
	s_barrier
	v_mfma_f32_16x16x32_bf16 v[124:127], v[160:163], v[204:207], v[124:127]
	v_mfma_f32_16x16x32_bf16 v[120:123], v[168:171], v[204:207], v[120:123]
	v_mfma_f32_16x16x32_bf16 v[116:119], v[160:163], v[212:215], v[116:119]
	v_mfma_f32_16x16x32_bf16 v[108:111], v[168:171], v[212:215], v[108:111]
	v_mfma_f32_16x16x32_bf16 v[100:103], v[160:163], v[220:223], v[100:103]
	v_mfma_f32_16x16x32_bf16 v[92:95], v[168:171], v[220:223], v[92:95]
	v_mfma_f32_16x16x32_bf16 v[84:87], v[160:163], v[228:231], v[84:87]
	v_mfma_f32_16x16x32_bf16 v[76:79], v[168:171], v[228:231], v[76:79]
	v_mfma_f32_16x16x32_bf16 v[124:127], v[164:167], v[208:211], v[124:127]
	v_mfma_f32_16x16x32_bf16 v[120:123], v[172:175], v[208:211], v[120:123]
	v_mfma_f32_16x16x32_bf16 v[116:119], v[164:167], v[216:219], v[116:119]
	v_mfma_f32_16x16x32_bf16 v[108:111], v[172:175], v[216:219], v[108:111]
	v_mfma_f32_16x16x32_bf16 v[100:103], v[164:167], v[224:227], v[100:103]
	v_mfma_f32_16x16x32_bf16 v[92:95], v[172:175], v[224:227], v[92:95]
	v_mfma_f32_16x16x32_bf16 v[84:87], v[164:167], v[232:235], v[84:87]
	v_mfma_f32_16x16x32_bf16 v[76:79], v[172:175], v[232:235], v[76:79]
	v_mfma_f32_16x16x32_bf16 v[112:115], v[176:179], v[204:207], v[112:115]
	v_mfma_f32_16x16x32_bf16 v[104:107], v[196:199], v[204:207], v[104:107]
	v_mfma_f32_16x16x32_bf16 v[96:99], v[176:179], v[212:215], v[96:99]
	v_mfma_f32_16x16x32_bf16 v[88:91], v[196:199], v[212:215], v[88:91]
	v_mfma_f32_16x16x32_bf16 v[80:83], v[176:179], v[220:223], v[80:83]
	v_mfma_f32_16x16x32_bf16 v[72:75], v[196:199], v[220:223], v[72:75]
	v_mfma_f32_16x16x32_bf16 v[68:71], v[176:179], v[228:231], v[68:71]
	v_mfma_f32_16x16x32_bf16 v[64:67], v[196:199], v[228:231], v[64:67]
	v_mfma_f32_16x16x32_bf16 v[112:115], v[192:195], v[208:211], v[112:115]
	v_mfma_f32_16x16x32_bf16 v[104:107], v[200:203], v[208:211], v[104:107]
	v_mfma_f32_16x16x32_bf16 v[96:99], v[192:195], v[216:219], v[96:99]
	v_mfma_f32_16x16x32_bf16 v[88:91], v[200:203], v[216:219], v[88:91]
	v_mfma_f32_16x16x32_bf16 v[80:83], v[192:195], v[224:227], v[80:83]
	v_mfma_f32_16x16x32_bf16 v[72:75], v[200:203], v[224:227], v[72:75]
	v_mfma_f32_16x16x32_bf16 v[68:71], v[192:195], v[232:235], v[68:71]
	v_mfma_f32_16x16x32_bf16 v[64:67], v[200:203], v[232:235], v[64:67]
	s_barrier
; #define PG8_STAGE(bufoff, gbase, voff) do { _Pragma("unroll") for (int _i = 0; _i < 2; ++_i) \
;         __builtin_amdgcn_global_load_lds((const unsigned*)((const char*)(gbase) + (voff)[_i]), (LAS unsigned*)(lds + (bufoff) + ldsw + _i * 8192), 16, 0, 0); } while (0)
; #define PG8_LDA(dst, b, h) do { _Pragma("unroll") for (int m = 0; m < 4; ++m) _Pragma("unroll") for (int k = 0; k < 2; ++k) dst[m][k] = *(const LAS bf16x8*)(lds + PG8_SA(b, h) + aoff + m * 2048 + k * 1024); } while (0)
; #define PG8_MMA(ai, bj, At, Bt) do { __builtin_amdgcn_s_setprio(1); _Pragma("unroll") for (int m = 0; m < 4; ++m) _Pragma("unroll") for (int n = 0; n < 2; ++n) _Pragma("unroll") for (int k = 0; k < 2; ++k) \
;         acc[ai][bj][m][n] = __builtin_amdgcn_mfma_f32_16x16x32_bf16(Bt[n][k], At[m][k], acc[ai][bj][m][n], 0, 0, 0); __builtin_amdgcn_s_setprio(0); } while (0)
; #define PG8_WAIT_V(n) asm volatile("s_waitcnt vmcnt(" #n ")" ::: "memory")
; #define PG8_WAIT_L(n) asm volatile("s_waitcnt lgkmcnt(" #n ")" ::: "memory")
; #define PG8_BAR __builtin_amdgcn_s_barrier()
; #define PG8_SCHED __builtin_amdgcn_sched_barrier(0)
; template <class Epi, class Map>
; __device__ __forceinline__ void gemm_phase(LAS unsigned char* lds, const Gemm g, const Sched<Map>& S, const Epi& E) {
;     ...
;             PG8_LDA(At, 1, 1); PG8_STAGE(PG8_SB(1, 0), b3, voffB); PG8_STAGE(PG8_SB(1, 1), b3 + hstepB, voffB); PG8_STAGE(PG8_SA(1, 0), a3, voffA);
;             PG8_WAIT_V(8); PG8_WAIT_L(0); PG8_BAR; PG8_MMA(1, 0, At, B0); PG8_MMA(1, 1, At, B1); PG8_BAR; PG8_SCHED;
;         }
	s_add_i32 s36, s39, s0
	v_lshl_add_u64 v[138:139], v[138:139], 0, s[82:83]
	s_mov_b32 m0, s36
	ds_read_b128 v[204:207], v143 offset:49152
	ds_read_b128 v[208:211], v143 offset:50176
	ds_read_b128 v[212:215], v143 offset:51200
	ds_read_b128 v[216:219], v143 offset:52224
	ds_read_b128 v[220:223], v143 offset:53248
	ds_read_b128 v[224:227], v143 offset:54272
	ds_read_b128 v[228:231], v143 offset:55296
	ds_read_b128 v[232:235], v143 offset:56320
	global_load_lds_dwordx4 v[138:139], off
	s_add_i32 m0, s36, 0x2000
	s_add_u32 s34, s34, 0x80080
	v_lshl_add_u64 v[138:139], v[180:181], 0, s[82:83]
	s_addc_u32 s35, s35, 0
	s_add_i32 s36, s44, s0
	global_load_lds_dwordx4 v[138:139], off
	v_lshl_add_u64 v[138:139], s[34:35], 0, v[144:145]
	s_mov_b32 m0, s36
	s_nop 0
	global_load_lds_dwordx4 v[138:139], off
	v_lshl_add_u64 v[138:139], s[34:35], 0, v[128:129]
	s_add_i32 m0, s36, 0x2000
	s_nop 0
	global_load_lds_dwordx4 v[138:139], off
	v_lshl_add_u64 v[138:139], v[236:237], 0, s[82:83]
	s_mov_b32 m0, s6
	s_nop 0
	global_load_lds_dwordx4 v[138:139], off
	v_lshl_add_u64 v[138:139], v[238:239], 0, s[82:83]
	s_mov_b32 m0, s7
	s_nop 0
	global_load_lds_dwordx4 v[138:139], off
	s_waitcnt vmcnt(8)
	s_waitcnt lgkmcnt(0)
	s_barrier
	v_mfma_f32_16x16x32_bf16 v[60:63], v[160:163], v[204:207], v[60:63]
	v_mfma_f32_16x16x32_bf16 v[56:59], v[168:171], v[204:207], v[56:59]
	v_mfma_f32_16x16x32_bf16 v[52:55], v[160:163], v[212:215], v[52:55]
	v_mfma_f32_16x16x32_bf16 v[44:47], v[168:171], v[212:215], v[44:47]
	v_mfma_f32_16x16x32_bf16 v[36:39], v[160:163], v[220:223], v[36:39]
	v_mfma_f32_16x16x32_bf16 v[28:31], v[168:171], v[220:223], v[28:31]
	v_mfma_f32_16x16x32_bf16 v[20:23], v[160:163], v[228:231], v[20:23]
	v_mfma_f32_16x16x32_bf16 v[12:15], v[168:171], v[228:231], v[12:15]
	v_mfma_f32_16x16x32_bf16 v[60:63], v[164:167], v[208:211], v[60:63]
	v_mfma_f32_16x16x32_bf16 v[56:59], v[172:175], v[208:211], v[56:59]
	v_mfma_f32_16x16x32_bf16 v[52:55], v[164:167], v[216:219], v[52:55]
	v_mfma_f32_16x16x32_bf16 v[44:47], v[172:175], v[216:219], v[44:47]
	v_mfma_f32_16x16x32_bf16 v[36:39], v[164:167], v[224:227], v[36:39]
	v_mfma_f32_16x16x32_bf16 v[28:31], v[172:175], v[224:227], v[28:31]
	v_mfma_f32_16x16x32_bf16 v[20:23], v[164:167], v[232:235], v[20:23]
	v_mfma_f32_16x16x32_bf16 v[12:15], v[172:175], v[232:235], v[12:15]
	v_mfma_f32_16x16x32_bf16 v[48:51], v[176:179], v[204:207], v[48:51]
	v_mfma_f32_16x16x32_bf16 v[40:43], v[196:199], v[204:207], v[40:43]
	v_mfma_f32_16x16x32_bf16 v[32:35], v[176:179], v[212:215], v[32:35]
	v_mfma_f32_16x16x32_bf16 v[24:27], v[196:199], v[212:215], v[24:27]
	v_mfma_f32_16x16x32_bf16 v[16:19], v[176:179], v[220:223], v[16:19]
	v_mfma_f32_16x16x32_bf16 v[8:11], v[196:199], v[220:223], v[8:11]
	v_mfma_f32_16x16x32_bf16 v[4:7], v[176:179], v[228:231], v[4:7]
	v_mfma_f32_16x16x32_bf16 v[0:3], v[196:199], v[228:231], v[0:3]
	v_mfma_f32_16x16x32_bf16 v[48:51], v[192:195], v[208:211], v[48:51]
	v_mfma_f32_16x16x32_bf16 v[40:43], v[200:203], v[208:211], v[40:43]
	v_mfma_f32_16x16x32_bf16 v[32:35], v[192:195], v[216:219], v[32:35]
	v_mfma_f32_16x16x32_bf16 v[24:27], v[200:203], v[216:219], v[24:27]
	v_mfma_f32_16x16x32_bf16 v[16:19], v[192:195], v[224:227], v[16:19]
	v_mfma_f32_16x16x32_bf16 v[8:11], v[200:203], v[224:227], v[8:11]
	v_mfma_f32_16x16x32_bf16 v[4:7], v[192:195], v[232:235], v[4:7]
	v_mfma_f32_16x16x32_bf16 v[0:3], v[200:203], v[232:235], v[0:3]
	s_barrier
	s_add_i32 s38, s38, 2
	s_add_u32 s30, s30, 0x100
	s_addc_u32 s31, s31, 0
	s_add_u32 s21, s21, 0x100
	s_addc_u32 s33, s33, 0
	s_cmp_gt_u32 s38, 29
	s_cbranch_scc0 .LBB0_587
	s_and_b64 vcc, exec, s[18:19]
	s_cbranch_vccz .LBB0_590

; #define PG8_STAGE(bufoff, gbase, voff) do { _Pragma("unroll") for (int _i = 0; _i < 2; ++_i) \
;         __builtin_amdgcn_global_load_lds((const unsigned*)((const char*)(gbase) + (voff)[_i]), (LAS unsigned*)(lds + (bufoff) + ldsw + _i * 8192), 16, 0, 0); } while (0)
; #define PG8_LDA(dst, b, h) do { _Pragma("unroll") for (int m = 0; m < 4; ++m) _Pragma("unroll") for (int k = 0; k < 2; ++k) dst[m][k] = *(const LAS bf16x8*)(lds + PG8_SA(b, h) + aoff + m * 2048 + k * 1024); } while (0)
; #define PG8_LDB(dst, b, h) do { _Pragma("unroll") for (int n = 0; n < 2; ++n) _Pragma("unroll") for (int k = 0; k < 2; ++k) dst[n][k] = *(const LAS bf16x8*)(lds + PG8_SB(b, h) + boff + n * 2048 + k * 1024); } while (0)
; #define PG8_MMA(ai, bj, At, Bt) do { __builtin_amdgcn_s_setprio(1); _Pragma("unroll") for (int m = 0; m < 4; ++m) _Pragma("unroll") for (int n = 0; n < 2; ++n) _Pragma("unroll") for (int k = 0; k < 2; ++k) \
;         acc[ai][bj][m][n] = __builtin_amdgcn_mfma_f32_16x16x32_bf16(Bt[n][k], At[m][k], acc[ai][bj][m][n], 0, 0, 0); __builtin_amdgcn_s_setprio(0); } while (0)
; #define PG8_WAIT_V(n) asm volatile("s_waitcnt vmcnt(" #n ")" ::: "memory")
; #define PG8_WAIT_L(n) asm volatile("s_waitcnt lgkmcnt(" #n ")" ::: "memory")
; #define PG8_BAR __builtin_amdgcn_s_barrier()
; #define PG8_SCHED __builtin_amdgcn_sched_barrier(0)
; template <class Epi, class Map>
; __device__ __forceinline__ void gemm_phase(LAS unsigned char* lds, const Gemm g, const Sched<Map>& S, const Epi& E) {
;     ...
;         for (int t = 0; t < nt; t += 2) {
;             const bool last = (t == nt - 2);
;             const char* a1 = cA + (size_t)(t + 1) * kstep;
;             const char* a2 = last ? nA : cA + (size_t)(t + 2) * kstep; const char* b2 = last ? nB : cB + (size_t)(t + 2) * kstep;
;             const char* a3 = a2 + kstep; const char* b3 = b2 + kstep;
;             PG8_LDB(B0, 0, 0); PG8_LDB(B1, 0, 1); PG8_SCHED; PG8_LDA(At, 0, 0); PG8_STAGE(PG8_SA(1, 1), a1 + hstepA, voffA);
;             PG8_WAIT_V(8); PG8_WAIT_L(0); PG8_BAR; PG8_MMA(0, 0, At, B0); PG8_MMA(0, 1, At, B1); PG8_BAR; PG8_SCHED;
;             PG8_LDA(At, 0, 1); PG8_STAGE(PG8_SB(0, 0), b2, voffB); PG8_STAGE(PG8_SB(0, 1), b2 + hstepB, voffB); PG8_STAGE(PG8_SA(0, 0), a2, voffA);
;             PG8_WAIT_V(8); PG8_WAIT_L(0); PG8_BAR; PG8_MMA(1, 0, At, B0); PG8_MMA(1, 1, At, B1); PG8_BAR; PG8_SCHED;
.LBB0_659:
	s_add_u32 s50, s30, s44
	s_addc_u32 s51, s31, s45
	s_add_u32 s48, s50, 0x100
	s_addc_u32 s49, s51, 0
	s_and_b64 s[46:47], s[36:37], exec
	s_cselect_b32 s47, s15, s49
	s_cselect_b32 s46, s33, s48
	s_add_u32 s44, s28, s44
	s_addc_u32 s45, s29, s45
	s_add_u32 s44, s44, 0x100
	s_addc_u32 s45, s45, 0
	s_add_i32 s62, 0, 0x10000
	s_and_b64 s[36:37], s[36:37], exec
	s_cselect_b32 s49, s38, s45
	s_cselect_b32 s48, s39, s44
	s_add_i32 s37, 0, 0x14000
	s_add_u32 s52, s50, 0x20080
	s_addc_u32 s53, s51, 0
	s_add_i32 s66, s62, s0
	s_add_i32 m0, s1, 0xc000
	s_add_i32 s63, s1, 0xe000
	s_add_i32 s58, s66, 0x2000
	v_add_u32_e32 v142, s62, v140
	s_add_u32 s50, s48, 0x10000
	ds_read_b128 v[134:137], v142
	ds_read_b128 v[160:163], v142 offset:1024
	ds_read_b128 v[164:167], v142 offset:2048
	ds_read_b128 v[168:171], v142 offset:3072
	v_add_u32_e32 v142, s37, v140
	s_addc_u32 s51, s49, 0
	s_add_i32 s65, s37, s0
	ds_read_b128 v[172:175], v142
	ds_read_b128 v[176:179], v142 offset:1024
	ds_read_b128 v[192:195], v142 offset:2048
	ds_read_b128 v[196:199], v142 offset:3072
	s_add_i32 s59, s65, 0x2000
	s_add_i32 s57, 0, 0x18000
	s_add_i32 s56, 0, 0x1c000
	s_add_u32 s44, s46, 0x20000
	s_addc_u32 s45, s47, 0
	s_add_i32 s55, s57, s0
	s_add_i32 s54, s55, 0x2000
	s_add_u32 s36, s48, 0x10080
	s_addc_u32 s37, s49, 0
	s_add_i32 s68, s56, s0
	s_add_i32 s67, s68, 0x2000
	v_lshl_add_u64 v[142:143], s[52:53], 0, v[132:133]
	ds_read_b128 v[200:203], v141
	ds_read_b128 v[204:207], v141 offset:1024
	ds_read_b128 v[208:211], v141 offset:2048
	ds_read_b128 v[212:215], v141 offset:3072
	ds_read_b128 v[216:219], v141 offset:4096
	ds_read_b128 v[220:223], v141 offset:5120
	ds_read_b128 v[224:227], v141 offset:6144
	ds_read_b128 v[228:231], v141 offset:7168
	global_load_lds_dwordx4 v[142:143], off
	v_lshl_add_u64 v[142:143], s[52:53], 0, v[130:131]
	s_mov_b32 m0, s63
	s_nop 0
	global_load_lds_dwordx4 v[142:143], off
	s_waitcnt vmcnt(8)
	s_waitcnt lgkmcnt(0)
	s_barrier
	v_mfma_f32_16x16x32_bf16 v[124:127], v[134:137], v[200:203], v[124:127]
	v_mfma_f32_16x16x32_bf16 v[120:123], v[164:167], v[200:203], v[120:123]
	v_mfma_f32_16x16x32_bf16 v[116:119], v[134:137], v[208:211], v[116:119]
	v_mfma_f32_16x16x32_bf16 v[112:115], v[164:167], v[208:211], v[112:115]
	v_mfma_f32_16x16x32_bf16 v[108:111], v[134:137], v[216:219], v[108:111]
	v_mfma_f32_16x16x32_bf16 v[104:107], v[164:167], v[216:219], v[104:107]
	v_mfma_f32_16x16x32_bf16 v[100:103], v[134:137], v[224:227], v[100:103]
	v_mfma_f32_16x16x32_bf16 v[96:99], v[164:167], v[224:227], v[96:99]
	v_mfma_f32_16x16x32_bf16 v[124:127], v[160:163], v[204:207], v[124:127]
	v_mfma_f32_16x16x32_bf16 v[120:123], v[168:171], v[204:207], v[120:123]
	v_mfma_f32_16x16x32_bf16 v[116:119], v[160:163], v[212:215], v[116:119]
	v_mfma_f32_16x16x32_bf16 v[112:115], v[168:171], v[212:215], v[112:115]
	v_mfma_f32_16x16x32_bf16 v[108:111], v[160:163], v[220:223], v[108:111]
	v_mfma_f32_16x16x32_bf16 v[104:107], v[168:171], v[220:223], v[104:107]
	v_mfma_f32_16x16x32_bf16 v[100:103], v[160:163], v[228:231], v[100:103]
	v_mfma_f32_16x16x32_bf16 v[96:99], v[168:171], v[228:231], v[96:99]
	v_mfma_f32_16x16x32_bf16 v[60:63], v[172:175], v[200:203], v[60:63]
	v_mfma_f32_16x16x32_bf16 v[56:59], v[192:195], v[200:203], v[56:59]
	v_mfma_f32_16x16x32_bf16 v[52:55], v[172:175], v[208:211], v[52:55]
	v_mfma_f32_16x16x32_bf16 v[48:51], v[192:195], v[208:211], v[48:51]
	v_mfma_f32_16x16x32_bf16 v[44:47], v[172:175], v[216:219], v[44:47]
	v_mfma_f32_16x16x32_bf16 v[40:43], v[192:195], v[216:219], v[40:43]
	v_mfma_f32_16x16x32_bf16 v[36:39], v[172:175], v[224:227], v[36:39]
	v_mfma_f32_16x16x32_bf16 v[32:35], v[192:195], v[224:227], v[32:35]
	v_mfma_f32_16x16x32_bf16 v[60:63], v[176:179], v[204:207], v[60:63]
	v_mfma_f32_16x16x32_bf16 v[56:59], v[196:199], v[204:207], v[56:59]
	v_mfma_f32_16x16x32_bf16 v[52:55], v[176:179], v[212:215], v[52:55]
	v_mfma_f32_16x16x32_bf16 v[48:51], v[196:199], v[212:215], v[48:51]
	v_mfma_f32_16x16x32_bf16 v[44:47], v[176:179], v[220:223], v[44:47]
	v_mfma_f32_16x16x32_bf16 v[40:43], v[196:199], v[220:223], v[40:43]
	v_mfma_f32_16x16x32_bf16 v[36:39], v[176:179], v[228:231], v[36:39]
	v_mfma_f32_16x16x32_bf16 v[32:35], v[196:199], v[228:231], v[32:35]
	s_barrier
	s_mov_b32 m0, s66
	v_lshl_add_u64 v[142:143], s[48:49], 0, v[144:145]
	ds_read_b128 v[200:203], v141 offset:16384
	ds_read_b128 v[204:207], v141 offset:17408
	ds_read_b128 v[208:211], v141 offset:18432
	ds_read_b128 v[212:215], v141 offset:19456
	ds_read_b128 v[216:219], v141 offset:20480
	ds_read_b128 v[220:223], v141 offset:21504
	ds_read_b128 v[224:227], v141 offset:22528
	ds_read_b128 v[228:231], v141 offset:23552
	global_load_lds_dwordx4 v[142:143], off
	v_lshl_add_u64 v[180:181], s[48:49], 0, v[128:129]
	s_mov_b32 m0, s58
	v_lshl_add_u64 v[232:233], s[50:51], 0, v[144:145]
	global_load_lds_dwordx4 v[180:181], off
	s_mov_b32 m0, s65
	v_lshl_add_u64 v[234:235], s[46:47], 0, v[130:131]
	global_load_lds_dwordx4 v[232:233], off
	v_lshl_add_u64 v[232:233], s[50:51], 0, v[128:129]
	s_mov_b32 m0, s59
	s_nop 0
	global_load_lds_dwordx4 v[232:233], off
	v_lshl_add_u64 v[232:233], s[46:47], 0, v[132:133]
	s_mov_b32 m0, s1
	s_nop 0
	global_load_lds_dwordx4 v[232:233], off
	s_mov_b32 m0, s2
	s_nop 0
	global_load_lds_dwordx4 v[234:235], off
	s_waitcnt vmcnt(8)
	s_waitcnt lgkmcnt(0)
	s_barrier
; #define PG8_STAGE(bufoff, gbase, voff) do { _Pragma("unroll") for (int _i = 0; _i < 2; ++_i) \
;         __builtin_amdgcn_global_load_lds((const unsigned*)((const char*)(gbase) + (voff)[_i]), (LAS unsigned*)(lds + (bufoff) + ldsw + _i * 8192), 16, 0, 0); } while (0)
; #define PG8_LDA(dst, b, h) do { _Pragma("unroll") for (int m = 0; m < 4; ++m) _Pragma("unroll") for (int k = 0; k < 2; ++k) dst[m][k] = *(const LAS bf16x8*)(lds + PG8_SA(b, h) + aoff + m * 2048 + k * 1024); } while (0)
; #define PG8_LDB(dst, b, h) do { _Pragma("unroll") for (int n = 0; n < 2; ++n) _Pragma("unroll") for (int k = 0; k < 2; ++k) dst[n][k] = *(const LAS bf16x8*)(lds + PG8_SB(b, h) + boff + n * 2048 + k * 1024); } while (0)
; #define PG8_MMA(ai, bj, At, Bt) do { __builtin_amdgcn_s_setprio(1); _Pragma("unroll") for (int m = 0; m < 4; ++m) _Pragma("unroll") for (int n = 0; n < 2; ++n) _Pragma("unroll") for (int k = 0; k < 2; ++k) \
;         acc[ai][bj][m][n] = __builtin_amdgcn_mfma_f32_16x16x32_bf16(Bt[n][k], At[m][k], acc[ai][bj][m][n], 0, 0, 0); __builtin_amdgcn_s_setprio(0); } while (0)
; #define PG8_WAIT_V(n) asm volatile("s_waitcnt vmcnt(" #n ")" ::: "memory")
; #define PG8_WAIT_L(n) asm volatile("s_waitcnt lgkmcnt(" #n ")" ::: "memory")
; #define PG8_BAR __builtin_amdgcn_s_barrier()
; #define PG8_SCHED __builtin_amdgcn_sched_barrier(0)
; template <class Epi, class Map>
; __device__ __forceinline__ void gemm_phase(LAS unsigned char* lds, const Gemm g, const Sched<Map>& S, const Epi& E) {
;     ...
;             PG8_WAIT_V(8); PG8_WAIT_L(0); PG8_BAR; PG8_MMA(1, 0, At, B0); PG8_MMA(1, 1, At, B1); PG8_BAR; PG8_SCHED;
;             PG8_LDB(B0, 1, 0); PG8_LDB(B1, 1, 1); PG8_SCHED; PG8_LDA(At, 1, 0); PG8_STAGE(PG8_SA(0, 1), a2 + hstepA, voffA);
;             PG8_WAIT_V(8); PG8_WAIT_L(0); PG8_BAR; PG8_MMA(0, 0, At, B0); PG8_MMA(0, 1, At, B1); PG8_BAR; PG8_SCHED;
	v_mfma_f32_16x16x32_bf16 v[92:95], v[134:137], v[200:203], v[92:95]
	v_mfma_f32_16x16x32_bf16 v[88:91], v[164:167], v[200:203], v[88:91]
	v_mfma_f32_16x16x32_bf16 v[84:87], v[134:137], v[208:211], v[84:87]
	v_mfma_f32_16x16x32_bf16 v[80:83], v[164:167], v[208:211], v[80:83]
	v_mfma_f32_16x16x32_bf16 v[76:79], v[134:137], v[216:219], v[76:79]
	v_mfma_f32_16x16x32_bf16 v[72:75], v[164:167], v[216:219], v[72:75]
	v_mfma_f32_16x16x32_bf16 v[68:71], v[134:137], v[224:227], v[68:71]
	v_mfma_f32_16x16x32_bf16 v[64:67], v[164:167], v[224:227], v[64:67]
	v_mfma_f32_16x16x32_bf16 v[92:95], v[160:163], v[204:207], v[92:95]
	v_mfma_f32_16x16x32_bf16 v[88:91], v[168:171], v[204:207], v[88:91]
	v_mfma_f32_16x16x32_bf16 v[84:87], v[160:163], v[212:215], v[84:87]
	v_mfma_f32_16x16x32_bf16 v[80:83], v[168:171], v[212:215], v[80:83]
	v_mfma_f32_16x16x32_bf16 v[76:79], v[160:163], v[220:223], v[76:79]
	v_mfma_f32_16x16x32_bf16 v[72:75], v[168:171], v[220:223], v[72:75]
	v_mfma_f32_16x16x32_bf16 v[68:71], v[160:163], v[228:231], v[68:71]
	v_mfma_f32_16x16x32_bf16 v[64:67], v[168:171], v[228:231], v[64:67]
	v_mfma_f32_16x16x32_bf16 v[28:31], v[172:175], v[200:203], v[28:31]
	v_mfma_f32_16x16x32_bf16 v[24:27], v[192:195], v[200:203], v[24:27]
	v_mfma_f32_16x16x32_bf16 v[20:23], v[172:175], v[208:211], v[20:23]
	v_mfma_f32_16x16x32_bf16 v[16:19], v[192:195], v[208:211], v[16:19]
	v_mfma_f32_16x16x32_bf16 v[12:15], v[172:175], v[216:219], v[12:15]
	v_mfma_f32_16x16x32_bf16 v[8:11], v[192:195], v[216:219], v[8:11]
	v_mfma_f32_16x16x32_bf16 v[4:7], v[172:175], v[224:227], v[4:7]
	v_mfma_f32_16x16x32_bf16 v[0:3], v[192:195], v[224:227], v[0:3]
	v_mfma_f32_16x16x32_bf16 v[28:31], v[176:179], v[204:207], v[28:31]
	v_mfma_f32_16x16x32_bf16 v[24:27], v[196:199], v[204:207], v[24:27]
	v_mfma_f32_16x16x32_bf16 v[20:23], v[176:179], v[212:215], v[20:23]
	v_mfma_f32_16x16x32_bf16 v[16:19], v[196:199], v[212:215], v[16:19]
	v_mfma_f32_16x16x32_bf16 v[12:15], v[176:179], v[220:223], v[12:15]
	v_mfma_f32_16x16x32_bf16 v[8:11], v[196:199], v[220:223], v[8:11]
	v_mfma_f32_16x16x32_bf16 v[4:7], v[176:179], v[228:231], v[4:7]
	v_mfma_f32_16x16x32_bf16 v[0:3], v[196:199], v[228:231], v[0:3]
	s_barrier
	v_add_u32_e32 v168, s57, v140
	v_add_u32_e32 v196, s56, v140
	ds_read_b128 v[134:137], v168
	ds_read_b128 v[160:163], v168 offset:1024
	ds_read_b128 v[164:167], v168 offset:2048
	ds_read_b128 v[168:171], v168 offset:3072
	ds_read_b128 v[172:175], v196
	ds_read_b128 v[176:179], v196 offset:1024
	ds_read_b128 v[192:195], v196 offset:2048
	ds_read_b128 v[196:199], v196 offset:3072
	s_mov_b32 m0, s3
	v_lshl_add_u64 v[236:237], s[44:45], 0, v[132:133]
	ds_read_b128 v[200:203], v141 offset:32768
	ds_read_b128 v[204:207], v141 offset:33792
	ds_read_b128 v[208:211], v141 offset:34816
	ds_read_b128 v[212:215], v141 offset:35840
	ds_read_b128 v[216:219], v141 offset:36864
	ds_read_b128 v[220:223], v141 offset:37888
	ds_read_b128 v[224:227], v141 offset:38912
	ds_read_b128 v[228:231], v141 offset:39936
	global_load_lds_dwordx4 v[236:237], off
	v_lshl_add_u64 v[236:237], s[44:45], 0, v[130:131]
	s_mov_b32 m0, s4
	s_nop 0
	global_load_lds_dwordx4 v[236:237], off
	s_waitcnt vmcnt(8)
	s_waitcnt lgkmcnt(0)
	s_barrier
	v_mfma_f32_16x16x32_bf16 v[124:127], v[134:137], v[200:203], v[124:127]
	v_mfma_f32_16x16x32_bf16 v[120:123], v[164:167], v[200:203], v[120:123]
	v_mfma_f32_16x16x32_bf16 v[116:119], v[134:137], v[208:211], v[116:119]
	v_mfma_f32_16x16x32_bf16 v[112:115], v[164:167], v[208:211], v[112:115]
	v_mfma_f32_16x16x32_bf16 v[108:111], v[134:137], v[216:219], v[108:111]
	v_mfma_f32_16x16x32_bf16 v[104:107], v[164:167], v[216:219], v[104:107]
	v_mfma_f32_16x16x32_bf16 v[100:103], v[134:137], v[224:227], v[100:103]
	v_mfma_f32_16x16x32_bf16 v[96:99], v[164:167], v[224:227], v[96:99]
	v_mfma_f32_16x16x32_bf16 v[124:127], v[160:163], v[204:207], v[124:127]
	v_mfma_f32_16x16x32_bf16 v[120:123], v[168:171], v[204:207], v[120:123]
	v_mfma_f32_16x16x32_bf16 v[116:119], v[160:163], v[212:215], v[116:119]
	v_mfma_f32_16x16x32_bf16 v[112:115], v[168:171], v[212:215], v[112:115]
	v_mfma_f32_16x16x32_bf16 v[108:111], v[160:163], v[220:223], v[108:111]
	v_mfma_f32_16x16x32_bf16 v[104:107], v[168:171], v[220:223], v[104:107]
	v_mfma_f32_16x16x32_bf16 v[100:103], v[160:163], v[228:231], v[100:103]
	v_mfma_f32_16x16x32_bf16 v[96:99], v[168:171], v[228:231], v[96:99]
	v_mfma_f32_16x16x32_bf16 v[60:63], v[172:175], v[200:203], v[60:63]
	v_mfma_f32_16x16x32_bf16 v[56:59], v[192:195], v[200:203], v[56:59]
	v_mfma_f32_16x16x32_bf16 v[52:55], v[172:175], v[208:211], v[52:55]
	v_mfma_f32_16x16x32_bf16 v[48:51], v[192:195], v[208:211], v[48:51]
	v_mfma_f32_16x16x32_bf16 v[44:47], v[172:175], v[216:219], v[44:47]
	v_mfma_f32_16x16x32_bf16 v[40:43], v[192:195], v[216:219], v[40:43]
	v_mfma_f32_16x16x32_bf16 v[36:39], v[172:175], v[224:227], v[36:39]
	v_mfma_f32_16x16x32_bf16 v[32:35], v[192:195], v[224:227], v[32:35]
	v_mfma_f32_16x16x32_bf16 v[60:63], v[176:179], v[204:207], v[60:63]
	v_mfma_f32_16x16x32_bf16 v[56:59], v[196:199], v[204:207], v[56:59]
	v_mfma_f32_16x16x32_bf16 v[52:55], v[176:179], v[212:215], v[52:55]
	v_mfma_f32_16x16x32_bf16 v[48:51], v[196:199], v[212:215], v[48:51]
	v_mfma_f32_16x16x32_bf16 v[44:47], v[176:179], v[220:223], v[44:47]
	v_mfma_f32_16x16x32_bf16 v[40:43], v[196:199], v[220:223], v[40:43]
	v_mfma_f32_16x16x32_bf16 v[36:39], v[176:179], v[228:231], v[36:39]
	v_mfma_f32_16x16x32_bf16 v[32:35], v[196:199], v[228:231], v[32:35]
	s_barrier
; #define PG8_STAGE(bufoff, gbase, voff) do { _Pragma("unroll") for (int _i = 0; _i < 2; ++_i) \
;         __builtin_amdgcn_global_load_lds((const unsigned*)((const char*)(gbase) + (voff)[_i]), (LAS unsigned*)(lds + (bufoff) + ldsw + _i * 8192), 16, 0, 0); } while (0)
; #define PG8_LDA(dst, b, h) do { _Pragma("unroll") for (int m = 0; m < 4; ++m) _Pragma("unroll") for (int k = 0; k < 2; ++k) dst[m][k] = *(const LAS bf16x8*)(lds + PG8_SA(b, h) + aoff + m * 2048 + k * 1024); } while (0)
; #define PG8_MMA(ai, bj, At, Bt) do { __builtin_amdgcn_s_setprio(1); _Pragma("unroll") for (int m = 0; m < 4; ++m) _Pragma("unroll") for (int n = 0; n < 2; ++n) _Pragma("unroll") for (int k = 0; k < 2; ++k) \
;         acc[ai][bj][m][n] = __builtin_amdgcn_mfma_f32_16x16x32_bf16(Bt[n][k], At[m][k], acc[ai][bj][m][n], 0, 0, 0); __builtin_amdgcn_s_setprio(0); } while (0)
; #define PG8_WAIT_V(n) asm volatile("s_waitcnt vmcnt(" #n ")" ::: "memory")
; #define PG8_WAIT_L(n) asm volatile("s_waitcnt lgkmcnt(" #n ")" ::: "memory")
; #define PG8_BAR __builtin_amdgcn_s_barrier()
; #define PG8_SCHED __builtin_amdgcn_sched_barrier(0)
; template <class Epi, class Map>
; __device__ __forceinline__ void gemm_phase(LAS unsigned char* lds, const Gemm g, const Sched<Map>& S, const Epi& E) {
;     ...
;             PG8_LDA(At, 1, 1); PG8_STAGE(PG8_SB(1, 0), b3, voffB); PG8_STAGE(PG8_SB(1, 1), b3 + hstepB, voffB); PG8_STAGE(PG8_SA(1, 0), a3, voffA);
;             PG8_WAIT_V(8); PG8_WAIT_L(0); PG8_BAR; PG8_MMA(1, 0, At, B0); PG8_MMA(1, 1, At, B1); PG8_BAR; PG8_SCHED;
;         }
	s_mov_b32 m0, s55
	v_lshl_add_u64 v[142:143], v[142:143], 0, s[82:83]
	ds_read_b128 v[200:203], v141 offset:49152
	ds_read_b128 v[204:207], v141 offset:50176
	ds_read_b128 v[208:211], v141 offset:51200
	ds_read_b128 v[212:215], v141 offset:52224
	ds_read_b128 v[216:219], v141 offset:53248
	ds_read_b128 v[220:223], v141 offset:54272
	ds_read_b128 v[224:227], v141 offset:55296
	ds_read_b128 v[228:231], v141 offset:56320
	global_load_lds_dwordx4 v[142:143], off
	v_lshl_add_u64 v[142:143], v[180:181], 0, s[82:83]
	s_mov_b32 m0, s54
	s_nop 0
	global_load_lds_dwordx4 v[142:143], off
	v_lshl_add_u64 v[142:143], s[36:37], 0, v[144:145]
	s_mov_b32 m0, s68
	s_nop 0
	global_load_lds_dwordx4 v[142:143], off
	v_lshl_add_u64 v[142:143], s[36:37], 0, v[128:129]
	s_mov_b32 m0, s67
	s_nop 0
	global_load_lds_dwordx4 v[142:143], off
	v_lshl_add_u64 v[142:143], v[232:233], 0, s[82:83]
	s_mov_b32 m0, s7
	s_nop 0
	global_load_lds_dwordx4 v[142:143], off
	v_lshl_add_u64 v[142:143], v[234:235], 0, s[82:83]
	s_mov_b32 m0, s8
	s_nop 0
	global_load_lds_dwordx4 v[142:143], off
	s_waitcnt vmcnt(8)
	s_waitcnt lgkmcnt(0)
	s_barrier
	v_mfma_f32_16x16x32_bf16 v[92:95], v[134:137], v[200:203], v[92:95]
	v_mfma_f32_16x16x32_bf16 v[88:91], v[164:167], v[200:203], v[88:91]
	v_mfma_f32_16x16x32_bf16 v[84:87], v[134:137], v[208:211], v[84:87]
	v_mfma_f32_16x16x32_bf16 v[80:83], v[164:167], v[208:211], v[80:83]
	v_mfma_f32_16x16x32_bf16 v[76:79], v[134:137], v[216:219], v[76:79]
	v_mfma_f32_16x16x32_bf16 v[72:75], v[164:167], v[216:219], v[72:75]
	v_mfma_f32_16x16x32_bf16 v[68:71], v[134:137], v[224:227], v[68:71]
	v_mfma_f32_16x16x32_bf16 v[64:67], v[164:167], v[224:227], v[64:67]
	v_mfma_f32_16x16x32_bf16 v[92:95], v[160:163], v[204:207], v[92:95]
	v_mfma_f32_16x16x32_bf16 v[88:91], v[168:171], v[204:207], v[88:91]
	v_mfma_f32_16x16x32_bf16 v[84:87], v[160:163], v[212:215], v[84:87]
	v_mfma_f32_16x16x32_bf16 v[80:83], v[168:171], v[212:215], v[80:83]
	v_mfma_f32_16x16x32_bf16 v[76:79], v[160:163], v[220:223], v[76:79]
	v_mfma_f32_16x16x32_bf16 v[72:75], v[168:171], v[220:223], v[72:75]
	v_mfma_f32_16x16x32_bf16 v[68:71], v[160:163], v[228:231], v[68:71]
	v_mfma_f32_16x16x32_bf16 v[64:67], v[168:171], v[228:231], v[64:67]
	v_mfma_f32_16x16x32_bf16 v[28:31], v[172:175], v[200:203], v[28:31]
	v_mfma_f32_16x16x32_bf16 v[24:27], v[192:195], v[200:203], v[24:27]
	v_mfma_f32_16x16x32_bf16 v[20:23], v[172:175], v[208:211], v[20:23]
	v_mfma_f32_16x16x32_bf16 v[16:19], v[192:195], v[208:211], v[16:19]
	v_mfma_f32_16x16x32_bf16 v[12:15], v[172:175], v[216:219], v[12:15]
	v_mfma_f32_16x16x32_bf16 v[8:11], v[192:195], v[216:219], v[8:11]
	v_mfma_f32_16x16x32_bf16 v[4:7], v[172:175], v[224:227], v[4:7]
	v_mfma_f32_16x16x32_bf16 v[0:3], v[192:195], v[224:227], v[0:3]
	v_mfma_f32_16x16x32_bf16 v[28:31], v[176:179], v[204:207], v[28:31]
	v_mfma_f32_16x16x32_bf16 v[24:27], v[196:199], v[204:207], v[24:27]
	v_mfma_f32_16x16x32_bf16 v[20:23], v[176:179], v[212:215], v[20:23]
	v_mfma_f32_16x16x32_bf16 v[16:19], v[196:199], v[212:215], v[16:19]
	v_mfma_f32_16x16x32_bf16 v[12:15], v[176:179], v[220:223], v[12:15]
	v_mfma_f32_16x16x32_bf16 v[8:11], v[196:199], v[220:223], v[8:11]
	v_mfma_f32_16x16x32_bf16 v[4:7], v[176:179], v[228:231], v[4:7]
	v_mfma_f32_16x16x32_bf16 v[0:3], v[196:199], v[228:231], v[0:3]
	s_barrier
	s_andn2_b64 vcc, exec, s[34:35]
	s_mov_b64 s[36:37], -1
	s_mov_b64 s[34:35], 0
	s_mov_b64 s[44:45], 0x100
	s_cbranch_vccz .LBB0_659
	s_and_b64 vcc, exec, s[18:19]
	s_cbranch_vccz .LBB0_662

; #define PG8_STAGE(bufoff, gbase, voff) do { _Pragma("unroll") for (int _i = 0; _i < 2; ++_i) \
;         __builtin_amdgcn_global_load_lds((const unsigned*)((const char*)(gbase) + (voff)[_i]), (LAS unsigned*)(lds + (bufoff) + ldsw + _i * 8192), 16, 0, 0); } while (0)
; #define PG8_LDA(dst, b, h) do { _Pragma("unroll") for (int m = 0; m < 4; ++m) _Pragma("unroll") for (int k = 0; k < 2; ++k) dst[m][k] = *(const LAS bf16x8*)(lds + PG8_SA(b, h) + aoff + m * 2048 + k * 1024); } while (0)
; #define PG8_LDB(dst, b, h) do { _Pragma("unroll") for (int n = 0; n < 2; ++n) _Pragma("unroll") for (int k = 0; k < 2; ++k) dst[n][k] = *(const LAS bf16x8*)(lds + PG8_SB(b, h) + boff + n * 2048 + k * 1024); } while (0)
; #define PG8_MMA(ai, bj, At, Bt) do { __builtin_amdgcn_s_setprio(1); _Pragma("unroll") for (int m = 0; m < 4; ++m) _Pragma("unroll") for (int n = 0; n < 2; ++n) _Pragma("unroll") for (int k = 0; k < 2; ++k) \
;         acc[ai][bj][m][n] = __builtin_amdgcn_mfma_f32_16x16x32_bf16(Bt[n][k], At[m][k], acc[ai][bj][m][n], 0, 0, 0); __builtin_amdgcn_s_setprio(0); } while (0)
; #define PG8_WAIT_V(n) asm volatile("s_waitcnt vmcnt(" #n ")" ::: "memory")
; #define PG8_WAIT_L(n) asm volatile("s_waitcnt lgkmcnt(" #n ")" ::: "memory")
; #define PG8_BAR __builtin_amdgcn_s_barrier()
; #define PG8_SCHED __builtin_amdgcn_sched_barrier(0)
; template <class Epi, class Map>
; __device__ __forceinline__ void gemm_phase(LAS unsigned char* lds, const Gemm g, const Sched<Map>& S, const Epi& E) {
;     ...
;         for (int t = 0; t < nt; t += 2) {
;             const bool last = (t == nt - 2);
;             const char* a1 = cA + (size_t)(t + 1) * kstep;
;             const char* a2 = last ? nA : cA + (size_t)(t + 2) * kstep; const char* b2 = last ? nB : cB + (size_t)(t + 2) * kstep;
;             const char* a3 = a2 + kstep; const char* b3 = b2 + kstep;
;             PG8_LDB(B0, 0, 0); PG8_LDB(B1, 0, 1); PG8_SCHED; PG8_LDA(At, 0, 0); PG8_STAGE(PG8_SA(1, 1), a1 + hstepA, voffA);
;             PG8_WAIT_V(8); PG8_WAIT_L(0); PG8_BAR; PG8_MMA(0, 0, At, B0); PG8_MMA(0, 1, At, B1); PG8_BAR; PG8_SCHED;
;             PG8_LDA(At, 0, 1); PG8_STAGE(PG8_SB(0, 0), b2, voffB); PG8_STAGE(PG8_SB(0, 1), b2 + hstepB, voffB); PG8_STAGE(PG8_SA(0, 0), a2, voffA);
;             PG8_WAIT_V(8); PG8_WAIT_L(0); PG8_BAR; PG8_MMA(1, 0, At, B0); PG8_MMA(1, 1, At, B1); PG8_BAR; PG8_SCHED;
.LBB0_679:
	s_add_u32 s21, s34, s46
	s_addc_u32 s33, s35, s47
	s_add_u32 s48, s21, 0x100
	s_addc_u32 s49, s33, 0
	s_and_b64 s[38:39], s[44:45], exec
	s_cselect_b32 s49, s12, s49
	s_cselect_b32 s48, s13, s48
	s_add_u32 s38, s30, s46
	s_addc_u32 s39, s31, s47
	s_add_u32 s46, s38, 0x100
	s_addc_u32 s47, s39, 0
	s_add_i32 s62, 0, 0x10000
	s_and_b64 s[38:39], s[44:45], exec
	s_cselect_b32 s51, s14, s47
	s_cselect_b32 s50, s15, s46
	s_add_i32 s45, 0, 0x14000
	s_add_u32 s54, s21, 0x20080
	s_addc_u32 s55, s33, 0
	s_add_i32 s59, s62, s0
	s_add_i32 m0, s1, 0xc000
	s_add_i32 s63, s1, 0xe000
	s_add_i32 s56, s59, 0x2000
	v_add_u32_e32 v134, s62, v138
	s_add_u32 s52, s50, 0x10000
	ds_read_b128 v[140:143], v134
	ds_read_b128 v[160:163], v134 offset:1024
	ds_read_b128 v[164:167], v134 offset:2048
	ds_read_b128 v[168:171], v134 offset:3072
	v_add_u32_e32 v134, s45, v138
	s_addc_u32 s53, s51, 0
	s_add_i32 s58, s45, s0
	ds_read_b128 v[172:175], v134
	ds_read_b128 v[176:179], v134 offset:1024
	ds_read_b128 v[192:195], v134 offset:2048
	ds_read_b128 v[196:199], v134 offset:3072
	s_add_i32 s57, s58, 0x2000
	s_add_i32 s39, 0, 0x18000
	s_add_i32 s38, 0, 0x1c000
	s_add_u32 s46, s48, 0x20000
	s_addc_u32 s47, s49, 0
	s_add_i32 s33, s39, s0
	s_add_i32 s21, s33, 0x2000
	s_add_u32 s44, s50, 0x10080
	s_addc_u32 s45, s51, 0
	s_add_i32 s66, s38, s0
	s_add_i32 s65, s66, 0x2000
	v_lshl_add_u64 v[134:135], s[54:55], 0, v[132:133]
	ds_read_b128 v[200:203], v139
	ds_read_b128 v[204:207], v139 offset:1024
	ds_read_b128 v[208:211], v139 offset:2048
	ds_read_b128 v[212:215], v139 offset:3072
	ds_read_b128 v[216:219], v139 offset:4096
	ds_read_b128 v[220:223], v139 offset:5120
	ds_read_b128 v[224:227], v139 offset:6144
	ds_read_b128 v[228:231], v139 offset:7168
	global_load_lds_dwordx4 v[134:135], off
	v_lshl_add_u64 v[134:135], s[54:55], 0, v[130:131]
	s_mov_b32 m0, s63
	s_nop 0
	global_load_lds_dwordx4 v[134:135], off
	s_waitcnt vmcnt(8)
	s_waitcnt lgkmcnt(0)
	s_barrier
	v_mfma_f32_16x16x32_bf16 v[124:127], v[140:143], v[200:203], v[124:127]
	v_mfma_f32_16x16x32_bf16 v[120:123], v[164:167], v[200:203], v[120:123]
	v_mfma_f32_16x16x32_bf16 v[116:119], v[140:143], v[208:211], v[116:119]
	v_mfma_f32_16x16x32_bf16 v[108:111], v[164:167], v[208:211], v[108:111]
	v_mfma_f32_16x16x32_bf16 v[100:103], v[140:143], v[216:219], v[100:103]
	v_mfma_f32_16x16x32_bf16 v[92:95], v[164:167], v[216:219], v[92:95]
	v_mfma_f32_16x16x32_bf16 v[84:87], v[140:143], v[224:227], v[84:87]
	v_mfma_f32_16x16x32_bf16 v[76:79], v[164:167], v[224:227], v[76:79]
	v_mfma_f32_16x16x32_bf16 v[124:127], v[160:163], v[204:207], v[124:127]
	v_mfma_f32_16x16x32_bf16 v[120:123], v[168:171], v[204:207], v[120:123]
	v_mfma_f32_16x16x32_bf16 v[116:119], v[160:163], v[212:215], v[116:119]
	v_mfma_f32_16x16x32_bf16 v[108:111], v[168:171], v[212:215], v[108:111]
	v_mfma_f32_16x16x32_bf16 v[100:103], v[160:163], v[220:223], v[100:103]
	v_mfma_f32_16x16x32_bf16 v[92:95], v[168:171], v[220:223], v[92:95]
	v_mfma_f32_16x16x32_bf16 v[84:87], v[160:163], v[228:231], v[84:87]
	v_mfma_f32_16x16x32_bf16 v[76:79], v[168:171], v[228:231], v[76:79]
	v_mfma_f32_16x16x32_bf16 v[112:115], v[172:175], v[200:203], v[112:115]
	v_mfma_f32_16x16x32_bf16 v[104:107], v[192:195], v[200:203], v[104:107]
	v_mfma_f32_16x16x32_bf16 v[96:99], v[172:175], v[208:211], v[96:99]
	v_mfma_f32_16x16x32_bf16 v[88:91], v[192:195], v[208:211], v[88:91]
	v_mfma_f32_16x16x32_bf16 v[80:83], v[172:175], v[216:219], v[80:83]
	v_mfma_f32_16x16x32_bf16 v[72:75], v[192:195], v[216:219], v[72:75]
	v_mfma_f32_16x16x32_bf16 v[68:71], v[172:175], v[224:227], v[68:71]
	v_mfma_f32_16x16x32_bf16 v[64:67], v[192:195], v[224:227], v[64:67]
	v_mfma_f32_16x16x32_bf16 v[112:115], v[176:179], v[204:207], v[112:115]
	v_mfma_f32_16x16x32_bf16 v[104:107], v[196:199], v[204:207], v[104:107]
	v_mfma_f32_16x16x32_bf16 v[96:99], v[176:179], v[212:215], v[96:99]
	v_mfma_f32_16x16x32_bf16 v[88:91], v[196:199], v[212:215], v[88:91]
	v_mfma_f32_16x16x32_bf16 v[80:83], v[176:179], v[220:223], v[80:83]
	v_mfma_f32_16x16x32_bf16 v[72:75], v[196:199], v[220:223], v[72:75]
	v_mfma_f32_16x16x32_bf16 v[68:71], v[176:179], v[228:231], v[68:71]
	v_mfma_f32_16x16x32_bf16 v[64:67], v[196:199], v[228:231], v[64:67]
	s_barrier
	s_mov_b32 m0, s59
	v_lshl_add_u64 v[134:135], s[50:51], 0, v[144:145]
	ds_read_b128 v[200:203], v139 offset:16384
	ds_read_b128 v[204:207], v139 offset:17408
	ds_read_b128 v[208:211], v139 offset:18432
	ds_read_b128 v[212:215], v139 offset:19456
	ds_read_b128 v[216:219], v139 offset:20480
	ds_read_b128 v[220:223], v139 offset:21504
	ds_read_b128 v[224:227], v139 offset:22528
	ds_read_b128 v[228:231], v139 offset:23552
	global_load_lds_dwordx4 v[134:135], off
	v_lshl_add_u64 v[180:181], s[50:51], 0, v[128:129]
	s_mov_b32 m0, s56
	v_lshl_add_u64 v[232:233], s[52:53], 0, v[144:145]
	global_load_lds_dwordx4 v[180:181], off
	s_mov_b32 m0, s58
	v_lshl_add_u64 v[234:235], s[48:49], 0, v[130:131]
	global_load_lds_dwordx4 v[232:233], off
	v_lshl_add_u64 v[232:233], s[52:53], 0, v[128:129]
	s_mov_b32 m0, s57
	s_nop 0
	global_load_lds_dwordx4 v[232:233], off
	v_lshl_add_u64 v[232:233], s[48:49], 0, v[132:133]
	s_mov_b32 m0, s1
	s_nop 0
	global_load_lds_dwordx4 v[232:233], off
	s_mov_b32 m0, s2
	s_nop 0
	global_load_lds_dwordx4 v[234:235], off
	s_waitcnt vmcnt(8)
	s_waitcnt lgkmcnt(0)
	s_barrier
; #define PG8_STAGE(bufoff, gbase, voff) do { _Pragma("unroll") for (int _i = 0; _i < 2; ++_i) \
;         __builtin_amdgcn_global_load_lds((const unsigned*)((const char*)(gbase) + (voff)[_i]), (LAS unsigned*)(lds + (bufoff) + ldsw + _i * 8192), 16, 0, 0); } while (0)
; #define PG8_LDA(dst, b, h) do { _Pragma("unroll") for (int m = 0; m < 4; ++m) _Pragma("unroll") for (int k = 0; k < 2; ++k) dst[m][k] = *(const LAS bf16x8*)(lds + PG8_SA(b, h) + aoff + m * 2048 + k * 1024); } while (0)
; #define PG8_LDB(dst, b, h) do { _Pragma("unroll") for (int n = 0; n < 2; ++n) _Pragma("unroll") for (int k = 0; k < 2; ++k) dst[n][k] = *(const LAS bf16x8*)(lds + PG8_SB(b, h) + boff + n * 2048 + k * 1024); } while (0)
; #define PG8_MMA(ai, bj, At, Bt) do { __builtin_amdgcn_s_setprio(1); _Pragma("unroll") for (int m = 0; m < 4; ++m) _Pragma("unroll") for (int n = 0; n < 2; ++n) _Pragma("unroll") for (int k = 0; k < 2; ++k) \
;         acc[ai][bj][m][n] = __builtin_amdgcn_mfma_f32_16x16x32_bf16(Bt[n][k], At[m][k], acc[ai][bj][m][n], 0, 0, 0); __builtin_amdgcn_s_setprio(0); } while (0)
; #define PG8_WAIT_V(n) asm volatile("s_waitcnt vmcnt(" #n ")" ::: "memory")
; #define PG8_WAIT_L(n) asm volatile("s_waitcnt lgkmcnt(" #n ")" ::: "memory")
; #define PG8_BAR __builtin_amdgcn_s_barrier()
; #define PG8_SCHED __builtin_amdgcn_sched_barrier(0)
; template <class Epi, class Map>
; __device__ __forceinline__ void gemm_phase(LAS unsigned char* lds, const Gemm g, const Sched<Map>& S, const Epi& E) {
;     ...
;             PG8_WAIT_V(8); PG8_WAIT_L(0); PG8_BAR; PG8_MMA(1, 0, At, B0); PG8_MMA(1, 1, At, B1); PG8_BAR; PG8_SCHED;
;             PG8_LDB(B0, 1, 0); PG8_LDB(B1, 1, 1); PG8_SCHED; PG8_LDA(At, 1, 0); PG8_STAGE(PG8_SA(0, 1), a2 + hstepA, voffA);
;             PG8_WAIT_V(8); PG8_WAIT_L(0); PG8_BAR; PG8_MMA(0, 0, At, B0); PG8_MMA(0, 1, At, B1); PG8_BAR; PG8_SCHED;
	v_mfma_f32_16x16x32_bf16 v[60:63], v[140:143], v[200:203], v[60:63]
	v_mfma_f32_16x16x32_bf16 v[56:59], v[164:167], v[200:203], v[56:59]
	v_mfma_f32_16x16x32_bf16 v[52:55], v[140:143], v[208:211], v[52:55]
	v_mfma_f32_16x16x32_bf16 v[44:47], v[164:167], v[208:211], v[44:47]
	v_mfma_f32_16x16x32_bf16 v[36:39], v[140:143], v[216:219], v[36:39]
	v_mfma_f32_16x16x32_bf16 v[28:31], v[164:167], v[216:219], v[28:31]
	v_mfma_f32_16x16x32_bf16 v[20:23], v[140:143], v[224:227], v[20:23]
	v_mfma_f32_16x16x32_bf16 v[12:15], v[164:167], v[224:227], v[12:15]
	v_mfma_f32_16x16x32_bf16 v[60:63], v[160:163], v[204:207], v[60:63]
	v_mfma_f32_16x16x32_bf16 v[56:59], v[168:171], v[204:207], v[56:59]
	v_mfma_f32_16x16x32_bf16 v[52:55], v[160:163], v[212:215], v[52:55]
	v_mfma_f32_16x16x32_bf16 v[44:47], v[168:171], v[212:215], v[44:47]
	v_mfma_f32_16x16x32_bf16 v[36:39], v[160:163], v[220:223], v[36:39]
	v_mfma_f32_16x16x32_bf16 v[28:31], v[168:171], v[220:223], v[28:31]
	v_mfma_f32_16x16x32_bf16 v[20:23], v[160:163], v[228:231], v[20:23]
	v_mfma_f32_16x16x32_bf16 v[12:15], v[168:171], v[228:231], v[12:15]
	v_mfma_f32_16x16x32_bf16 v[48:51], v[172:175], v[200:203], v[48:51]
	v_mfma_f32_16x16x32_bf16 v[40:43], v[192:195], v[200:203], v[40:43]
	v_mfma_f32_16x16x32_bf16 v[32:35], v[172:175], v[208:211], v[32:35]
	v_mfma_f32_16x16x32_bf16 v[24:27], v[192:195], v[208:211], v[24:27]
	v_mfma_f32_16x16x32_bf16 v[16:19], v[172:175], v[216:219], v[16:19]
	v_mfma_f32_16x16x32_bf16 v[8:11], v[192:195], v[216:219], v[8:11]
	v_mfma_f32_16x16x32_bf16 v[4:7], v[172:175], v[224:227], v[4:7]
	v_mfma_f32_16x16x32_bf16 v[0:3], v[192:195], v[224:227], v[0:3]
	v_mfma_f32_16x16x32_bf16 v[48:51], v[176:179], v[204:207], v[48:51]
	v_mfma_f32_16x16x32_bf16 v[40:43], v[196:199], v[204:207], v[40:43]
	v_mfma_f32_16x16x32_bf16 v[32:35], v[176:179], v[212:215], v[32:35]
	v_mfma_f32_16x16x32_bf16 v[24:27], v[196:199], v[212:215], v[24:27]
	v_mfma_f32_16x16x32_bf16 v[16:19], v[176:179], v[220:223], v[16:19]
	v_mfma_f32_16x16x32_bf16 v[8:11], v[196:199], v[220:223], v[8:11]
	v_mfma_f32_16x16x32_bf16 v[4:7], v[176:179], v[228:231], v[4:7]
	v_mfma_f32_16x16x32_bf16 v[0:3], v[196:199], v[228:231], v[0:3]
	s_barrier
	v_add_u32_e32 v168, s39, v138
	v_add_u32_e32 v196, s38, v138
	ds_read_b128 v[140:143], v168
	ds_read_b128 v[160:163], v168 offset:1024
	ds_read_b128 v[164:167], v168 offset:2048
	ds_read_b128 v[168:171], v168 offset:3072
	ds_read_b128 v[172:175], v196
	ds_read_b128 v[176:179], v196 offset:1024
	ds_read_b128 v[192:195], v196 offset:2048
	ds_read_b128 v[196:199], v196 offset:3072
	s_mov_b32 m0, s3
	v_lshl_add_u64 v[236:237], s[46:47], 0, v[132:133]
	ds_read_b128 v[200:203], v139 offset:32768
	ds_read_b128 v[204:207], v139 offset:33792
	ds_read_b128 v[208:211], v139 offset:34816
	ds_read_b128 v[212:215], v139 offset:35840
	ds_read_b128 v[216:219], v139 offset:36864
	ds_read_b128 v[220:223], v139 offset:37888
	ds_read_b128 v[224:227], v139 offset:38912
	ds_read_b128 v[228:231], v139 offset:39936
	global_load_lds_dwordx4 v[236:237], off
	v_lshl_add_u64 v[236:237], s[46:47], 0, v[130:131]
	s_mov_b32 m0, s4
	s_nop 0
	global_load_lds_dwordx4 v[236:237], off
	s_waitcnt vmcnt(8)
	s_waitcnt lgkmcnt(0)
	s_barrier
	v_mfma_f32_16x16x32_bf16 v[124:127], v[140:143], v[200:203], v[124:127]
	v_mfma_f32_16x16x32_bf16 v[120:123], v[164:167], v[200:203], v[120:123]
	v_mfma_f32_16x16x32_bf16 v[116:119], v[140:143], v[208:211], v[116:119]
	v_mfma_f32_16x16x32_bf16 v[108:111], v[164:167], v[208:211], v[108:111]
	v_mfma_f32_16x16x32_bf16 v[100:103], v[140:143], v[216:219], v[100:103]
	v_mfma_f32_16x16x32_bf16 v[92:95], v[164:167], v[216:219], v[92:95]
	v_mfma_f32_16x16x32_bf16 v[84:87], v[140:143], v[224:227], v[84:87]
	v_mfma_f32_16x16x32_bf16 v[76:79], v[164:167], v[224:227], v[76:79]
	v_mfma_f32_16x16x32_bf16 v[124:127], v[160:163], v[204:207], v[124:127]
	v_mfma_f32_16x16x32_bf16 v[120:123], v[168:171], v[204:207], v[120:123]
	v_mfma_f32_16x16x32_bf16 v[116:119], v[160:163], v[212:215], v[116:119]
	v_mfma_f32_16x16x32_bf16 v[108:111], v[168:171], v[212:215], v[108:111]
	v_mfma_f32_16x16x32_bf16 v[100:103], v[160:163], v[220:223], v[100:103]
	v_mfma_f32_16x16x32_bf16 v[92:95], v[168:171], v[220:223], v[92:95]
	v_mfma_f32_16x16x32_bf16 v[84:87], v[160:163], v[228:231], v[84:87]
	v_mfma_f32_16x16x32_bf16 v[76:79], v[168:171], v[228:231], v[76:79]
	v_mfma_f32_16x16x32_bf16 v[112:115], v[172:175], v[200:203], v[112:115]
	v_mfma_f32_16x16x32_bf16 v[104:107], v[192:195], v[200:203], v[104:107]
	v_mfma_f32_16x16x32_bf16 v[96:99], v[172:175], v[208:211], v[96:99]
	v_mfma_f32_16x16x32_bf16 v[88:91], v[192:195], v[208:211], v[88:91]
	v_mfma_f32_16x16x32_bf16 v[80:83], v[172:175], v[216:219], v[80:83]
	v_mfma_f32_16x16x32_bf16 v[72:75], v[192:195], v[216:219], v[72:75]
	v_mfma_f32_16x16x32_bf16 v[68:71], v[172:175], v[224:227], v[68:71]
	v_mfma_f32_16x16x32_bf16 v[64:67], v[192:195], v[224:227], v[64:67]
	v_mfma_f32_16x16x32_bf16 v[112:115], v[176:179], v[204:207], v[112:115]
	v_mfma_f32_16x16x32_bf16 v[104:107], v[196:199], v[204:207], v[104:107]
	v_mfma_f32_16x16x32_bf16 v[96:99], v[176:179], v[212:215], v[96:99]
	v_mfma_f32_16x16x32_bf16 v[88:91], v[196:199], v[212:215], v[88:91]
	v_mfma_f32_16x16x32_bf16 v[80:83], v[176:179], v[220:223], v[80:83]
	v_mfma_f32_16x16x32_bf16 v[72:75], v[196:199], v[220:223], v[72:75]
	v_mfma_f32_16x16x32_bf16 v[68:71], v[176:179], v[228:231], v[68:71]
	v_mfma_f32_16x16x32_bf16 v[64:67], v[196:199], v[228:231], v[64:67]
	s_barrier
; #define PG8_STAGE(bufoff, gbase, voff) do { _Pragma("unroll") for (int _i = 0; _i < 2; ++_i) \
;         __builtin_amdgcn_global_load_lds((const unsigned*)((const char*)(gbase) + (voff)[_i]), (LAS unsigned*)(lds + (bufoff) + ldsw + _i * 8192), 16, 0, 0); } while (0)
; #define PG8_LDA(dst, b, h) do { _Pragma("unroll") for (int m = 0; m < 4; ++m) _Pragma("unroll") for (int k = 0; k < 2; ++k) dst[m][k] = *(const LAS bf16x8*)(lds + PG8_SA(b, h) + aoff + m * 2048 + k * 1024); } while (0)
; #define PG8_MMA(ai, bj, At, Bt) do { __builtin_amdgcn_s_setprio(1); _Pragma("unroll") for (int m = 0; m < 4; ++m) _Pragma("unroll") for (int n = 0; n < 2; ++n) _Pragma("unroll") for (int k = 0; k < 2; ++k) \
;         acc[ai][bj][m][n] = __builtin_amdgcn_mfma_f32_16x16x32_bf16(Bt[n][k], At[m][k], acc[ai][bj][m][n], 0, 0, 0); __builtin_amdgcn_s_setprio(0); } while (0)
; #define PG8_WAIT_V(n) asm volatile("s_waitcnt vmcnt(" #n ")" ::: "memory")
; #define PG8_WAIT_L(n) asm volatile("s_waitcnt lgkmcnt(" #n ")" ::: "memory")
; #define PG8_BAR __builtin_amdgcn_s_barrier()
; #define PG8_SCHED __builtin_amdgcn_sched_barrier(0)
; template <class Epi, class Map>
; __device__ __forceinline__ void gemm_phase(LAS unsigned char* lds, const Gemm g, const Sched<Map>& S, const Epi& E) {
;     ...
;             PG8_LDA(At, 1, 1); PG8_STAGE(PG8_SB(1, 0), b3, voffB); PG8_STAGE(PG8_SB(1, 1), b3 + hstepB, voffB); PG8_STAGE(PG8_SA(1, 0), a3, voffA);
;             PG8_WAIT_V(8); PG8_WAIT_L(0); PG8_BAR; PG8_MMA(1, 0, At, B0); PG8_MMA(1, 1, At, B1); PG8_BAR; PG8_SCHED;
;         }
	s_mov_b32 m0, s33
	v_lshl_add_u64 v[134:135], v[134:135], 0, s[82:83]
	ds_read_b128 v[200:203], v139 offset:49152
	ds_read_b128 v[204:207], v139 offset:50176
	ds_read_b128 v[208:211], v139 offset:51200
	ds_read_b128 v[212:215], v139 offset:52224
	ds_read_b128 v[216:219], v139 offset:53248
	ds_read_b128 v[220:223], v139 offset:54272
	ds_read_b128 v[224:227], v139 offset:55296
	ds_read_b128 v[228:231], v139 offset:56320
	global_load_lds_dwordx4 v[134:135], off
	v_lshl_add_u64 v[134:135], v[180:181], 0, s[82:83]
	s_mov_b32 m0, s21
	s_nop 0
	global_load_lds_dwordx4 v[134:135], off
	v_lshl_add_u64 v[134:135], s[44:45], 0, v[144:145]
	s_mov_b32 m0, s66
	s_nop 0
	global_load_lds_dwordx4 v[134:135], off
	v_lshl_add_u64 v[134:135], s[44:45], 0, v[128:129]
	s_mov_b32 m0, s65
	s_nop 0
	global_load_lds_dwordx4 v[134:135], off
	v_lshl_add_u64 v[134:135], v[232:233], 0, s[82:83]
	s_mov_b32 m0, s6
	s_nop 0
	global_load_lds_dwordx4 v[134:135], off
	v_lshl_add_u64 v[134:135], v[234:235], 0, s[82:83]
	s_mov_b32 m0, s7
	s_nop 0
	global_load_lds_dwordx4 v[134:135], off
	s_waitcnt vmcnt(8)
	s_waitcnt lgkmcnt(0)
	s_barrier
	v_mfma_f32_16x16x32_bf16 v[60:63], v[140:143], v[200:203], v[60:63]
	v_mfma_f32_16x16x32_bf16 v[56:59], v[164:167], v[200:203], v[56:59]
	v_mfma_f32_16x16x32_bf16 v[52:55], v[140:143], v[208:211], v[52:55]
	v_mfma_f32_16x16x32_bf16 v[44:47], v[164:167], v[208:211], v[44:47]
	v_mfma_f32_16x16x32_bf16 v[36:39], v[140:143], v[216:219], v[36:39]
	v_mfma_f32_16x16x32_bf16 v[28:31], v[164:167], v[216:219], v[28:31]
	v_mfma_f32_16x16x32_bf16 v[20:23], v[140:143], v[224:227], v[20:23]
	v_mfma_f32_16x16x32_bf16 v[12:15], v[164:167], v[224:227], v[12:15]
	v_mfma_f32_16x16x32_bf16 v[60:63], v[160:163], v[204:207], v[60:63]
	v_mfma_f32_16x16x32_bf16 v[56:59], v[168:171], v[204:207], v[56:59]
	v_mfma_f32_16x16x32_bf16 v[52:55], v[160:163], v[212:215], v[52:55]
	v_mfma_f32_16x16x32_bf16 v[44:47], v[168:171], v[212:215], v[44:47]
	v_mfma_f32_16x16x32_bf16 v[36:39], v[160:163], v[220:223], v[36:39]
	v_mfma_f32_16x16x32_bf16 v[28:31], v[168:171], v[220:223], v[28:31]
	v_mfma_f32_16x16x32_bf16 v[20:23], v[160:163], v[228:231], v[20:23]
	v_mfma_f32_16x16x32_bf16 v[12:15], v[168:171], v[228:231], v[12:15]
	v_mfma_f32_16x16x32_bf16 v[48:51], v[172:175], v[200:203], v[48:51]
	v_mfma_f32_16x16x32_bf16 v[40:43], v[192:195], v[200:203], v[40:43]
	v_mfma_f32_16x16x32_bf16 v[32:35], v[172:175], v[208:211], v[32:35]
	v_mfma_f32_16x16x32_bf16 v[24:27], v[192:195], v[208:211], v[24:27]
	v_mfma_f32_16x16x32_bf16 v[16:19], v[172:175], v[216:219], v[16:19]
	v_mfma_f32_16x16x32_bf16 v[8:11], v[192:195], v[216:219], v[8:11]
	v_mfma_f32_16x16x32_bf16 v[4:7], v[172:175], v[224:227], v[4:7]
	v_mfma_f32_16x16x32_bf16 v[0:3], v[192:195], v[224:227], v[0:3]
	v_mfma_f32_16x16x32_bf16 v[48:51], v[176:179], v[204:207], v[48:51]
	v_mfma_f32_16x16x32_bf16 v[40:43], v[196:199], v[204:207], v[40:43]
	v_mfma_f32_16x16x32_bf16 v[32:35], v[176:179], v[212:215], v[32:35]
	v_mfma_f32_16x16x32_bf16 v[24:27], v[196:199], v[212:215], v[24:27]
	v_mfma_f32_16x16x32_bf16 v[16:19], v[176:179], v[220:223], v[16:19]
	v_mfma_f32_16x16x32_bf16 v[8:11], v[196:199], v[220:223], v[8:11]
	v_mfma_f32_16x16x32_bf16 v[4:7], v[176:179], v[228:231], v[4:7]
	v_mfma_f32_16x16x32_bf16 v[0:3], v[196:199], v[228:231], v[0:3]
	s_barrier
	s_andn2_b64 vcc, exec, s[36:37]
	s_mov_b64 s[44:45], -1
	s_mov_b64 s[36:37], 0
	s_mov_b64 s[46:47], 0x100
	s_cbranch_vccz .LBB0_679
	s_and_b64 vcc, exec, s[18:19]
	s_cbranch_vccz .LBB0_682

; #define PG8_STAGE(bufoff, gbase, voff) do { _Pragma("unroll") for (int _i = 0; _i < 2; ++_i) \
;         __builtin_amdgcn_global_load_lds((const unsigned*)((const char*)(gbase) + (voff)[_i]), (LAS unsigned*)(lds + (bufoff) + ldsw + _i * 8192), 16, 0, 0); } while (0)
; #define PG8_LDA(dst, b, h) do { _Pragma("unroll") for (int m = 0; m < 4; ++m) _Pragma("unroll") for (int k = 0; k < 2; ++k) dst[m][k] = *(const LAS bf16x8*)(lds + PG8_SA(b, h) + aoff + m * 2048 + k * 1024); } while (0)
; #define PG8_LDB(dst, b, h) do { _Pragma("unroll") for (int n = 0; n < 2; ++n) _Pragma("unroll") for (int k = 0; k < 2; ++k) dst[n][k] = *(const LAS bf16x8*)(lds + PG8_SB(b, h) + boff + n * 2048 + k * 1024); } while (0)
; #define PG8_MMA(ai, bj, At, Bt) do { __builtin_amdgcn_s_setprio(1); _Pragma("unroll") for (int m = 0; m < 4; ++m) _Pragma("unroll") for (int n = 0; n < 2; ++n) _Pragma("unroll") for (int k = 0; k < 2; ++k) \
;         acc[ai][bj][m][n] = __builtin_amdgcn_mfma_f32_16x16x32_bf16(Bt[n][k], At[m][k], acc[ai][bj][m][n], 0, 0, 0); __builtin_amdgcn_s_setprio(0); } while (0)
; #define PG8_WAIT_V(n) asm volatile("s_waitcnt vmcnt(" #n ")" ::: "memory")
; #define PG8_WAIT_L(n) asm volatile("s_waitcnt lgkmcnt(" #n ")" ::: "memory")
; #define PG8_BAR __builtin_amdgcn_s_barrier()
; #define PG8_SCHED __builtin_amdgcn_sched_barrier(0)
; template <class Epi, class Map>
; __device__ __forceinline__ void gemm_phase(LAS unsigned char* lds, const Gemm g, const Sched<Map>& S, const Epi& E) {
;     ...
;         for (int t = 0; t < nt; t += 2) {
;             const bool last = (t == nt - 2);
;             const char* a1 = cA + (size_t)(t + 1) * kstep;
;             const char* a2 = last ? nA : cA + (size_t)(t + 2) * kstep; const char* b2 = last ? nB : cB + (size_t)(t + 2) * kstep;
;             const char* a3 = a2 + kstep; const char* b3 = b2 + kstep;
;             PG8_LDB(B0, 0, 0); PG8_LDB(B1, 0, 1); PG8_SCHED; PG8_LDA(At, 0, 0); PG8_STAGE(PG8_SA(1, 1), a1 + hstepA, voffA);
;             PG8_WAIT_V(8); PG8_WAIT_L(0); PG8_BAR; PG8_MMA(0, 0, At, B0); PG8_MMA(0, 1, At, B1); PG8_BAR; PG8_SCHED;
;             PG8_LDA(At, 0, 1); PG8_STAGE(PG8_SB(0, 0), b2, voffB); PG8_STAGE(PG8_SB(0, 1), b2 + hstepB, voffB); PG8_STAGE(PG8_SA(0, 0), a2, voffA);
;             PG8_WAIT_V(8); PG8_WAIT_L(0); PG8_BAR; PG8_MMA(1, 0, At, B0); PG8_MMA(1, 1, At, B1); PG8_BAR; PG8_SCHED;
.LBB0_808:
	s_add_u32 s36, s34, 0xfffe0080
	s_addc_u32 s37, s35, -1
	s_add_i32 s48, 0, 0x10000
	s_cmp_eq_u32 s47, 4
	s_cselect_b32 s45, s21, s37
	s_cselect_b32 s44, s25, s36
	v_add_u32_e32 v161, s48, v159
	s_cselect_b32 s37, s33, s46
	s_cselect_b32 s36, s38, s39
	s_add_i32 s50, 0, 0x14000
	ds_read_b128 v[138:141], v161
	ds_read_b128 v[162:165], v161 offset:1024
	ds_read_b128 v[166:169], v161 offset:2048
	ds_read_b128 v[170:173], v161 offset:3072
	v_add_u32_e32 v161, s50, v159
	ds_read_b128 v[174:177], v161
	ds_read_b128 v[178:181], v161 offset:1024
	ds_read_b128 v[192:195], v161 offset:2048
	ds_read_b128 v[196:199], v161 offset:3072
	v_lshl_add_u64 v[232:233], s[34:35], 0, v[134:135]
	s_add_i32 m0, s1, 0xc000
	ds_read_b128 v[200:203], v160
	ds_read_b128 v[204:207], v160 offset:1024
	ds_read_b128 v[208:211], v160 offset:2048
	ds_read_b128 v[212:215], v160 offset:3072
	ds_read_b128 v[216:219], v160 offset:4096
	ds_read_b128 v[220:223], v160 offset:5120
	ds_read_b128 v[224:227], v160 offset:6144
	ds_read_b128 v[228:231], v160 offset:7168
	global_load_lds_dwordx4 v[232:233], off
	v_lshl_add_u64 v[232:233], s[34:35], 0, v[136:137]
	s_add_i32 m0, s1, 0xe000
	s_nop 0
	global_load_lds_dwordx4 v[232:233], off
	s_waitcnt vmcnt(8)
	s_waitcnt lgkmcnt(0)
	s_barrier
	v_mfma_f32_16x16x32_bf16 v[124:127], v[138:141], v[200:203], v[124:127]
	v_mfma_f32_16x16x32_bf16 v[120:123], v[166:169], v[200:203], v[120:123]
	v_mfma_f32_16x16x32_bf16 v[116:119], v[138:141], v[208:211], v[116:119]
	v_mfma_f32_16x16x32_bf16 v[112:115], v[166:169], v[208:211], v[112:115]
	v_mfma_f32_16x16x32_bf16 v[108:111], v[138:141], v[216:219], v[108:111]
	v_mfma_f32_16x16x32_bf16 v[104:107], v[166:169], v[216:219], v[104:107]
	v_mfma_f32_16x16x32_bf16 v[100:103], v[138:141], v[224:227], v[100:103]
	v_mfma_f32_16x16x32_bf16 v[96:99], v[166:169], v[224:227], v[96:99]
	v_mfma_f32_16x16x32_bf16 v[124:127], v[162:165], v[204:207], v[124:127]
	v_mfma_f32_16x16x32_bf16 v[120:123], v[170:173], v[204:207], v[120:123]
	v_mfma_f32_16x16x32_bf16 v[116:119], v[162:165], v[212:215], v[116:119]
	v_mfma_f32_16x16x32_bf16 v[112:115], v[170:173], v[212:215], v[112:115]
	v_mfma_f32_16x16x32_bf16 v[108:111], v[162:165], v[220:223], v[108:111]
	v_mfma_f32_16x16x32_bf16 v[104:107], v[170:173], v[220:223], v[104:107]
	v_mfma_f32_16x16x32_bf16 v[100:103], v[162:165], v[228:231], v[100:103]
	v_mfma_f32_16x16x32_bf16 v[96:99], v[170:173], v[228:231], v[96:99]
	v_mfma_f32_16x16x32_bf16 v[92:95], v[174:177], v[200:203], v[92:95]
	v_mfma_f32_16x16x32_bf16 v[88:91], v[192:195], v[200:203], v[88:91]
	v_mfma_f32_16x16x32_bf16 v[84:87], v[174:177], v[208:211], v[84:87]
	v_mfma_f32_16x16x32_bf16 v[80:83], v[192:195], v[208:211], v[80:83]
	v_mfma_f32_16x16x32_bf16 v[76:79], v[174:177], v[216:219], v[76:79]
	v_mfma_f32_16x16x32_bf16 v[72:75], v[192:195], v[216:219], v[72:75]
	v_mfma_f32_16x16x32_bf16 v[68:71], v[174:177], v[224:227], v[68:71]
	v_mfma_f32_16x16x32_bf16 v[64:67], v[192:195], v[224:227], v[64:67]
	v_mfma_f32_16x16x32_bf16 v[92:95], v[178:181], v[204:207], v[92:95]
	v_mfma_f32_16x16x32_bf16 v[88:91], v[196:199], v[204:207], v[88:91]
	v_mfma_f32_16x16x32_bf16 v[84:87], v[178:181], v[212:215], v[84:87]
	v_mfma_f32_16x16x32_bf16 v[80:83], v[196:199], v[212:215], v[80:83]
	v_mfma_f32_16x16x32_bf16 v[76:79], v[178:181], v[220:223], v[76:79]
	v_mfma_f32_16x16x32_bf16 v[72:75], v[196:199], v[220:223], v[72:75]
	v_mfma_f32_16x16x32_bf16 v[68:71], v[178:181], v[228:231], v[68:71]
	v_mfma_f32_16x16x32_bf16 v[64:67], v[196:199], v[228:231], v[64:67]
	s_barrier
	s_add_i32 s48, s48, s0
	v_lshl_add_u64 v[232:233], s[36:37], 0, v[144:145]
	s_mov_b32 m0, s48
	ds_read_b128 v[200:203], v160 offset:16384
	ds_read_b128 v[204:207], v160 offset:17408
	ds_read_b128 v[208:211], v160 offset:18432
	ds_read_b128 v[212:215], v160 offset:19456
	ds_read_b128 v[216:219], v160 offset:20480
	ds_read_b128 v[220:223], v160 offset:21504
	ds_read_b128 v[224:227], v160 offset:22528
	ds_read_b128 v[228:231], v160 offset:23552
	global_load_lds_dwordx4 v[232:233], off
	s_add_i32 m0, s48, 0x2000
	s_add_u32 s48, s36, 0x20000
	v_lshl_add_u64 v[234:235], s[36:37], 0, v[128:129]
	s_addc_u32 s49, s37, 0
	s_add_i32 s50, s50, s0
	global_load_lds_dwordx4 v[234:235], off
	v_lshl_add_u64 v[236:237], s[48:49], 0, v[144:145]
	s_mov_b32 m0, s50
	v_lshl_add_u64 v[238:239], s[44:45], 0, v[130:131]
	global_load_lds_dwordx4 v[236:237], off
	v_lshl_add_u64 v[236:237], s[48:49], 0, v[128:129]
	s_add_i32 m0, s50, 0x2000
	s_nop 0
	global_load_lds_dwordx4 v[236:237], off
	v_lshl_add_u64 v[236:237], s[44:45], 0, v[132:133]
	s_mov_b32 m0, s1
	s_nop 0
	global_load_lds_dwordx4 v[236:237], off
	s_mov_b32 m0, s2
	s_nop 0
	global_load_lds_dwordx4 v[238:239], off
	s_waitcnt vmcnt(8)
	s_waitcnt lgkmcnt(0)
	s_barrier
; #define PG8_STAGE(bufoff, gbase, voff) do { _Pragma("unroll") for (int _i = 0; _i < 2; ++_i) \
;         __builtin_amdgcn_global_load_lds((const unsigned*)((const char*)(gbase) + (voff)[_i]), (LAS unsigned*)(lds + (bufoff) + ldsw + _i * 8192), 16, 0, 0); } while (0)
; #define PG8_LDA(dst, b, h) do { _Pragma("unroll") for (int m = 0; m < 4; ++m) _Pragma("unroll") for (int k = 0; k < 2; ++k) dst[m][k] = *(const LAS bf16x8*)(lds + PG8_SA(b, h) + aoff + m * 2048 + k * 1024); } while (0)
; #define PG8_LDB(dst, b, h) do { _Pragma("unroll") for (int n = 0; n < 2; ++n) _Pragma("unroll") for (int k = 0; k < 2; ++k) dst[n][k] = *(const LAS bf16x8*)(lds + PG8_SB(b, h) + boff + n * 2048 + k * 1024); } while (0)
; #define PG8_MMA(ai, bj, At, Bt) do { __builtin_amdgcn_s_setprio(1); _Pragma("unroll") for (int m = 0; m < 4; ++m) _Pragma("unroll") for (int n = 0; n < 2; ++n) _Pragma("unroll") for (int k = 0; k < 2; ++k) \
;         acc[ai][bj][m][n] = __builtin_amdgcn_mfma_f32_16x16x32_bf16(Bt[n][k], At[m][k], acc[ai][bj][m][n], 0, 0, 0); __builtin_amdgcn_s_setprio(0); } while (0)
; #define PG8_WAIT_V(n) asm volatile("s_waitcnt vmcnt(" #n ")" ::: "memory")
; #define PG8_WAIT_L(n) asm volatile("s_waitcnt lgkmcnt(" #n ")" ::: "memory")
; #define PG8_BAR __builtin_amdgcn_s_barrier()
; #define PG8_SCHED __builtin_amdgcn_sched_barrier(0)
; template <class Epi, class Map>
; __device__ __forceinline__ void gemm_phase(LAS unsigned char* lds, const Gemm g, const Sched<Map>& S, const Epi& E) {
;     ...
;             PG8_WAIT_V(8); PG8_WAIT_L(0); PG8_BAR; PG8_MMA(1, 0, At, B0); PG8_MMA(1, 1, At, B1); PG8_BAR; PG8_SCHED;
;             PG8_LDB(B0, 1, 0); PG8_LDB(B1, 1, 1); PG8_SCHED; PG8_LDA(At, 1, 0); PG8_STAGE(PG8_SA(0, 1), a2 + hstepA, voffA);
;             PG8_WAIT_V(8); PG8_WAIT_L(0); PG8_BAR; PG8_MMA(0, 0, At, B0); PG8_MMA(0, 1, At, B1); PG8_BAR; PG8_SCHED;
	v_mfma_f32_16x16x32_bf16 v[60:63], v[138:141], v[200:203], v[60:63]
	v_mfma_f32_16x16x32_bf16 v[56:59], v[166:169], v[200:203], v[56:59]
	v_mfma_f32_16x16x32_bf16 v[52:55], v[138:141], v[208:211], v[52:55]
	v_mfma_f32_16x16x32_bf16 v[48:51], v[166:169], v[208:211], v[48:51]
	v_mfma_f32_16x16x32_bf16 v[44:47], v[138:141], v[216:219], v[44:47]
	v_mfma_f32_16x16x32_bf16 v[40:43], v[166:169], v[216:219], v[40:43]
	v_mfma_f32_16x16x32_bf16 v[36:39], v[138:141], v[224:227], v[36:39]
	v_mfma_f32_16x16x32_bf16 v[32:35], v[166:169], v[224:227], v[32:35]
	v_mfma_f32_16x16x32_bf16 v[60:63], v[162:165], v[204:207], v[60:63]
	v_mfma_f32_16x16x32_bf16 v[56:59], v[170:173], v[204:207], v[56:59]
	v_mfma_f32_16x16x32_bf16 v[52:55], v[162:165], v[212:215], v[52:55]
	v_mfma_f32_16x16x32_bf16 v[48:51], v[170:173], v[212:215], v[48:51]
	v_mfma_f32_16x16x32_bf16 v[44:47], v[162:165], v[220:223], v[44:47]
	v_mfma_f32_16x16x32_bf16 v[40:43], v[170:173], v[220:223], v[40:43]
	v_mfma_f32_16x16x32_bf16 v[36:39], v[162:165], v[228:231], v[36:39]
	v_mfma_f32_16x16x32_bf16 v[32:35], v[170:173], v[228:231], v[32:35]
	v_mfma_f32_16x16x32_bf16 v[28:31], v[174:177], v[200:203], v[28:31]
	v_mfma_f32_16x16x32_bf16 v[24:27], v[192:195], v[200:203], v[24:27]
	v_mfma_f32_16x16x32_bf16 v[20:23], v[174:177], v[208:211], v[20:23]
	v_mfma_f32_16x16x32_bf16 v[16:19], v[192:195], v[208:211], v[16:19]
	v_mfma_f32_16x16x32_bf16 v[12:15], v[174:177], v[216:219], v[12:15]
	v_mfma_f32_16x16x32_bf16 v[8:11], v[192:195], v[216:219], v[8:11]
	v_mfma_f32_16x16x32_bf16 v[4:7], v[174:177], v[224:227], v[4:7]
	v_mfma_f32_16x16x32_bf16 v[0:3], v[192:195], v[224:227], v[0:3]
	v_mfma_f32_16x16x32_bf16 v[28:31], v[178:181], v[204:207], v[28:31]
	v_mfma_f32_16x16x32_bf16 v[24:27], v[196:199], v[204:207], v[24:27]
	v_mfma_f32_16x16x32_bf16 v[20:23], v[178:181], v[212:215], v[20:23]
	v_mfma_f32_16x16x32_bf16 v[16:19], v[196:199], v[212:215], v[16:19]
	v_mfma_f32_16x16x32_bf16 v[12:15], v[178:181], v[220:223], v[12:15]
	v_mfma_f32_16x16x32_bf16 v[8:11], v[196:199], v[220:223], v[8:11]
	v_mfma_f32_16x16x32_bf16 v[4:7], v[178:181], v[228:231], v[4:7]
	v_mfma_f32_16x16x32_bf16 v[0:3], v[196:199], v[228:231], v[0:3]
	s_barrier
	s_add_i32 s48, 0, 0x18000
	v_add_u32_e32 v161, s48, v159
	s_add_i32 s49, 0, 0x1c000
	ds_read_b128 v[138:141], v161
	ds_read_b128 v[162:165], v161 offset:1024
	ds_read_b128 v[166:169], v161 offset:2048
	ds_read_b128 v[170:173], v161 offset:3072
	v_add_u32_e32 v161, s49, v159
	ds_read_b128 v[174:177], v161
	ds_read_b128 v[178:181], v161 offset:1024
	ds_read_b128 v[192:195], v161 offset:2048
	ds_read_b128 v[196:199], v161 offset:3072
	s_add_u32 s44, s44, 0x20000
	s_addc_u32 s45, s45, 0
	s_mov_b32 m0, s3
	v_lshl_add_u64 v[240:241], s[44:45], 0, v[132:133]
	ds_read_b128 v[200:203], v160 offset:32768
	ds_read_b128 v[204:207], v160 offset:33792
	ds_read_b128 v[208:211], v160 offset:34816
	ds_read_b128 v[212:215], v160 offset:35840
	ds_read_b128 v[216:219], v160 offset:36864
	ds_read_b128 v[220:223], v160 offset:37888
	ds_read_b128 v[224:227], v160 offset:38912
	ds_read_b128 v[228:231], v160 offset:39936
	global_load_lds_dwordx4 v[240:241], off
	v_lshl_add_u64 v[240:241], s[44:45], 0, v[130:131]
	s_mov_b32 m0, s4
	s_nop 0
	global_load_lds_dwordx4 v[240:241], off
	s_waitcnt vmcnt(8)
	s_waitcnt lgkmcnt(0)
	s_barrier
	v_mfma_f32_16x16x32_bf16 v[124:127], v[138:141], v[200:203], v[124:127]
	v_mfma_f32_16x16x32_bf16 v[120:123], v[166:169], v[200:203], v[120:123]
	v_mfma_f32_16x16x32_bf16 v[116:119], v[138:141], v[208:211], v[116:119]
	v_mfma_f32_16x16x32_bf16 v[112:115], v[166:169], v[208:211], v[112:115]
	v_mfma_f32_16x16x32_bf16 v[108:111], v[138:141], v[216:219], v[108:111]
	v_mfma_f32_16x16x32_bf16 v[104:107], v[166:169], v[216:219], v[104:107]
	v_mfma_f32_16x16x32_bf16 v[100:103], v[138:141], v[224:227], v[100:103]
	v_mfma_f32_16x16x32_bf16 v[96:99], v[166:169], v[224:227], v[96:99]
	v_mfma_f32_16x16x32_bf16 v[124:127], v[162:165], v[204:207], v[124:127]
	v_mfma_f32_16x16x32_bf16 v[120:123], v[170:173], v[204:207], v[120:123]
	v_mfma_f32_16x16x32_bf16 v[116:119], v[162:165], v[212:215], v[116:119]
	v_mfma_f32_16x16x32_bf16 v[112:115], v[170:173], v[212:215], v[112:115]
	v_mfma_f32_16x16x32_bf16 v[108:111], v[162:165], v[220:223], v[108:111]
	v_mfma_f32_16x16x32_bf16 v[104:107], v[170:173], v[220:223], v[104:107]
	v_mfma_f32_16x16x32_bf16 v[100:103], v[162:165], v[228:231], v[100:103]
	v_mfma_f32_16x16x32_bf16 v[96:99], v[170:173], v[228:231], v[96:99]
	v_mfma_f32_16x16x32_bf16 v[92:95], v[174:177], v[200:203], v[92:95]
	v_mfma_f32_16x16x32_bf16 v[88:91], v[192:195], v[200:203], v[88:91]
	v_mfma_f32_16x16x32_bf16 v[84:87], v[174:177], v[208:211], v[84:87]
	v_mfma_f32_16x16x32_bf16 v[80:83], v[192:195], v[208:211], v[80:83]
	v_mfma_f32_16x16x32_bf16 v[76:79], v[174:177], v[216:219], v[76:79]
	v_mfma_f32_16x16x32_bf16 v[72:75], v[192:195], v[216:219], v[72:75]
	v_mfma_f32_16x16x32_bf16 v[68:71], v[174:177], v[224:227], v[68:71]
	v_mfma_f32_16x16x32_bf16 v[64:67], v[192:195], v[224:227], v[64:67]
	v_mfma_f32_16x16x32_bf16 v[92:95], v[178:181], v[204:207], v[92:95]
	v_mfma_f32_16x16x32_bf16 v[88:91], v[196:199], v[204:207], v[88:91]
	v_mfma_f32_16x16x32_bf16 v[84:87], v[178:181], v[212:215], v[84:87]
	v_mfma_f32_16x16x32_bf16 v[80:83], v[196:199], v[212:215], v[80:83]
	v_mfma_f32_16x16x32_bf16 v[76:79], v[178:181], v[220:223], v[76:79]
	v_mfma_f32_16x16x32_bf16 v[72:75], v[196:199], v[220:223], v[72:75]
	v_mfma_f32_16x16x32_bf16 v[68:71], v[178:181], v[228:231], v[68:71]
	v_mfma_f32_16x16x32_bf16 v[64:67], v[196:199], v[228:231], v[64:67]
	s_barrier
; #define PG8_STAGE(bufoff, gbase, voff) do { _Pragma("unroll") for (int _i = 0; _i < 2; ++_i) \
;         __builtin_amdgcn_global_load_lds((const unsigned*)((const char*)(gbase) + (voff)[_i]), (LAS unsigned*)(lds + (bufoff) + ldsw + _i * 8192), 16, 0, 0); } while (0)
; #define PG8_LDA(dst, b, h) do { _Pragma("unroll") for (int m = 0; m < 4; ++m) _Pragma("unroll") for (int k = 0; k < 2; ++k) dst[m][k] = *(const LAS bf16x8*)(lds + PG8_SA(b, h) + aoff + m * 2048 + k * 1024); } while (0)
; #define PG8_MMA(ai, bj, At, Bt) do { __builtin_amdgcn_s_setprio(1); _Pragma("unroll") for (int m = 0; m < 4; ++m) _Pragma("unroll") for (int n = 0; n < 2; ++n) _Pragma("unroll") for (int k = 0; k < 2; ++k) \
;         acc[ai][bj][m][n] = __builtin_amdgcn_mfma_f32_16x16x32_bf16(Bt[n][k], At[m][k], acc[ai][bj][m][n], 0, 0, 0); __builtin_amdgcn_s_setprio(0); } while (0)
; #define PG8_WAIT_V(n) asm volatile("s_waitcnt vmcnt(" #n ")" ::: "memory")
; #define PG8_WAIT_L(n) asm volatile("s_waitcnt lgkmcnt(" #n ")" ::: "memory")
; #define PG8_BAR __builtin_amdgcn_s_barrier()
; #define PG8_SCHED __builtin_amdgcn_sched_barrier(0)
; template <class Epi, class Map>
; __device__ __forceinline__ void gemm_phase(LAS unsigned char* lds, const Gemm g, const Sched<Map>& S, const Epi& E) {
;     ...
;             PG8_LDA(At, 1, 1); PG8_STAGE(PG8_SB(1, 0), b3, voffB); PG8_STAGE(PG8_SB(1, 1), b3 + hstepB, voffB); PG8_STAGE(PG8_SA(1, 0), a3, voffA);
;             PG8_WAIT_V(8); PG8_WAIT_L(0); PG8_BAR; PG8_MMA(1, 0, At, B0); PG8_MMA(1, 1, At, B1); PG8_BAR; PG8_SCHED;
;         }
	s_add_i32 s44, s48, s0
	v_lshl_add_u64 v[232:233], v[232:233], 0, s[82:83]
	s_mov_b32 m0, s44
	ds_read_b128 v[200:203], v160 offset:49152
	ds_read_b128 v[204:207], v160 offset:50176
	ds_read_b128 v[208:211], v160 offset:51200
	ds_read_b128 v[212:215], v160 offset:52224
	ds_read_b128 v[216:219], v160 offset:53248
	ds_read_b128 v[220:223], v160 offset:54272
	ds_read_b128 v[224:227], v160 offset:55296
	ds_read_b128 v[228:231], v160 offset:56320
	global_load_lds_dwordx4 v[232:233], off
	s_add_i32 m0, s44, 0x2000
	s_add_u32 s36, s36, 0x20080
	v_lshl_add_u64 v[232:233], v[234:235], 0, s[82:83]
	s_addc_u32 s37, s37, 0
	s_add_i32 s44, s49, s0
	global_load_lds_dwordx4 v[232:233], off
	v_lshl_add_u64 v[232:233], s[36:37], 0, v[144:145]
	s_mov_b32 m0, s44
	s_nop 0
	global_load_lds_dwordx4 v[232:233], off
	v_lshl_add_u64 v[232:233], s[36:37], 0, v[128:129]
	s_add_i32 m0, s44, 0x2000
	s_nop 0
	global_load_lds_dwordx4 v[232:233], off
	v_lshl_add_u64 v[232:233], v[236:237], 0, s[82:83]
	s_mov_b32 m0, s6
	s_nop 0
	global_load_lds_dwordx4 v[232:233], off
	v_lshl_add_u64 v[232:233], v[238:239], 0, s[82:83]
	s_mov_b32 m0, s7
	s_nop 0
	global_load_lds_dwordx4 v[232:233], off
	s_waitcnt vmcnt(8)
	s_waitcnt lgkmcnt(0)
	s_barrier
	v_mfma_f32_16x16x32_bf16 v[60:63], v[138:141], v[200:203], v[60:63]
	v_mfma_f32_16x16x32_bf16 v[56:59], v[166:169], v[200:203], v[56:59]
	v_mfma_f32_16x16x32_bf16 v[52:55], v[138:141], v[208:211], v[52:55]
	v_mfma_f32_16x16x32_bf16 v[48:51], v[166:169], v[208:211], v[48:51]
	v_mfma_f32_16x16x32_bf16 v[44:47], v[138:141], v[216:219], v[44:47]
	v_mfma_f32_16x16x32_bf16 v[40:43], v[166:169], v[216:219], v[40:43]
	v_mfma_f32_16x16x32_bf16 v[36:39], v[138:141], v[224:227], v[36:39]
	v_mfma_f32_16x16x32_bf16 v[32:35], v[166:169], v[224:227], v[32:35]
	v_mfma_f32_16x16x32_bf16 v[60:63], v[162:165], v[204:207], v[60:63]
	v_mfma_f32_16x16x32_bf16 v[56:59], v[170:173], v[204:207], v[56:59]
	v_mfma_f32_16x16x32_bf16 v[52:55], v[162:165], v[212:215], v[52:55]
	v_mfma_f32_16x16x32_bf16 v[48:51], v[170:173], v[212:215], v[48:51]
	v_mfma_f32_16x16x32_bf16 v[44:47], v[162:165], v[220:223], v[44:47]
	v_mfma_f32_16x16x32_bf16 v[40:43], v[170:173], v[220:223], v[40:43]
	v_mfma_f32_16x16x32_bf16 v[36:39], v[162:165], v[228:231], v[36:39]
	v_mfma_f32_16x16x32_bf16 v[32:35], v[170:173], v[228:231], v[32:35]
	v_mfma_f32_16x16x32_bf16 v[28:31], v[174:177], v[200:203], v[28:31]
	v_mfma_f32_16x16x32_bf16 v[24:27], v[192:195], v[200:203], v[24:27]
	v_mfma_f32_16x16x32_bf16 v[20:23], v[174:177], v[208:211], v[20:23]
	v_mfma_f32_16x16x32_bf16 v[16:19], v[192:195], v[208:211], v[16:19]
	v_mfma_f32_16x16x32_bf16 v[12:15], v[174:177], v[216:219], v[12:15]
	v_mfma_f32_16x16x32_bf16 v[8:11], v[192:195], v[216:219], v[8:11]
	v_mfma_f32_16x16x32_bf16 v[4:7], v[174:177], v[224:227], v[4:7]
	v_mfma_f32_16x16x32_bf16 v[0:3], v[192:195], v[224:227], v[0:3]
	v_mfma_f32_16x16x32_bf16 v[28:31], v[178:181], v[204:207], v[28:31]
	v_mfma_f32_16x16x32_bf16 v[24:27], v[196:199], v[204:207], v[24:27]
	v_mfma_f32_16x16x32_bf16 v[20:23], v[178:181], v[212:215], v[20:23]
	v_mfma_f32_16x16x32_bf16 v[16:19], v[196:199], v[212:215], v[16:19]
	v_mfma_f32_16x16x32_bf16 v[12:15], v[178:181], v[220:223], v[12:15]
	v_mfma_f32_16x16x32_bf16 v[8:11], v[196:199], v[220:223], v[8:11]
	v_mfma_f32_16x16x32_bf16 v[4:7], v[178:181], v[228:231], v[4:7]
	v_mfma_f32_16x16x32_bf16 v[0:3], v[196:199], v[228:231], v[0:3]
	s_barrier
	s_add_i32 s47, s47, 2
	s_add_u32 s34, s34, 0x100
	s_addc_u32 s35, s35, 0
	s_add_u32 s39, s39, 0x100
	s_addc_u32 s46, s46, 0
	s_cmp_gt_u32 s47, 5
	s_cbranch_scc0 .LBB0_808
	s_and_b64 vcc, exec, s[18:19]
	s_cbranch_vccz .LBB0_811

; #define PG8_STAGE(bufoff, gbase, voff) do { _Pragma("unroll") for (int _i = 0; _i < 2; ++_i) \
;         __builtin_amdgcn_global_load_lds((const unsigned*)((const char*)(gbase) + (voff)[_i]), (LAS unsigned*)(lds + (bufoff) + ldsw + _i * 8192), 16, 0, 0); } while (0)
; #define PG8_LDA(dst, b, h) do { _Pragma("unroll") for (int m = 0; m < 4; ++m) _Pragma("unroll") for (int k = 0; k < 2; ++k) dst[m][k] = *(const LAS bf16x8*)(lds + PG8_SA(b, h) + aoff + m * 2048 + k * 1024); } while (0)
; #define PG8_LDB(dst, b, h) do { _Pragma("unroll") for (int n = 0; n < 2; ++n) _Pragma("unroll") for (int k = 0; k < 2; ++k) dst[n][k] = *(const LAS bf16x8*)(lds + PG8_SB(b, h) + boff + n * 2048 + k * 1024); } while (0)
; #define PG8_MMA(ai, bj, At, Bt) do { __builtin_amdgcn_s_setprio(1); _Pragma("unroll") for (int m = 0; m < 4; ++m) _Pragma("unroll") for (int n = 0; n < 2; ++n) _Pragma("unroll") for (int k = 0; k < 2; ++k) \
;         acc[ai][bj][m][n] = __builtin_amdgcn_mfma_f32_16x16x32_bf16(Bt[n][k], At[m][k], acc[ai][bj][m][n], 0, 0, 0); __builtin_amdgcn_s_setprio(0); } while (0)
; #define PG8_WAIT_V(n) asm volatile("s_waitcnt vmcnt(" #n ")" ::: "memory")
; #define PG8_WAIT_L(n) asm volatile("s_waitcnt lgkmcnt(" #n ")" ::: "memory")
; #define PG8_BAR __builtin_amdgcn_s_barrier()
; #define PG8_SCHED __builtin_amdgcn_sched_barrier(0)
; template <class Epi, class Map>
; __device__ __forceinline__ void gemm_phase(LAS unsigned char* lds, const Gemm g, const Sched<Map>& S, const Epi& E) {
;     ...
;         for (int t = 0; t < nt; t += 2) {
;             const bool last = (t == nt - 2);
;             const char* a1 = cA + (size_t)(t + 1) * kstep;
;             const char* a2 = last ? nA : cA + (size_t)(t + 2) * kstep; const char* b2 = last ? nB : cB + (size_t)(t + 2) * kstep;
;             const char* a3 = a2 + kstep; const char* b3 = b2 + kstep;
;             PG8_LDB(B0, 0, 0); PG8_LDB(B1, 0, 1); PG8_SCHED; PG8_LDA(At, 0, 0); PG8_STAGE(PG8_SA(1, 1), a1 + hstepA, voffA);
;             PG8_WAIT_V(8); PG8_WAIT_L(0); PG8_BAR; PG8_MMA(0, 0, At, B0); PG8_MMA(0, 1, At, B1); PG8_BAR; PG8_SCHED;
;             PG8_LDA(At, 0, 1); PG8_STAGE(PG8_SB(0, 0), b2, voffB); PG8_STAGE(PG8_SB(0, 1), b2 + hstepB, voffB); PG8_STAGE(PG8_SA(0, 0), a2, voffA);
;             PG8_WAIT_V(8); PG8_WAIT_L(0); PG8_BAR; PG8_MMA(1, 0, At, B0); PG8_MMA(1, 1, At, B1); PG8_BAR; PG8_SCHED;
.LBB0_880:
	s_add_u32 s9, s18, 0xfff80080
	s_addc_u32 s10, s19, -1
	s_add_i32 s11, 0, 0x10000
	s_cmp_eq_u32 s8, 28
	s_cselect_b32 s25, s2, s10
	s_cselect_b32 s24, s3, s9
	s_cselect_b32 s21, s4, s7
	s_cselect_b32 s20, s5, s6
	s_add_i32 s9, 0, 0x14000
	v_add_u32_e32 v166, s11, v173
	v_add_u32_e32 v170, s9, v173
	ds_read_b128 v[124:127], v166
	ds_read_b128 v[132:135], v166 offset:1024
	ds_read_b128 v[162:165], v166 offset:2048
	ds_read_b128 v[166:169], v166 offset:3072
	ds_read_b128 v[176:179], v170
	ds_read_b128 v[192:195], v170 offset:1024
	ds_read_b128 v[196:199], v170 offset:2048
	ds_read_b128 v[200:203], v170 offset:3072
	v_lshl_add_u64 v[170:171], s[18:19], 0, v[142:143]
	s_add_i32 m0, s29, 0xc000
	ds_read_b128 v[204:207], v174
	ds_read_b128 v[208:211], v174 offset:1024
	ds_read_b128 v[212:215], v174 offset:2048
	ds_read_b128 v[216:219], v174 offset:3072
	ds_read_b128 v[220:223], v174 offset:4096
	ds_read_b128 v[224:227], v174 offset:5120
	ds_read_b128 v[228:231], v174 offset:6144
	ds_read_b128 v[232:235], v174 offset:7168
	global_load_lds_dwordx4 v[170:171], off
	v_lshl_add_u64 v[170:171], s[18:19], 0, v[160:161]
	s_add_i32 m0, s29, 0xe000
	s_nop 0
	global_load_lds_dwordx4 v[170:171], off
	s_waitcnt vmcnt(8)
	s_waitcnt lgkmcnt(0)
	s_barrier
	v_mfma_f32_16x16x32_bf16 v[128:131], v[124:127], v[204:207], v[128:131]
	v_mfma_f32_16x16x32_bf16 v[120:123], v[162:165], v[204:207], v[120:123]
	v_mfma_f32_16x16x32_bf16 v[108:111], v[124:127], v[212:215], v[108:111]
	v_mfma_f32_16x16x32_bf16 v[104:107], v[162:165], v[212:215], v[104:107]
	v_mfma_f32_16x16x32_bf16 v[92:95], v[124:127], v[220:223], v[92:95]
	v_mfma_f32_16x16x32_bf16 v[88:91], v[162:165], v[220:223], v[88:91]
	v_mfma_f32_16x16x32_bf16 v[76:79], v[124:127], v[228:231], v[76:79]
	v_mfma_f32_16x16x32_bf16 v[72:75], v[162:165], v[228:231], v[72:75]
	v_mfma_f32_16x16x32_bf16 v[128:131], v[132:135], v[208:211], v[128:131]
	v_mfma_f32_16x16x32_bf16 v[120:123], v[166:169], v[208:211], v[120:123]
	v_mfma_f32_16x16x32_bf16 v[108:111], v[132:135], v[216:219], v[108:111]
	v_mfma_f32_16x16x32_bf16 v[104:107], v[166:169], v[216:219], v[104:107]
	v_mfma_f32_16x16x32_bf16 v[92:95], v[132:135], v[224:227], v[92:95]
	v_mfma_f32_16x16x32_bf16 v[88:91], v[166:169], v[224:227], v[88:91]
	v_mfma_f32_16x16x32_bf16 v[76:79], v[132:135], v[232:235], v[76:79]
	v_mfma_f32_16x16x32_bf16 v[72:75], v[166:169], v[232:235], v[72:75]
	v_mfma_f32_16x16x32_bf16 v[116:119], v[176:179], v[204:207], v[116:119]
	v_mfma_f32_16x16x32_bf16 v[112:115], v[196:199], v[204:207], v[112:115]
	v_mfma_f32_16x16x32_bf16 v[100:103], v[176:179], v[212:215], v[100:103]
	v_mfma_f32_16x16x32_bf16 v[96:99], v[196:199], v[212:215], v[96:99]
	v_mfma_f32_16x16x32_bf16 v[84:87], v[176:179], v[220:223], v[84:87]
	v_mfma_f32_16x16x32_bf16 v[80:83], v[196:199], v[220:223], v[80:83]
	v_mfma_f32_16x16x32_bf16 v[68:71], v[176:179], v[228:231], v[68:71]
	v_mfma_f32_16x16x32_bf16 v[64:67], v[196:199], v[228:231], v[64:67]
	v_mfma_f32_16x16x32_bf16 v[116:119], v[192:195], v[208:211], v[116:119]
	v_mfma_f32_16x16x32_bf16 v[112:115], v[200:203], v[208:211], v[112:115]
	v_mfma_f32_16x16x32_bf16 v[100:103], v[192:195], v[216:219], v[100:103]
	v_mfma_f32_16x16x32_bf16 v[96:99], v[200:203], v[216:219], v[96:99]
	v_mfma_f32_16x16x32_bf16 v[84:87], v[192:195], v[224:227], v[84:87]
	v_mfma_f32_16x16x32_bf16 v[80:83], v[200:203], v[224:227], v[80:83]
	v_mfma_f32_16x16x32_bf16 v[68:71], v[192:195], v[232:235], v[68:71]
	v_mfma_f32_16x16x32_bf16 v[64:67], v[200:203], v[232:235], v[64:67]
	s_barrier
	s_add_i32 s10, s11, s28
	v_lshl_add_u64 v[170:171], s[20:21], 0, v[144:145]
	s_mov_b32 m0, s10
	ds_read_b128 v[204:207], v174 offset:16384
	ds_read_b128 v[208:211], v174 offset:17408
	ds_read_b128 v[212:215], v174 offset:18432
	ds_read_b128 v[216:219], v174 offset:19456
	ds_read_b128 v[220:223], v174 offset:20480
	ds_read_b128 v[224:227], v174 offset:21504
	ds_read_b128 v[228:231], v174 offset:22528
	ds_read_b128 v[232:235], v174 offset:23552
	global_load_lds_dwordx4 v[170:171], off
	s_add_i32 m0, s10, 0x2000
	s_add_u32 s10, s20, 0x80000
	v_lshl_add_u64 v[180:181], s[20:21], 0, v[136:137]
	s_addc_u32 s11, s21, 0
	s_add_i32 s9, s9, s28
	global_load_lds_dwordx4 v[180:181], off
	v_lshl_add_u64 v[236:237], s[10:11], 0, v[144:145]
	s_mov_b32 m0, s9
	v_lshl_add_u64 v[238:239], s[24:25], 0, v[138:139]
	global_load_lds_dwordx4 v[236:237], off
	v_lshl_add_u64 v[236:237], s[10:11], 0, v[136:137]
	s_add_i32 m0, s9, 0x2000
	s_nop 0
	global_load_lds_dwordx4 v[236:237], off
	v_lshl_add_u64 v[236:237], s[24:25], 0, v[140:141]
	s_mov_b32 m0, s29
	s_nop 0
	global_load_lds_dwordx4 v[236:237], off
	s_mov_b32 m0, s30
	s_nop 0
	global_load_lds_dwordx4 v[238:239], off
	s_waitcnt vmcnt(8)
	s_waitcnt lgkmcnt(0)
	s_barrier
; #define PG8_STAGE(bufoff, gbase, voff) do { _Pragma("unroll") for (int _i = 0; _i < 2; ++_i) \
;         __builtin_amdgcn_global_load_lds((const unsigned*)((const char*)(gbase) + (voff)[_i]), (LAS unsigned*)(lds + (bufoff) + ldsw + _i * 8192), 16, 0, 0); } while (0)
; #define PG8_LDA(dst, b, h) do { _Pragma("unroll") for (int m = 0; m < 4; ++m) _Pragma("unroll") for (int k = 0; k < 2; ++k) dst[m][k] = *(const LAS bf16x8*)(lds + PG8_SA(b, h) + aoff + m * 2048 + k * 1024); } while (0)
; #define PG8_LDB(dst, b, h) do { _Pragma("unroll") for (int n = 0; n < 2; ++n) _Pragma("unroll") for (int k = 0; k < 2; ++k) dst[n][k] = *(const LAS bf16x8*)(lds + PG8_SB(b, h) + boff + n * 2048 + k * 1024); } while (0)
; #define PG8_MMA(ai, bj, At, Bt) do { __builtin_amdgcn_s_setprio(1); _Pragma("unroll") for (int m = 0; m < 4; ++m) _Pragma("unroll") for (int n = 0; n < 2; ++n) _Pragma("unroll") for (int k = 0; k < 2; ++k) \
;         acc[ai][bj][m][n] = __builtin_amdgcn_mfma_f32_16x16x32_bf16(Bt[n][k], At[m][k], acc[ai][bj][m][n], 0, 0, 0); __builtin_amdgcn_s_setprio(0); } while (0)
; #define PG8_WAIT_V(n) asm volatile("s_waitcnt vmcnt(" #n ")" ::: "memory")
; #define PG8_WAIT_L(n) asm volatile("s_waitcnt lgkmcnt(" #n ")" ::: "memory")
; #define PG8_BAR __builtin_amdgcn_s_barrier()
; #define PG8_SCHED __builtin_amdgcn_sched_barrier(0)
; template <class Epi, class Map>
; __device__ __forceinline__ void gemm_phase(LAS unsigned char* lds, const Gemm g, const Sched<Map>& S, const Epi& E) {
;     ...
;             PG8_WAIT_V(8); PG8_WAIT_L(0); PG8_BAR; PG8_MMA(1, 0, At, B0); PG8_MMA(1, 1, At, B1); PG8_BAR; PG8_SCHED;
;             PG8_LDB(B0, 1, 0); PG8_LDB(B1, 1, 1); PG8_SCHED; PG8_LDA(At, 1, 0); PG8_STAGE(PG8_SA(0, 1), a2 + hstepA, voffA);
;             PG8_WAIT_V(8); PG8_WAIT_L(0); PG8_BAR; PG8_MMA(0, 0, At, B0); PG8_MMA(0, 1, At, B1); PG8_BAR; PG8_SCHED;
	v_mfma_f32_16x16x32_bf16 v[60:63], v[124:127], v[204:207], v[60:63]
	v_mfma_f32_16x16x32_bf16 v[56:59], v[162:165], v[204:207], v[56:59]
	v_mfma_f32_16x16x32_bf16 v[44:47], v[124:127], v[212:215], v[44:47]
	v_mfma_f32_16x16x32_bf16 v[40:43], v[162:165], v[212:215], v[40:43]
	v_mfma_f32_16x16x32_bf16 v[28:31], v[124:127], v[220:223], v[28:31]
	v_mfma_f32_16x16x32_bf16 v[24:27], v[162:165], v[220:223], v[24:27]
	v_mfma_f32_16x16x32_bf16 v[12:15], v[124:127], v[228:231], v[12:15]
	v_mfma_f32_16x16x32_bf16 v[8:11], v[162:165], v[228:231], v[8:11]
	v_mfma_f32_16x16x32_bf16 v[60:63], v[132:135], v[208:211], v[60:63]
	v_mfma_f32_16x16x32_bf16 v[56:59], v[166:169], v[208:211], v[56:59]
	v_mfma_f32_16x16x32_bf16 v[44:47], v[132:135], v[216:219], v[44:47]
	v_mfma_f32_16x16x32_bf16 v[40:43], v[166:169], v[216:219], v[40:43]
	v_mfma_f32_16x16x32_bf16 v[28:31], v[132:135], v[224:227], v[28:31]
	v_mfma_f32_16x16x32_bf16 v[24:27], v[166:169], v[224:227], v[24:27]
	v_mfma_f32_16x16x32_bf16 v[12:15], v[132:135], v[232:235], v[12:15]
	v_mfma_f32_16x16x32_bf16 v[8:11], v[166:169], v[232:235], v[8:11]
	v_mfma_f32_16x16x32_bf16 v[52:55], v[176:179], v[204:207], v[52:55]
	v_mfma_f32_16x16x32_bf16 v[48:51], v[196:199], v[204:207], v[48:51]
	v_mfma_f32_16x16x32_bf16 v[36:39], v[176:179], v[212:215], v[36:39]
	v_mfma_f32_16x16x32_bf16 v[32:35], v[196:199], v[212:215], v[32:35]
	v_mfma_f32_16x16x32_bf16 v[20:23], v[176:179], v[220:223], v[20:23]
	v_mfma_f32_16x16x32_bf16 v[16:19], v[196:199], v[220:223], v[16:19]
	v_mfma_f32_16x16x32_bf16 v[4:7], v[176:179], v[228:231], v[4:7]
	v_mfma_f32_16x16x32_bf16 v[0:3], v[196:199], v[228:231], v[0:3]
	v_mfma_f32_16x16x32_bf16 v[52:55], v[192:195], v[208:211], v[52:55]
	v_mfma_f32_16x16x32_bf16 v[48:51], v[200:203], v[208:211], v[48:51]
	v_mfma_f32_16x16x32_bf16 v[36:39], v[192:195], v[216:219], v[36:39]
	v_mfma_f32_16x16x32_bf16 v[32:35], v[200:203], v[216:219], v[32:35]
	v_mfma_f32_16x16x32_bf16 v[20:23], v[192:195], v[224:227], v[20:23]
	v_mfma_f32_16x16x32_bf16 v[16:19], v[200:203], v[224:227], v[16:19]
	v_mfma_f32_16x16x32_bf16 v[4:7], v[192:195], v[232:235], v[4:7]
	v_mfma_f32_16x16x32_bf16 v[0:3], v[200:203], v[232:235], v[0:3]
	s_barrier
	s_add_i32 s9, 0, 0x18000
	s_add_i32 s12, 0, 0x1c000
	v_add_u32_e32 v166, s9, v173
	v_add_u32_e32 v175, s12, v173
	ds_read_b128 v[124:127], v166
	ds_read_b128 v[132:135], v166 offset:1024
	ds_read_b128 v[162:165], v166 offset:2048
	ds_read_b128 v[166:169], v166 offset:3072
	ds_read_b128 v[176:179], v175
	ds_read_b128 v[192:195], v175 offset:1024
	ds_read_b128 v[196:199], v175 offset:2048
	ds_read_b128 v[200:203], v175 offset:3072
	s_add_u32 s10, s24, 0x80000
	s_addc_u32 s11, s25, 0
	s_mov_b32 m0, s31
	v_lshl_add_u64 v[240:241], s[10:11], 0, v[140:141]
	ds_read_b128 v[204:207], v174 offset:32768
	ds_read_b128 v[208:211], v174 offset:33792
	ds_read_b128 v[212:215], v174 offset:34816
	ds_read_b128 v[216:219], v174 offset:35840
	ds_read_b128 v[220:223], v174 offset:36864
	ds_read_b128 v[224:227], v174 offset:37888
	ds_read_b128 v[228:231], v174 offset:38912
	ds_read_b128 v[232:235], v174 offset:39936
	global_load_lds_dwordx4 v[240:241], off
	v_lshl_add_u64 v[240:241], s[10:11], 0, v[138:139]
	s_mov_b32 m0, s34
	s_nop 0
	global_load_lds_dwordx4 v[240:241], off
	s_waitcnt vmcnt(8)
	s_waitcnt lgkmcnt(0)
	s_barrier
	v_mfma_f32_16x16x32_bf16 v[128:131], v[124:127], v[204:207], v[128:131]
	v_mfma_f32_16x16x32_bf16 v[120:123], v[162:165], v[204:207], v[120:123]
	v_mfma_f32_16x16x32_bf16 v[108:111], v[124:127], v[212:215], v[108:111]
	v_mfma_f32_16x16x32_bf16 v[104:107], v[162:165], v[212:215], v[104:107]
	v_mfma_f32_16x16x32_bf16 v[92:95], v[124:127], v[220:223], v[92:95]
	v_mfma_f32_16x16x32_bf16 v[88:91], v[162:165], v[220:223], v[88:91]
	v_mfma_f32_16x16x32_bf16 v[76:79], v[124:127], v[228:231], v[76:79]
	v_mfma_f32_16x16x32_bf16 v[72:75], v[162:165], v[228:231], v[72:75]
	v_mfma_f32_16x16x32_bf16 v[128:131], v[132:135], v[208:211], v[128:131]
	v_mfma_f32_16x16x32_bf16 v[120:123], v[166:169], v[208:211], v[120:123]
	v_mfma_f32_16x16x32_bf16 v[108:111], v[132:135], v[216:219], v[108:111]
	v_mfma_f32_16x16x32_bf16 v[104:107], v[166:169], v[216:219], v[104:107]
	v_mfma_f32_16x16x32_bf16 v[92:95], v[132:135], v[224:227], v[92:95]
	v_mfma_f32_16x16x32_bf16 v[88:91], v[166:169], v[224:227], v[88:91]
	v_mfma_f32_16x16x32_bf16 v[76:79], v[132:135], v[232:235], v[76:79]
	v_mfma_f32_16x16x32_bf16 v[72:75], v[166:169], v[232:235], v[72:75]
	v_mfma_f32_16x16x32_bf16 v[116:119], v[176:179], v[204:207], v[116:119]
	v_mfma_f32_16x16x32_bf16 v[112:115], v[196:199], v[204:207], v[112:115]
	v_mfma_f32_16x16x32_bf16 v[100:103], v[176:179], v[212:215], v[100:103]
	v_mfma_f32_16x16x32_bf16 v[96:99], v[196:199], v[212:215], v[96:99]
	v_mfma_f32_16x16x32_bf16 v[84:87], v[176:179], v[220:223], v[84:87]
	v_mfma_f32_16x16x32_bf16 v[80:83], v[196:199], v[220:223], v[80:83]
	v_mfma_f32_16x16x32_bf16 v[68:71], v[176:179], v[228:231], v[68:71]
	v_mfma_f32_16x16x32_bf16 v[64:67], v[196:199], v[228:231], v[64:67]
	v_mfma_f32_16x16x32_bf16 v[116:119], v[192:195], v[208:211], v[116:119]
	v_mfma_f32_16x16x32_bf16 v[112:115], v[200:203], v[208:211], v[112:115]
	v_mfma_f32_16x16x32_bf16 v[100:103], v[192:195], v[216:219], v[100:103]
	v_mfma_f32_16x16x32_bf16 v[96:99], v[200:203], v[216:219], v[96:99]
	v_mfma_f32_16x16x32_bf16 v[84:87], v[192:195], v[224:227], v[84:87]
	v_mfma_f32_16x16x32_bf16 v[80:83], v[200:203], v[224:227], v[80:83]
	v_mfma_f32_16x16x32_bf16 v[68:71], v[192:195], v[232:235], v[68:71]
	v_mfma_f32_16x16x32_bf16 v[64:67], v[200:203], v[232:235], v[64:67]
	s_barrier
; #define PG8_STAGE(bufoff, gbase, voff) do { _Pragma("unroll") for (int _i = 0; _i < 2; ++_i) \
;         __builtin_amdgcn_global_load_lds((const unsigned*)((const char*)(gbase) + (voff)[_i]), (LAS unsigned*)(lds + (bufoff) + ldsw + _i * 8192), 16, 0, 0); } while (0)
; #define PG8_LDA(dst, b, h) do { _Pragma("unroll") for (int m = 0; m < 4; ++m) _Pragma("unroll") for (int k = 0; k < 2; ++k) dst[m][k] = *(const LAS bf16x8*)(lds + PG8_SA(b, h) + aoff + m * 2048 + k * 1024); } while (0)
; #define PG8_MMA(ai, bj, At, Bt) do { __builtin_amdgcn_s_setprio(1); _Pragma("unroll") for (int m = 0; m < 4; ++m) _Pragma("unroll") for (int n = 0; n < 2; ++n) _Pragma("unroll") for (int k = 0; k < 2; ++k) \
;         acc[ai][bj][m][n] = __builtin_amdgcn_mfma_f32_16x16x32_bf16(Bt[n][k], At[m][k], acc[ai][bj][m][n], 0, 0, 0); __builtin_amdgcn_s_setprio(0); } while (0)
; #define PG8_WAIT_V(n) asm volatile("s_waitcnt vmcnt(" #n ")" ::: "memory")
; #define PG8_WAIT_L(n) asm volatile("s_waitcnt lgkmcnt(" #n ")" ::: "memory")
; #define PG8_BAR __builtin_amdgcn_s_barrier()
; #define PG8_SCHED __builtin_amdgcn_sched_barrier(0)
; template <class Epi, class Map>
; __device__ __forceinline__ void gemm_phase(LAS unsigned char* lds, const Gemm g, const Sched<Map>& S, const Epi& E) {
;     ...
;             PG8_LDA(At, 1, 1); PG8_STAGE(PG8_SB(1, 0), b3, voffB); PG8_STAGE(PG8_SB(1, 1), b3 + hstepB, voffB); PG8_STAGE(PG8_SA(1, 0), a3, voffA);
;             PG8_WAIT_V(8); PG8_WAIT_L(0); PG8_BAR; PG8_MMA(1, 0, At, B0); PG8_MMA(1, 1, At, B1); PG8_BAR; PG8_SCHED;
;         }
	s_add_i32 s9, s9, s28
	v_lshl_add_u64 v[170:171], v[170:171], 0, s[82:83]
	s_mov_b32 m0, s9
	ds_read_b128 v[204:207], v174 offset:49152
	ds_read_b128 v[208:211], v174 offset:50176
	ds_read_b128 v[212:215], v174 offset:51200
	ds_read_b128 v[216:219], v174 offset:52224
	ds_read_b128 v[220:223], v174 offset:53248
	ds_read_b128 v[224:227], v174 offset:54272
	ds_read_b128 v[228:231], v174 offset:55296
	ds_read_b128 v[232:235], v174 offset:56320
	global_load_lds_dwordx4 v[170:171], off
	s_add_i32 m0, s9, 0x2000
	s_add_u32 s10, s20, 0x80080
	v_lshl_add_u64 v[170:171], v[180:181], 0, s[82:83]
	s_addc_u32 s11, s21, 0
	s_add_i32 s9, s12, s28
	global_load_lds_dwordx4 v[170:171], off
	v_lshl_add_u64 v[170:171], s[10:11], 0, v[144:145]
	s_mov_b32 m0, s9
	s_nop 0
	global_load_lds_dwordx4 v[170:171], off
	v_lshl_add_u64 v[170:171], s[10:11], 0, v[136:137]
	s_add_i32 m0, s9, 0x2000
	s_nop 0
	global_load_lds_dwordx4 v[170:171], off
	v_lshl_add_u64 v[170:171], v[236:237], 0, s[82:83]
	s_mov_b32 m0, s36
	s_nop 0
	global_load_lds_dwordx4 v[170:171], off
	v_lshl_add_u64 v[170:171], v[238:239], 0, s[82:83]
	s_mov_b32 m0, s37
	s_nop 0
	global_load_lds_dwordx4 v[170:171], off
	s_waitcnt vmcnt(8)
	s_waitcnt lgkmcnt(0)
	s_barrier
	v_mfma_f32_16x16x32_bf16 v[60:63], v[124:127], v[204:207], v[60:63]
	v_mfma_f32_16x16x32_bf16 v[56:59], v[162:165], v[204:207], v[56:59]
	v_mfma_f32_16x16x32_bf16 v[44:47], v[124:127], v[212:215], v[44:47]
	v_mfma_f32_16x16x32_bf16 v[40:43], v[162:165], v[212:215], v[40:43]
	v_mfma_f32_16x16x32_bf16 v[28:31], v[124:127], v[220:223], v[28:31]
	v_mfma_f32_16x16x32_bf16 v[24:27], v[162:165], v[220:223], v[24:27]
	v_mfma_f32_16x16x32_bf16 v[12:15], v[124:127], v[228:231], v[12:15]
	v_mfma_f32_16x16x32_bf16 v[8:11], v[162:165], v[228:231], v[8:11]
	v_mfma_f32_16x16x32_bf16 v[60:63], v[132:135], v[208:211], v[60:63]
	v_mfma_f32_16x16x32_bf16 v[56:59], v[166:169], v[208:211], v[56:59]
	v_mfma_f32_16x16x32_bf16 v[44:47], v[132:135], v[216:219], v[44:47]
	v_mfma_f32_16x16x32_bf16 v[40:43], v[166:169], v[216:219], v[40:43]
	v_mfma_f32_16x16x32_bf16 v[28:31], v[132:135], v[224:227], v[28:31]
	v_mfma_f32_16x16x32_bf16 v[24:27], v[166:169], v[224:227], v[24:27]
	v_mfma_f32_16x16x32_bf16 v[12:15], v[132:135], v[232:235], v[12:15]
	v_mfma_f32_16x16x32_bf16 v[8:11], v[166:169], v[232:235], v[8:11]
	v_mfma_f32_16x16x32_bf16 v[52:55], v[176:179], v[204:207], v[52:55]
	v_mfma_f32_16x16x32_bf16 v[48:51], v[196:199], v[204:207], v[48:51]
	v_mfma_f32_16x16x32_bf16 v[36:39], v[176:179], v[212:215], v[36:39]
	v_mfma_f32_16x16x32_bf16 v[32:35], v[196:199], v[212:215], v[32:35]
	v_mfma_f32_16x16x32_bf16 v[20:23], v[176:179], v[220:223], v[20:23]
	v_mfma_f32_16x16x32_bf16 v[16:19], v[196:199], v[220:223], v[16:19]
	v_mfma_f32_16x16x32_bf16 v[4:7], v[176:179], v[228:231], v[4:7]
	v_mfma_f32_16x16x32_bf16 v[0:3], v[196:199], v[228:231], v[0:3]
	v_mfma_f32_16x16x32_bf16 v[52:55], v[192:195], v[208:211], v[52:55]
	v_mfma_f32_16x16x32_bf16 v[48:51], v[200:203], v[208:211], v[48:51]
	v_mfma_f32_16x16x32_bf16 v[36:39], v[192:195], v[216:219], v[36:39]
	v_mfma_f32_16x16x32_bf16 v[32:35], v[200:203], v[216:219], v[32:35]
	v_mfma_f32_16x16x32_bf16 v[20:23], v[192:195], v[224:227], v[20:23]
	v_mfma_f32_16x16x32_bf16 v[16:19], v[200:203], v[224:227], v[16:19]
	v_mfma_f32_16x16x32_bf16 v[4:7], v[192:195], v[232:235], v[4:7]
	v_mfma_f32_16x16x32_bf16 v[0:3], v[200:203], v[232:235], v[0:3]
	s_barrier
	s_add_i32 s8, s8, 2
	s_add_u32 s18, s18, 0x100
	s_addc_u32 s19, s19, 0
	s_add_u32 s6, s6, 0x100
	s_addc_u32 s7, s7, 0
	s_cmp_gt_u32 s8, 29
	s_cbranch_scc0 .LBB0_880
	s_and_b64 vcc, exec, s[44:45]
	s_cbranch_vccz .LBB0_883

; #define PG8_STAGE(bufoff, gbase, voff) do { _Pragma("unroll") for (int _i = 0; _i < 2; ++_i) \
;         __builtin_amdgcn_global_load_lds((const unsigned*)((const char*)(gbase) + (voff)[_i]), (LAS unsigned*)(lds + (bufoff) + ldsw + _i * 8192), 16, 0, 0); } while (0)
; #define PG8_LDA(dst, b, h) do { _Pragma("unroll") for (int m = 0; m < 4; ++m) _Pragma("unroll") for (int k = 0; k < 2; ++k) dst[m][k] = *(const LAS bf16x8*)(lds + PG8_SA(b, h) + aoff + m * 2048 + k * 1024); } while (0)
; #define PG8_LDB(dst, b, h) do { _Pragma("unroll") for (int n = 0; n < 2; ++n) _Pragma("unroll") for (int k = 0; k < 2; ++k) dst[n][k] = *(const LAS bf16x8*)(lds + PG8_SB(b, h) + boff + n * 2048 + k * 1024); } while (0)
; #define PG8_MMA(ai, bj, At, Bt) do { __builtin_amdgcn_s_setprio(1); _Pragma("unroll") for (int m = 0; m < 4; ++m) _Pragma("unroll") for (int n = 0; n < 2; ++n) _Pragma("unroll") for (int k = 0; k < 2; ++k) \
;         acc[ai][bj][m][n] = __builtin_amdgcn_mfma_f32_16x16x32_bf16(Bt[n][k], At[m][k], acc[ai][bj][m][n], 0, 0, 0); __builtin_amdgcn_s_setprio(0); } while (0)
; #define PG8_WAIT_V(n) asm volatile("s_waitcnt vmcnt(" #n ")" ::: "memory")
; #define PG8_WAIT_L(n) asm volatile("s_waitcnt lgkmcnt(" #n ")" ::: "memory")
; #define PG8_BAR __builtin_amdgcn_s_barrier()
; #define PG8_SCHED __builtin_amdgcn_sched_barrier(0)
; template <class Epi, class Map>
; __device__ __forceinline__ void gemm_phase(LAS unsigned char* lds, const Gemm g, const Sched<Map>& S, const Epi& E) {
;     ...
;         for (int t = 0; t < nt; t += 2) {
;             const bool last = (t == nt - 2);
;             const char* a1 = cA + (size_t)(t + 1) * kstep;
;             const char* a2 = last ? nA : cA + (size_t)(t + 2) * kstep; const char* b2 = last ? nB : cB + (size_t)(t + 2) * kstep;
;             const char* a3 = a2 + kstep; const char* b3 = b2 + kstep;
;             PG8_LDB(B0, 0, 0); PG8_LDB(B1, 0, 1); PG8_SCHED; PG8_LDA(At, 0, 0); PG8_STAGE(PG8_SA(1, 1), a1 + hstepA, voffA);
;             PG8_WAIT_V(8); PG8_WAIT_L(0); PG8_BAR; PG8_MMA(0, 0, At, B0); PG8_MMA(0, 1, At, B1); PG8_BAR; PG8_SCHED;
;             PG8_LDA(At, 0, 1); PG8_STAGE(PG8_SB(0, 0), b2, voffB); PG8_STAGE(PG8_SB(0, 1), b2 + hstepB, voffB); PG8_STAGE(PG8_SA(0, 0), a2, voffA);
;             PG8_WAIT_V(8); PG8_WAIT_L(0); PG8_BAR; PG8_MMA(1, 0, At, B0); PG8_MMA(1, 1, At, B1); PG8_BAR; PG8_SCHED;
.LBB0_952:
	s_add_u32 s40, s36, 0xfff00080
	s_addc_u32 s41, s37, -1
	s_add_i32 s50, 0, 0x10000
	s_cmp_eq_u32 s49, 60
	s_cselect_b32 s43, s33, s41
	s_cselect_b32 s42, s44, s40
	s_cselect_b32 s41, s45, s48
	s_cselect_b32 s40, s46, s47
	s_add_i32 s52, 0, 0x14000
	v_add_u32_e32 v108, s50, v173
	v_add_u32_e32 v170, s52, v173
	ds_read_b128 v[64:67], v108
	ds_read_b128 v[68:71], v108 offset:1024
	ds_read_b128 v[72:75], v108 offset:2048
	ds_read_b128 v[108:111], v108 offset:3072
	ds_read_b128 v[166:169], v170
	ds_read_b128 v[176:179], v170 offset:1024
	ds_read_b128 v[192:195], v170 offset:2048
	ds_read_b128 v[196:199], v170 offset:3072
	v_lshl_add_u64 v[170:171], s[36:37], 0, v[162:163]
	s_add_i32 m0, s1, 0xc000
	ds_read_b128 v[200:203], v174
	ds_read_b128 v[204:207], v174 offset:1024
	ds_read_b128 v[208:211], v174 offset:2048
	ds_read_b128 v[212:215], v174 offset:3072
	ds_read_b128 v[216:219], v174 offset:4096
	ds_read_b128 v[220:223], v174 offset:5120
	ds_read_b128 v[224:227], v174 offset:6144
	ds_read_b128 v[228:231], v174 offset:7168
	global_load_lds_dwordx4 v[170:171], off
	v_lshl_add_u64 v[170:171], s[36:37], 0, v[164:165]
	s_add_i32 m0, s1, 0xe000
	s_nop 0
	global_load_lds_dwordx4 v[170:171], off
	s_waitcnt vmcnt(8)
	s_waitcnt lgkmcnt(0)
	s_barrier
	v_mfma_f32_16x16x32_bf16 v[140:143], v[64:67], v[200:203], v[140:143]
	v_mfma_f32_16x16x32_bf16 v[136:139], v[72:75], v[200:203], v[136:139]
	v_mfma_f32_16x16x32_bf16 v[132:135], v[64:67], v[208:211], v[132:135]
	v_mfma_f32_16x16x32_bf16 v[128:131], v[72:75], v[208:211], v[128:131]
	v_mfma_f32_16x16x32_bf16 v[104:107], v[64:67], v[216:219], v[104:107]
	v_mfma_f32_16x16x32_bf16 v[100:103], v[72:75], v[216:219], v[100:103]
	v_mfma_f32_16x16x32_bf16 v[96:99], v[64:67], v[224:227], v[96:99]
	v_mfma_f32_16x16x32_bf16 v[92:95], v[72:75], v[224:227], v[92:95]
	v_mfma_f32_16x16x32_bf16 v[140:143], v[68:71], v[204:207], v[140:143]
	v_mfma_f32_16x16x32_bf16 v[136:139], v[108:111], v[204:207], v[136:139]
	v_mfma_f32_16x16x32_bf16 v[132:135], v[68:71], v[212:215], v[132:135]
	v_mfma_f32_16x16x32_bf16 v[128:131], v[108:111], v[212:215], v[128:131]
	v_mfma_f32_16x16x32_bf16 v[104:107], v[68:71], v[220:223], v[104:107]
	v_mfma_f32_16x16x32_bf16 v[100:103], v[108:111], v[220:223], v[100:103]
	v_mfma_f32_16x16x32_bf16 v[96:99], v[68:71], v[228:231], v[96:99]
	v_mfma_f32_16x16x32_bf16 v[92:95], v[108:111], v[228:231], v[92:95]
	v_mfma_f32_16x16x32_bf16 v[124:127], v[166:169], v[200:203], v[124:127]
	v_mfma_f32_16x16x32_bf16 v[120:123], v[192:195], v[200:203], v[120:123]
	v_mfma_f32_16x16x32_bf16 v[116:119], v[166:169], v[208:211], v[116:119]
	v_mfma_f32_16x16x32_bf16 v[112:115], v[192:195], v[208:211], v[112:115]
	v_mfma_f32_16x16x32_bf16 v[88:91], v[166:169], v[216:219], v[88:91]
	v_mfma_f32_16x16x32_bf16 v[84:87], v[192:195], v[216:219], v[84:87]
	v_mfma_f32_16x16x32_bf16 v[80:83], v[166:169], v[224:227], v[80:83]
	v_mfma_f32_16x16x32_bf16 v[76:79], v[192:195], v[224:227], v[76:79]
	v_mfma_f32_16x16x32_bf16 v[124:127], v[176:179], v[204:207], v[124:127]
	v_mfma_f32_16x16x32_bf16 v[120:123], v[196:199], v[204:207], v[120:123]
	v_mfma_f32_16x16x32_bf16 v[116:119], v[176:179], v[212:215], v[116:119]
	v_mfma_f32_16x16x32_bf16 v[112:115], v[196:199], v[212:215], v[112:115]
	v_mfma_f32_16x16x32_bf16 v[88:91], v[176:179], v[220:223], v[88:91]
	v_mfma_f32_16x16x32_bf16 v[84:87], v[196:199], v[220:223], v[84:87]
	v_mfma_f32_16x16x32_bf16 v[80:83], v[176:179], v[228:231], v[80:83]
	v_mfma_f32_16x16x32_bf16 v[76:79], v[196:199], v[228:231], v[76:79]
	s_barrier
	s_add_i32 s50, s50, s0
	v_lshl_add_u64 v[170:171], s[40:41], 0, v[144:145]
	s_mov_b32 m0, s50
	ds_read_b128 v[200:203], v174 offset:16384
	ds_read_b128 v[204:207], v174 offset:17408
	ds_read_b128 v[208:211], v174 offset:18432
	ds_read_b128 v[212:215], v174 offset:19456
	ds_read_b128 v[216:219], v174 offset:20480
	ds_read_b128 v[220:223], v174 offset:21504
	ds_read_b128 v[224:227], v174 offset:22528
	ds_read_b128 v[228:231], v174 offset:23552
	global_load_lds_dwordx4 v[170:171], off
	s_add_i32 m0, s50, 0x2000
	s_add_u32 s50, s40, 0x100000
	v_lshl_add_u64 v[180:181], s[40:41], 0, v[160:161]
	s_addc_u32 s51, s41, 0
	s_add_i32 s52, s52, s0
	global_load_lds_dwordx4 v[180:181], off
	v_lshl_add_u64 v[232:233], s[50:51], 0, v[144:145]
	s_mov_b32 m0, s52
	v_lshl_add_u64 v[234:235], s[42:43], 0, v[160:161]
	global_load_lds_dwordx4 v[232:233], off
	v_lshl_add_u64 v[232:233], s[50:51], 0, v[160:161]
	s_add_i32 m0, s52, 0x2000
	s_nop 0
	global_load_lds_dwordx4 v[232:233], off
	v_lshl_add_u64 v[232:233], s[42:43], 0, v[144:145]
	s_mov_b32 m0, s1
	s_nop 0
	global_load_lds_dwordx4 v[232:233], off
	s_mov_b32 m0, s2
	s_nop 0
	global_load_lds_dwordx4 v[234:235], off
	s_waitcnt vmcnt(8)
	s_waitcnt lgkmcnt(0)
	s_barrier
; #define PG8_STAGE(bufoff, gbase, voff) do { _Pragma("unroll") for (int _i = 0; _i < 2; ++_i) \
;         __builtin_amdgcn_global_load_lds((const unsigned*)((const char*)(gbase) + (voff)[_i]), (LAS unsigned*)(lds + (bufoff) + ldsw + _i * 8192), 16, 0, 0); } while (0)
; #define PG8_LDA(dst, b, h) do { _Pragma("unroll") for (int m = 0; m < 4; ++m) _Pragma("unroll") for (int k = 0; k < 2; ++k) dst[m][k] = *(const LAS bf16x8*)(lds + PG8_SA(b, h) + aoff + m * 2048 + k * 1024); } while (0)
; #define PG8_LDB(dst, b, h) do { _Pragma("unroll") for (int n = 0; n < 2; ++n) _Pragma("unroll") for (int k = 0; k < 2; ++k) dst[n][k] = *(const LAS bf16x8*)(lds + PG8_SB(b, h) + boff + n * 2048 + k * 1024); } while (0)
; #define PG8_MMA(ai, bj, At, Bt) do { __builtin_amdgcn_s_setprio(1); _Pragma("unroll") for (int m = 0; m < 4; ++m) _Pragma("unroll") for (int n = 0; n < 2; ++n) _Pragma("unroll") for (int k = 0; k < 2; ++k) \
;         acc[ai][bj][m][n] = __builtin_amdgcn_mfma_f32_16x16x32_bf16(Bt[n][k], At[m][k], acc[ai][bj][m][n], 0, 0, 0); __builtin_amdgcn_s_setprio(0); } while (0)
; #define PG8_WAIT_V(n) asm volatile("s_waitcnt vmcnt(" #n ")" ::: "memory")
; #define PG8_WAIT_L(n) asm volatile("s_waitcnt lgkmcnt(" #n ")" ::: "memory")
; #define PG8_BAR __builtin_amdgcn_s_barrier()
; #define PG8_SCHED __builtin_amdgcn_sched_barrier(0)
; template <class Epi, class Map>
; __device__ __forceinline__ void gemm_phase(LAS unsigned char* lds, const Gemm g, const Sched<Map>& S, const Epi& E) {
;     ...
;             PG8_WAIT_V(8); PG8_WAIT_L(0); PG8_BAR; PG8_MMA(1, 0, At, B0); PG8_MMA(1, 1, At, B1); PG8_BAR; PG8_SCHED;
;             PG8_LDB(B0, 1, 0); PG8_LDB(B1, 1, 1); PG8_SCHED; PG8_LDA(At, 1, 0); PG8_STAGE(PG8_SA(0, 1), a2 + hstepA, voffA);
;             PG8_WAIT_V(8); PG8_WAIT_L(0); PG8_BAR; PG8_MMA(0, 0, At, B0); PG8_MMA(0, 1, At, B1); PG8_BAR; PG8_SCHED;
	v_mfma_f32_16x16x32_bf16 v[60:63], v[64:67], v[200:203], v[60:63]
	v_mfma_f32_16x16x32_bf16 v[56:59], v[72:75], v[200:203], v[56:59]
	v_mfma_f32_16x16x32_bf16 v[52:55], v[64:67], v[208:211], v[52:55]
	v_mfma_f32_16x16x32_bf16 v[48:51], v[72:75], v[208:211], v[48:51]
	v_mfma_f32_16x16x32_bf16 v[28:31], v[64:67], v[216:219], v[28:31]
	v_mfma_f32_16x16x32_bf16 v[24:27], v[72:75], v[216:219], v[24:27]
	v_mfma_f32_16x16x32_bf16 v[20:23], v[64:67], v[224:227], v[20:23]
	v_mfma_f32_16x16x32_bf16 v[8:11], v[72:75], v[224:227], v[8:11]
	v_mfma_f32_16x16x32_bf16 v[60:63], v[68:71], v[204:207], v[60:63]
	v_mfma_f32_16x16x32_bf16 v[56:59], v[108:111], v[204:207], v[56:59]
	v_mfma_f32_16x16x32_bf16 v[52:55], v[68:71], v[212:215], v[52:55]
	v_mfma_f32_16x16x32_bf16 v[48:51], v[108:111], v[212:215], v[48:51]
	v_mfma_f32_16x16x32_bf16 v[28:31], v[68:71], v[220:223], v[28:31]
	v_mfma_f32_16x16x32_bf16 v[24:27], v[108:111], v[220:223], v[24:27]
	v_mfma_f32_16x16x32_bf16 v[20:23], v[68:71], v[228:231], v[20:23]
	v_mfma_f32_16x16x32_bf16 v[8:11], v[108:111], v[228:231], v[8:11]
	v_mfma_f32_16x16x32_bf16 v[44:47], v[166:169], v[200:203], v[44:47]
	v_mfma_f32_16x16x32_bf16 v[40:43], v[192:195], v[200:203], v[40:43]
	v_mfma_f32_16x16x32_bf16 v[36:39], v[166:169], v[208:211], v[36:39]
	v_mfma_f32_16x16x32_bf16 v[32:35], v[192:195], v[208:211], v[32:35]
	v_mfma_f32_16x16x32_bf16 v[16:19], v[166:169], v[216:219], v[16:19]
	v_mfma_f32_16x16x32_bf16 v[12:15], v[192:195], v[216:219], v[12:15]
	v_mfma_f32_16x16x32_bf16 v[4:7], v[166:169], v[224:227], v[4:7]
	v_mfma_f32_16x16x32_bf16 v[0:3], v[192:195], v[224:227], v[0:3]
	v_mfma_f32_16x16x32_bf16 v[44:47], v[176:179], v[204:207], v[44:47]
	v_mfma_f32_16x16x32_bf16 v[40:43], v[196:199], v[204:207], v[40:43]
	v_mfma_f32_16x16x32_bf16 v[36:39], v[176:179], v[212:215], v[36:39]
	v_mfma_f32_16x16x32_bf16 v[32:35], v[196:199], v[212:215], v[32:35]
	v_mfma_f32_16x16x32_bf16 v[16:19], v[176:179], v[220:223], v[16:19]
	v_mfma_f32_16x16x32_bf16 v[12:15], v[196:199], v[220:223], v[12:15]
	v_mfma_f32_16x16x32_bf16 v[4:7], v[176:179], v[228:231], v[4:7]
	v_mfma_f32_16x16x32_bf16 v[0:3], v[196:199], v[228:231], v[0:3]
	s_barrier
	s_add_i32 s50, 0, 0x18000
	s_add_i32 s51, 0, 0x1c000
	v_add_u32_e32 v108, s50, v173
	v_add_u32_e32 v175, s51, v173
	ds_read_b128 v[64:67], v108
	ds_read_b128 v[68:71], v108 offset:1024
	ds_read_b128 v[72:75], v108 offset:2048
	ds_read_b128 v[108:111], v108 offset:3072
	ds_read_b128 v[166:169], v175
	ds_read_b128 v[176:179], v175 offset:1024
	ds_read_b128 v[192:195], v175 offset:2048
	ds_read_b128 v[196:199], v175 offset:3072
	s_add_u32 s42, s42, 0x100000
	s_addc_u32 s43, s43, 0
	s_mov_b32 m0, s3
	v_lshl_add_u64 v[236:237], s[42:43], 0, v[144:145]
	ds_read_b128 v[200:203], v174 offset:32768
	ds_read_b128 v[204:207], v174 offset:33792
	ds_read_b128 v[208:211], v174 offset:34816
	ds_read_b128 v[212:215], v174 offset:35840
	ds_read_b128 v[216:219], v174 offset:36864
	ds_read_b128 v[220:223], v174 offset:37888
	ds_read_b128 v[224:227], v174 offset:38912
	ds_read_b128 v[228:231], v174 offset:39936
	global_load_lds_dwordx4 v[236:237], off
	v_lshl_add_u64 v[236:237], s[42:43], 0, v[160:161]
	s_mov_b32 m0, s4
	s_nop 0
	global_load_lds_dwordx4 v[236:237], off
	s_waitcnt vmcnt(8)
	s_waitcnt lgkmcnt(0)
	s_barrier
	v_mfma_f32_16x16x32_bf16 v[140:143], v[64:67], v[200:203], v[140:143]
	v_mfma_f32_16x16x32_bf16 v[136:139], v[72:75], v[200:203], v[136:139]
	v_mfma_f32_16x16x32_bf16 v[132:135], v[64:67], v[208:211], v[132:135]
	v_mfma_f32_16x16x32_bf16 v[128:131], v[72:75], v[208:211], v[128:131]
	v_mfma_f32_16x16x32_bf16 v[104:107], v[64:67], v[216:219], v[104:107]
	v_mfma_f32_16x16x32_bf16 v[100:103], v[72:75], v[216:219], v[100:103]
	v_mfma_f32_16x16x32_bf16 v[96:99], v[64:67], v[224:227], v[96:99]
	v_mfma_f32_16x16x32_bf16 v[92:95], v[72:75], v[224:227], v[92:95]
	v_mfma_f32_16x16x32_bf16 v[140:143], v[68:71], v[204:207], v[140:143]
	v_mfma_f32_16x16x32_bf16 v[136:139], v[108:111], v[204:207], v[136:139]
	v_mfma_f32_16x16x32_bf16 v[132:135], v[68:71], v[212:215], v[132:135]
	v_mfma_f32_16x16x32_bf16 v[128:131], v[108:111], v[212:215], v[128:131]
	v_mfma_f32_16x16x32_bf16 v[104:107], v[68:71], v[220:223], v[104:107]
	v_mfma_f32_16x16x32_bf16 v[100:103], v[108:111], v[220:223], v[100:103]
	v_mfma_f32_16x16x32_bf16 v[96:99], v[68:71], v[228:231], v[96:99]
	v_mfma_f32_16x16x32_bf16 v[92:95], v[108:111], v[228:231], v[92:95]
	v_mfma_f32_16x16x32_bf16 v[124:127], v[166:169], v[200:203], v[124:127]
	v_mfma_f32_16x16x32_bf16 v[120:123], v[192:195], v[200:203], v[120:123]
	v_mfma_f32_16x16x32_bf16 v[116:119], v[166:169], v[208:211], v[116:119]
	v_mfma_f32_16x16x32_bf16 v[112:115], v[192:195], v[208:211], v[112:115]
	v_mfma_f32_16x16x32_bf16 v[88:91], v[166:169], v[216:219], v[88:91]
	v_mfma_f32_16x16x32_bf16 v[84:87], v[192:195], v[216:219], v[84:87]
	v_mfma_f32_16x16x32_bf16 v[80:83], v[166:169], v[224:227], v[80:83]
	v_mfma_f32_16x16x32_bf16 v[76:79], v[192:195], v[224:227], v[76:79]
	v_mfma_f32_16x16x32_bf16 v[124:127], v[176:179], v[204:207], v[124:127]
	v_mfma_f32_16x16x32_bf16 v[120:123], v[196:199], v[204:207], v[120:123]
	v_mfma_f32_16x16x32_bf16 v[116:119], v[176:179], v[212:215], v[116:119]
	v_mfma_f32_16x16x32_bf16 v[112:115], v[196:199], v[212:215], v[112:115]
	v_mfma_f32_16x16x32_bf16 v[88:91], v[176:179], v[220:223], v[88:91]
	v_mfma_f32_16x16x32_bf16 v[84:87], v[196:199], v[220:223], v[84:87]
	v_mfma_f32_16x16x32_bf16 v[80:83], v[176:179], v[228:231], v[80:83]
	v_mfma_f32_16x16x32_bf16 v[76:79], v[196:199], v[228:231], v[76:79]
	s_barrier
; #define PG8_STAGE(bufoff, gbase, voff) do { _Pragma("unroll") for (int _i = 0; _i < 2; ++_i) \
;         __builtin_amdgcn_global_load_lds((const unsigned*)((const char*)(gbase) + (voff)[_i]), (LAS unsigned*)(lds + (bufoff) + ldsw + _i * 8192), 16, 0, 0); } while (0)
; #define PG8_LDA(dst, b, h) do { _Pragma("unroll") for (int m = 0; m < 4; ++m) _Pragma("unroll") for (int k = 0; k < 2; ++k) dst[m][k] = *(const LAS bf16x8*)(lds + PG8_SA(b, h) + aoff + m * 2048 + k * 1024); } while (0)
; #define PG8_MMA(ai, bj, At, Bt) do { __builtin_amdgcn_s_setprio(1); _Pragma("unroll") for (int m = 0; m < 4; ++m) _Pragma("unroll") for (int n = 0; n < 2; ++n) _Pragma("unroll") for (int k = 0; k < 2; ++k) \
;         acc[ai][bj][m][n] = __builtin_amdgcn_mfma_f32_16x16x32_bf16(Bt[n][k], At[m][k], acc[ai][bj][m][n], 0, 0, 0); __builtin_amdgcn_s_setprio(0); } while (0)
; #define PG8_WAIT_V(n) asm volatile("s_waitcnt vmcnt(" #n ")" ::: "memory")
; #define PG8_WAIT_L(n) asm volatile("s_waitcnt lgkmcnt(" #n ")" ::: "memory")
; #define PG8_BAR __builtin_amdgcn_s_barrier()
; #define PG8_SCHED __builtin_amdgcn_sched_barrier(0)
; template <class Epi, class Map>
; __device__ __forceinline__ void gemm_phase(LAS unsigned char* lds, const Gemm g, const Sched<Map>& S, const Epi& E) {
;     ...
;             PG8_LDA(At, 1, 1); PG8_STAGE(PG8_SB(1, 0), b3, voffB); PG8_STAGE(PG8_SB(1, 1), b3 + hstepB, voffB); PG8_STAGE(PG8_SA(1, 0), a3, voffA);
;             PG8_WAIT_V(8); PG8_WAIT_L(0); PG8_BAR; PG8_MMA(1, 0, At, B0); PG8_MMA(1, 1, At, B1); PG8_BAR; PG8_SCHED;
;         }
	s_add_i32 s42, s50, s0
	v_lshl_add_u64 v[170:171], v[170:171], 0, s[82:83]
	s_mov_b32 m0, s42
	ds_read_b128 v[200:203], v174 offset:49152
	ds_read_b128 v[204:207], v174 offset:50176
	ds_read_b128 v[208:211], v174 offset:51200
	ds_read_b128 v[212:215], v174 offset:52224
	ds_read_b128 v[216:219], v174 offset:53248
	ds_read_b128 v[220:223], v174 offset:54272
	ds_read_b128 v[224:227], v174 offset:55296
	ds_read_b128 v[228:231], v174 offset:56320
	global_load_lds_dwordx4 v[170:171], off
	s_add_i32 m0, s42, 0x2000
	s_add_u32 s40, s40, 0x100080
	v_lshl_add_u64 v[170:171], v[180:181], 0, s[82:83]
	s_addc_u32 s41, s41, 0
	s_add_i32 s42, s51, s0
	global_load_lds_dwordx4 v[170:171], off
	v_lshl_add_u64 v[170:171], s[40:41], 0, v[144:145]
	s_mov_b32 m0, s42
	s_nop 0
	global_load_lds_dwordx4 v[170:171], off
	v_lshl_add_u64 v[170:171], s[40:41], 0, v[160:161]
	s_add_i32 m0, s42, 0x2000
	s_nop 0
	global_load_lds_dwordx4 v[170:171], off
	v_lshl_add_u64 v[170:171], v[232:233], 0, s[82:83]
	s_mov_b32 m0, s7
	s_nop 0
	global_load_lds_dwordx4 v[170:171], off
	v_lshl_add_u64 v[170:171], v[234:235], 0, s[82:83]
	s_mov_b32 m0, s8
	s_nop 0
	global_load_lds_dwordx4 v[170:171], off
	s_waitcnt vmcnt(8)
	s_waitcnt lgkmcnt(0)
	s_barrier
	v_mfma_f32_16x16x32_bf16 v[60:63], v[64:67], v[200:203], v[60:63]
	v_mfma_f32_16x16x32_bf16 v[56:59], v[72:75], v[200:203], v[56:59]
	v_mfma_f32_16x16x32_bf16 v[52:55], v[64:67], v[208:211], v[52:55]
	v_mfma_f32_16x16x32_bf16 v[48:51], v[72:75], v[208:211], v[48:51]
	v_mfma_f32_16x16x32_bf16 v[28:31], v[64:67], v[216:219], v[28:31]
	v_mfma_f32_16x16x32_bf16 v[24:27], v[72:75], v[216:219], v[24:27]
	v_mfma_f32_16x16x32_bf16 v[20:23], v[64:67], v[224:227], v[20:23]
	v_mfma_f32_16x16x32_bf16 v[8:11], v[72:75], v[224:227], v[8:11]
	v_mfma_f32_16x16x32_bf16 v[60:63], v[68:71], v[204:207], v[60:63]
	v_mfma_f32_16x16x32_bf16 v[56:59], v[108:111], v[204:207], v[56:59]
	v_mfma_f32_16x16x32_bf16 v[52:55], v[68:71], v[212:215], v[52:55]
	v_mfma_f32_16x16x32_bf16 v[48:51], v[108:111], v[212:215], v[48:51]
	v_mfma_f32_16x16x32_bf16 v[28:31], v[68:71], v[220:223], v[28:31]
	v_mfma_f32_16x16x32_bf16 v[24:27], v[108:111], v[220:223], v[24:27]
	v_mfma_f32_16x16x32_bf16 v[20:23], v[68:71], v[228:231], v[20:23]
	v_mfma_f32_16x16x32_bf16 v[8:11], v[108:111], v[228:231], v[8:11]
	v_mfma_f32_16x16x32_bf16 v[44:47], v[166:169], v[200:203], v[44:47]
	v_mfma_f32_16x16x32_bf16 v[40:43], v[192:195], v[200:203], v[40:43]
	v_mfma_f32_16x16x32_bf16 v[36:39], v[166:169], v[208:211], v[36:39]
	v_mfma_f32_16x16x32_bf16 v[32:35], v[192:195], v[208:211], v[32:35]
	v_mfma_f32_16x16x32_bf16 v[16:19], v[166:169], v[216:219], v[16:19]
	v_mfma_f32_16x16x32_bf16 v[12:15], v[192:195], v[216:219], v[12:15]
	v_mfma_f32_16x16x32_bf16 v[4:7], v[166:169], v[224:227], v[4:7]
	v_mfma_f32_16x16x32_bf16 v[0:3], v[192:195], v[224:227], v[0:3]
	v_mfma_f32_16x16x32_bf16 v[44:47], v[176:179], v[204:207], v[44:47]
	v_mfma_f32_16x16x32_bf16 v[40:43], v[196:199], v[204:207], v[40:43]
	v_mfma_f32_16x16x32_bf16 v[36:39], v[176:179], v[212:215], v[36:39]
	v_mfma_f32_16x16x32_bf16 v[32:35], v[196:199], v[212:215], v[32:35]
	v_mfma_f32_16x16x32_bf16 v[16:19], v[176:179], v[220:223], v[16:19]
	v_mfma_f32_16x16x32_bf16 v[12:15], v[196:199], v[220:223], v[12:15]
	v_mfma_f32_16x16x32_bf16 v[4:7], v[176:179], v[228:231], v[4:7]
	v_mfma_f32_16x16x32_bf16 v[0:3], v[196:199], v[228:231], v[0:3]
	s_barrier
	s_add_i32 s49, s49, 2
	s_add_u32 s36, s36, 0x100
	s_addc_u32 s37, s37, 0
	s_add_u32 s47, s47, 0x100
	s_addc_u32 s48, s48, 0
	s_cmp_gt_u32 s49, 61
	s_cbranch_scc0 .LBB0_952
	s_and_b64 vcc, exec, s[28:29]
	s_cbranch_vccz .LBB0_955

; #define PG8_STAGE(bufoff, gbase, voff) do { _Pragma("unroll") for (int _i = 0; _i < 2; ++_i) \
;         __builtin_amdgcn_global_load_lds((const unsigned*)((const char*)(gbase) + (voff)[_i]), (LAS unsigned*)(lds + (bufoff) + ldsw + _i * 8192), 16, 0, 0); } while (0)
; #define PG8_LDA(dst, b, h) do { _Pragma("unroll") for (int m = 0; m < 4; ++m) _Pragma("unroll") for (int k = 0; k < 2; ++k) dst[m][k] = *(const LAS bf16x8*)(lds + PG8_SA(b, h) + aoff + m * 2048 + k * 1024); } while (0)
; #define PG8_LDB(dst, b, h) do { _Pragma("unroll") for (int n = 0; n < 2; ++n) _Pragma("unroll") for (int k = 0; k < 2; ++k) dst[n][k] = *(const LAS bf16x8*)(lds + PG8_SB(b, h) + boff + n * 2048 + k * 1024); } while (0)
; #define PG8_MMA(ai, bj, At, Bt) do { __builtin_amdgcn_s_setprio(1); _Pragma("unroll") for (int m = 0; m < 4; ++m) _Pragma("unroll") for (int n = 0; n < 2; ++n) _Pragma("unroll") for (int k = 0; k < 2; ++k) \
;         acc[ai][bj][m][n] = __builtin_amdgcn_mfma_f32_16x16x32_bf16(Bt[n][k], At[m][k], acc[ai][bj][m][n], 0, 0, 0); __builtin_amdgcn_s_setprio(0); } while (0)
; #define PG8_WAIT_V(n) asm volatile("s_waitcnt vmcnt(" #n ")" ::: "memory")
; #define PG8_WAIT_L(n) asm volatile("s_waitcnt lgkmcnt(" #n ")" ::: "memory")
; #define PG8_BAR __builtin_amdgcn_s_barrier()
; #define PG8_SCHED __builtin_amdgcn_sched_barrier(0)
; template <class Epi, class Map>
; __device__ __forceinline__ void gemm_phase(LAS unsigned char* lds, const Gemm g, const Sched<Map>& S, const Epi& E) {
;     ...
;         for (int t = 0; t < nt; t += 2) {
;             const bool last = (t == nt - 2);
;             const char* a1 = cA + (size_t)(t + 1) * kstep;
;             const char* a2 = last ? nA : cA + (size_t)(t + 2) * kstep; const char* b2 = last ? nB : cB + (size_t)(t + 2) * kstep;
;             const char* a3 = a2 + kstep; const char* b3 = b2 + kstep;
;             PG8_LDB(B0, 0, 0); PG8_LDB(B1, 0, 1); PG8_SCHED; PG8_LDA(At, 0, 0); PG8_STAGE(PG8_SA(1, 1), a1 + hstepA, voffA);
;             PG8_WAIT_V(8); PG8_WAIT_L(0); PG8_BAR; PG8_MMA(0, 0, At, B0); PG8_MMA(0, 1, At, B1); PG8_BAR; PG8_SCHED;
;             PG8_LDA(At, 0, 1); PG8_STAGE(PG8_SB(0, 0), b2, voffB); PG8_STAGE(PG8_SB(0, 1), b2 + hstepB, voffB); PG8_STAGE(PG8_SA(0, 0), a2, voffA);
;             PG8_WAIT_V(8); PG8_WAIT_L(0); PG8_BAR; PG8_MMA(1, 0, At, B0); PG8_MMA(1, 1, At, B1); PG8_BAR; PG8_SCHED;
.LBB0_1088:
	s_add_u32 s34, s30, 0xfff80080
	s_addc_u32 s35, s31, -1
	s_add_i32 s41, 0, 0x10000
	s_cmp_eq_u32 s40, 28
	s_cselect_b32 s37, s12, s35
	s_cselect_b32 s36, s13, s34
	v_add_u32_e32 v138, s41, v142
	s_cselect_b32 s35, s14, s33
	s_cselect_b32 s34, s15, s21
	s_add_i32 s46, 0, 0x14000
	ds_read_b128 v[160:163], v138
	ds_read_b128 v[164:167], v138 offset:1024
	ds_read_b128 v[168:171], v138 offset:2048
	ds_read_b128 v[172:175], v138 offset:3072
	v_add_u32_e32 v138, s46, v142
	ds_read_b128 v[176:179], v138
	ds_read_b128 v[192:195], v138 offset:1024
	ds_read_b128 v[196:199], v138 offset:2048
	ds_read_b128 v[200:203], v138 offset:3072
	v_lshl_add_u64 v[138:139], s[30:31], 0, v[134:135]
	s_add_i32 m0, s1, 0xc000
	ds_read_b128 v[204:207], v143
	ds_read_b128 v[208:211], v143 offset:1024
	ds_read_b128 v[212:215], v143 offset:2048
	ds_read_b128 v[216:219], v143 offset:3072
	ds_read_b128 v[220:223], v143 offset:4096
	ds_read_b128 v[224:227], v143 offset:5120
	ds_read_b128 v[228:231], v143 offset:6144
	ds_read_b128 v[232:235], v143 offset:7168
	global_load_lds_dwordx4 v[138:139], off
	v_lshl_add_u64 v[138:139], s[30:31], 0, v[136:137]
	s_add_i32 m0, s1, 0xe000
	s_nop 0
	global_load_lds_dwordx4 v[138:139], off
	s_waitcnt vmcnt(8)
	s_waitcnt lgkmcnt(0)
	s_barrier
	v_mfma_f32_16x16x32_bf16 v[124:127], v[160:163], v[204:207], v[124:127]
	v_mfma_f32_16x16x32_bf16 v[120:123], v[168:171], v[204:207], v[120:123]
	v_mfma_f32_16x16x32_bf16 v[108:111], v[160:163], v[212:215], v[108:111]
	v_mfma_f32_16x16x32_bf16 v[104:107], v[168:171], v[212:215], v[104:107]
	v_mfma_f32_16x16x32_bf16 v[92:95], v[160:163], v[220:223], v[92:95]
	v_mfma_f32_16x16x32_bf16 v[88:91], v[168:171], v[220:223], v[88:91]
	v_mfma_f32_16x16x32_bf16 v[76:79], v[160:163], v[228:231], v[76:79]
	v_mfma_f32_16x16x32_bf16 v[72:75], v[168:171], v[228:231], v[72:75]
	v_mfma_f32_16x16x32_bf16 v[124:127], v[164:167], v[208:211], v[124:127]
	v_mfma_f32_16x16x32_bf16 v[120:123], v[172:175], v[208:211], v[120:123]
	v_mfma_f32_16x16x32_bf16 v[108:111], v[164:167], v[216:219], v[108:111]
	v_mfma_f32_16x16x32_bf16 v[104:107], v[172:175], v[216:219], v[104:107]
	v_mfma_f32_16x16x32_bf16 v[92:95], v[164:167], v[224:227], v[92:95]
	v_mfma_f32_16x16x32_bf16 v[88:91], v[172:175], v[224:227], v[88:91]
	v_mfma_f32_16x16x32_bf16 v[76:79], v[164:167], v[232:235], v[76:79]
	v_mfma_f32_16x16x32_bf16 v[72:75], v[172:175], v[232:235], v[72:75]
	v_mfma_f32_16x16x32_bf16 v[116:119], v[176:179], v[204:207], v[116:119]
	v_mfma_f32_16x16x32_bf16 v[112:115], v[196:199], v[204:207], v[112:115]
	v_mfma_f32_16x16x32_bf16 v[100:103], v[176:179], v[212:215], v[100:103]
	v_mfma_f32_16x16x32_bf16 v[96:99], v[196:199], v[212:215], v[96:99]
	v_mfma_f32_16x16x32_bf16 v[84:87], v[176:179], v[220:223], v[84:87]
	v_mfma_f32_16x16x32_bf16 v[80:83], v[196:199], v[220:223], v[80:83]
	v_mfma_f32_16x16x32_bf16 v[68:71], v[176:179], v[228:231], v[68:71]
	v_mfma_f32_16x16x32_bf16 v[64:67], v[196:199], v[228:231], v[64:67]
	v_mfma_f32_16x16x32_bf16 v[116:119], v[192:195], v[208:211], v[116:119]
	v_mfma_f32_16x16x32_bf16 v[112:115], v[200:203], v[208:211], v[112:115]
	v_mfma_f32_16x16x32_bf16 v[100:103], v[192:195], v[216:219], v[100:103]
	v_mfma_f32_16x16x32_bf16 v[96:99], v[200:203], v[216:219], v[96:99]
	v_mfma_f32_16x16x32_bf16 v[84:87], v[192:195], v[224:227], v[84:87]
	v_mfma_f32_16x16x32_bf16 v[80:83], v[200:203], v[224:227], v[80:83]
	v_mfma_f32_16x16x32_bf16 v[68:71], v[192:195], v[232:235], v[68:71]
	v_mfma_f32_16x16x32_bf16 v[64:67], v[200:203], v[232:235], v[64:67]
	s_barrier
	s_add_i32 s41, s41, s0
	v_lshl_add_u64 v[138:139], s[34:35], 0, v[144:145]
	s_mov_b32 m0, s41
	ds_read_b128 v[204:207], v143 offset:16384
	ds_read_b128 v[208:211], v143 offset:17408
	ds_read_b128 v[212:215], v143 offset:18432
	ds_read_b128 v[216:219], v143 offset:19456
	ds_read_b128 v[220:223], v143 offset:20480
	ds_read_b128 v[224:227], v143 offset:21504
	ds_read_b128 v[228:231], v143 offset:22528
	ds_read_b128 v[232:235], v143 offset:23552
	global_load_lds_dwordx4 v[138:139], off
	s_add_i32 m0, s41, 0x2000
	s_add_u32 s44, s34, 0x80000
	v_lshl_add_u64 v[180:181], s[34:35], 0, v[128:129]
	s_addc_u32 s45, s35, 0
	s_add_i32 s41, s46, s0
	global_load_lds_dwordx4 v[180:181], off
	v_lshl_add_u64 v[236:237], s[44:45], 0, v[144:145]
	s_mov_b32 m0, s41
	v_lshl_add_u64 v[238:239], s[36:37], 0, v[130:131]
	global_load_lds_dwordx4 v[236:237], off
	v_lshl_add_u64 v[236:237], s[44:45], 0, v[128:129]
	s_add_i32 m0, s41, 0x2000
	s_nop 0
	global_load_lds_dwordx4 v[236:237], off
	v_lshl_add_u64 v[236:237], s[36:37], 0, v[132:133]
	s_mov_b32 m0, s1
	s_nop 0
	global_load_lds_dwordx4 v[236:237], off
	s_mov_b32 m0, s2
	s_nop 0
	global_load_lds_dwordx4 v[238:239], off
	s_waitcnt vmcnt(8)
	s_waitcnt lgkmcnt(0)
	s_barrier
; #define PG8_STAGE(bufoff, gbase, voff) do { _Pragma("unroll") for (int _i = 0; _i < 2; ++_i) \
;         __builtin_amdgcn_global_load_lds((const unsigned*)((const char*)(gbase) + (voff)[_i]), (LAS unsigned*)(lds + (bufoff) + ldsw + _i * 8192), 16, 0, 0); } while (0)
; #define PG8_LDA(dst, b, h) do { _Pragma("unroll") for (int m = 0; m < 4; ++m) _Pragma("unroll") for (int k = 0; k < 2; ++k) dst[m][k] = *(const LAS bf16x8*)(lds + PG8_SA(b, h) + aoff + m * 2048 + k * 1024); } while (0)
; #define PG8_LDB(dst, b, h) do { _Pragma("unroll") for (int n = 0; n < 2; ++n) _Pragma("unroll") for (int k = 0; k < 2; ++k) dst[n][k] = *(const LAS bf16x8*)(lds + PG8_SB(b, h) + boff + n * 2048 + k * 1024); } while (0)
; #define PG8_MMA(ai, bj, At, Bt) do { __builtin_amdgcn_s_setprio(1); _Pragma("unroll") for (int m = 0; m < 4; ++m) _Pragma("unroll") for (int n = 0; n < 2; ++n) _Pragma("unroll") for (int k = 0; k < 2; ++k) \
;         acc[ai][bj][m][n] = __builtin_amdgcn_mfma_f32_16x16x32_bf16(Bt[n][k], At[m][k], acc[ai][bj][m][n], 0, 0, 0); __builtin_amdgcn_s_setprio(0); } while (0)
; #define PG8_WAIT_V(n) asm volatile("s_waitcnt vmcnt(" #n ")" ::: "memory")
; #define PG8_WAIT_L(n) asm volatile("s_waitcnt lgkmcnt(" #n ")" ::: "memory")
; #define PG8_BAR __builtin_amdgcn_s_barrier()
; #define PG8_SCHED __builtin_amdgcn_sched_barrier(0)
; template <class Epi, class Map>
; __device__ __forceinline__ void gemm_phase(LAS unsigned char* lds, const Gemm g, const Sched<Map>& S, const Epi& E) {
;     ...
;             PG8_WAIT_V(8); PG8_WAIT_L(0); PG8_BAR; PG8_MMA(1, 0, At, B0); PG8_MMA(1, 1, At, B1); PG8_BAR; PG8_SCHED;
;             PG8_LDB(B0, 1, 0); PG8_LDB(B1, 1, 1); PG8_SCHED; PG8_LDA(At, 1, 0); PG8_STAGE(PG8_SA(0, 1), a2 + hstepA, voffA);
;             PG8_WAIT_V(8); PG8_WAIT_L(0); PG8_BAR; PG8_MMA(0, 0, At, B0); PG8_MMA(0, 1, At, B1); PG8_BAR; PG8_SCHED;
	v_mfma_f32_16x16x32_bf16 v[60:63], v[160:163], v[204:207], v[60:63]
	v_mfma_f32_16x16x32_bf16 v[56:59], v[168:171], v[204:207], v[56:59]
	v_mfma_f32_16x16x32_bf16 v[44:47], v[160:163], v[212:215], v[44:47]
	v_mfma_f32_16x16x32_bf16 v[40:43], v[168:171], v[212:215], v[40:43]
	v_mfma_f32_16x16x32_bf16 v[28:31], v[160:163], v[220:223], v[28:31]
	v_mfma_f32_16x16x32_bf16 v[24:27], v[168:171], v[220:223], v[24:27]
	v_mfma_f32_16x16x32_bf16 v[12:15], v[160:163], v[228:231], v[12:15]
	v_mfma_f32_16x16x32_bf16 v[8:11], v[168:171], v[228:231], v[8:11]
	v_mfma_f32_16x16x32_bf16 v[60:63], v[164:167], v[208:211], v[60:63]
	v_mfma_f32_16x16x32_bf16 v[56:59], v[172:175], v[208:211], v[56:59]
	v_mfma_f32_16x16x32_bf16 v[44:47], v[164:167], v[216:219], v[44:47]
	v_mfma_f32_16x16x32_bf16 v[40:43], v[172:175], v[216:219], v[40:43]
	v_mfma_f32_16x16x32_bf16 v[28:31], v[164:167], v[224:227], v[28:31]
	v_mfma_f32_16x16x32_bf16 v[24:27], v[172:175], v[224:227], v[24:27]
	v_mfma_f32_16x16x32_bf16 v[12:15], v[164:167], v[232:235], v[12:15]
	v_mfma_f32_16x16x32_bf16 v[8:11], v[172:175], v[232:235], v[8:11]
	v_mfma_f32_16x16x32_bf16 v[52:55], v[176:179], v[204:207], v[52:55]
	v_mfma_f32_16x16x32_bf16 v[48:51], v[196:199], v[204:207], v[48:51]
	v_mfma_f32_16x16x32_bf16 v[36:39], v[176:179], v[212:215], v[36:39]
	v_mfma_f32_16x16x32_bf16 v[32:35], v[196:199], v[212:215], v[32:35]
	v_mfma_f32_16x16x32_bf16 v[20:23], v[176:179], v[220:223], v[20:23]
	v_mfma_f32_16x16x32_bf16 v[16:19], v[196:199], v[220:223], v[16:19]
	v_mfma_f32_16x16x32_bf16 v[4:7], v[176:179], v[228:231], v[4:7]
	v_mfma_f32_16x16x32_bf16 v[0:3], v[196:199], v[228:231], v[0:3]
	v_mfma_f32_16x16x32_bf16 v[52:55], v[192:195], v[208:211], v[52:55]
	v_mfma_f32_16x16x32_bf16 v[48:51], v[200:203], v[208:211], v[48:51]
	v_mfma_f32_16x16x32_bf16 v[36:39], v[192:195], v[216:219], v[36:39]
	v_mfma_f32_16x16x32_bf16 v[32:35], v[200:203], v[216:219], v[32:35]
	v_mfma_f32_16x16x32_bf16 v[20:23], v[192:195], v[224:227], v[20:23]
	v_mfma_f32_16x16x32_bf16 v[16:19], v[200:203], v[224:227], v[16:19]
	v_mfma_f32_16x16x32_bf16 v[4:7], v[192:195], v[232:235], v[4:7]
	v_mfma_f32_16x16x32_bf16 v[0:3], v[200:203], v[232:235], v[0:3]
	s_barrier
	s_add_i32 s41, 0, 0x18000
	v_add_u32_e32 v159, s41, v142
	s_add_i32 s44, 0, 0x1c000
	ds_read_b128 v[160:163], v159
	ds_read_b128 v[164:167], v159 offset:1024
	ds_read_b128 v[168:171], v159 offset:2048
	ds_read_b128 v[172:175], v159 offset:3072
	v_add_u32_e32 v159, s44, v142
	ds_read_b128 v[176:179], v159
	ds_read_b128 v[192:195], v159 offset:1024
	ds_read_b128 v[196:199], v159 offset:2048
	ds_read_b128 v[200:203], v159 offset:3072
	s_add_u32 s36, s36, 0x80000
	s_addc_u32 s37, s37, 0
	s_mov_b32 m0, s3
	v_lshl_add_u64 v[240:241], s[36:37], 0, v[132:133]
	ds_read_b128 v[204:207], v143 offset:32768
	ds_read_b128 v[208:211], v143 offset:33792
	ds_read_b128 v[212:215], v143 offset:34816
	ds_read_b128 v[216:219], v143 offset:35840
	ds_read_b128 v[220:223], v143 offset:36864
	ds_read_b128 v[224:227], v143 offset:37888
	ds_read_b128 v[228:231], v143 offset:38912
	ds_read_b128 v[232:235], v143 offset:39936
	global_load_lds_dwordx4 v[240:241], off
	v_lshl_add_u64 v[240:241], s[36:37], 0, v[130:131]
	s_mov_b32 m0, s4
	s_nop 0
	global_load_lds_dwordx4 v[240:241], off
	s_waitcnt vmcnt(8)
	s_waitcnt lgkmcnt(0)
	s_barrier
	v_mfma_f32_16x16x32_bf16 v[124:127], v[160:163], v[204:207], v[124:127]
	v_mfma_f32_16x16x32_bf16 v[120:123], v[168:171], v[204:207], v[120:123]
	v_mfma_f32_16x16x32_bf16 v[108:111], v[160:163], v[212:215], v[108:111]
	v_mfma_f32_16x16x32_bf16 v[104:107], v[168:171], v[212:215], v[104:107]
	v_mfma_f32_16x16x32_bf16 v[92:95], v[160:163], v[220:223], v[92:95]
	v_mfma_f32_16x16x32_bf16 v[88:91], v[168:171], v[220:223], v[88:91]
	v_mfma_f32_16x16x32_bf16 v[76:79], v[160:163], v[228:231], v[76:79]
	v_mfma_f32_16x16x32_bf16 v[72:75], v[168:171], v[228:231], v[72:75]
	v_mfma_f32_16x16x32_bf16 v[124:127], v[164:167], v[208:211], v[124:127]
	v_mfma_f32_16x16x32_bf16 v[120:123], v[172:175], v[208:211], v[120:123]
	v_mfma_f32_16x16x32_bf16 v[108:111], v[164:167], v[216:219], v[108:111]
	v_mfma_f32_16x16x32_bf16 v[104:107], v[172:175], v[216:219], v[104:107]
	v_mfma_f32_16x16x32_bf16 v[92:95], v[164:167], v[224:227], v[92:95]
	v_mfma_f32_16x16x32_bf16 v[88:91], v[172:175], v[224:227], v[88:91]
	v_mfma_f32_16x16x32_bf16 v[76:79], v[164:167], v[232:235], v[76:79]
	v_mfma_f32_16x16x32_bf16 v[72:75], v[172:175], v[232:235], v[72:75]
	v_mfma_f32_16x16x32_bf16 v[116:119], v[176:179], v[204:207], v[116:119]
	v_mfma_f32_16x16x32_bf16 v[112:115], v[196:199], v[204:207], v[112:115]
	v_mfma_f32_16x16x32_bf16 v[100:103], v[176:179], v[212:215], v[100:103]
	v_mfma_f32_16x16x32_bf16 v[96:99], v[196:199], v[212:215], v[96:99]
	v_mfma_f32_16x16x32_bf16 v[84:87], v[176:179], v[220:223], v[84:87]
	v_mfma_f32_16x16x32_bf16 v[80:83], v[196:199], v[220:223], v[80:83]
	v_mfma_f32_16x16x32_bf16 v[68:71], v[176:179], v[228:231], v[68:71]
	v_mfma_f32_16x16x32_bf16 v[64:67], v[196:199], v[228:231], v[64:67]
	v_mfma_f32_16x16x32_bf16 v[116:119], v[192:195], v[208:211], v[116:119]
	v_mfma_f32_16x16x32_bf16 v[112:115], v[200:203], v[208:211], v[112:115]
	v_mfma_f32_16x16x32_bf16 v[100:103], v[192:195], v[216:219], v[100:103]
	v_mfma_f32_16x16x32_bf16 v[96:99], v[200:203], v[216:219], v[96:99]
	v_mfma_f32_16x16x32_bf16 v[84:87], v[192:195], v[224:227], v[84:87]
	v_mfma_f32_16x16x32_bf16 v[80:83], v[200:203], v[224:227], v[80:83]
	v_mfma_f32_16x16x32_bf16 v[68:71], v[192:195], v[232:235], v[68:71]
	v_mfma_f32_16x16x32_bf16 v[64:67], v[200:203], v[232:235], v[64:67]
	s_barrier
; #define PG8_STAGE(bufoff, gbase, voff) do { _Pragma("unroll") for (int _i = 0; _i < 2; ++_i) \
;         __builtin_amdgcn_global_load_lds((const unsigned*)((const char*)(gbase) + (voff)[_i]), (LAS unsigned*)(lds + (bufoff) + ldsw + _i * 8192), 16, 0, 0); } while (0)
; #define PG8_LDA(dst, b, h) do { _Pragma("unroll") for (int m = 0; m < 4; ++m) _Pragma("unroll") for (int k = 0; k < 2; ++k) dst[m][k] = *(const LAS bf16x8*)(lds + PG8_SA(b, h) + aoff + m * 2048 + k * 1024); } while (0)
; #define PG8_MMA(ai, bj, At, Bt) do { __builtin_amdgcn_s_setprio(1); _Pragma("unroll") for (int m = 0; m < 4; ++m) _Pragma("unroll") for (int n = 0; n < 2; ++n) _Pragma("unroll") for (int k = 0; k < 2; ++k) \
;         acc[ai][bj][m][n] = __builtin_amdgcn_mfma_f32_16x16x32_bf16(Bt[n][k], At[m][k], acc[ai][bj][m][n], 0, 0, 0); __builtin_amdgcn_s_setprio(0); } while (0)
; #define PG8_WAIT_V(n) asm volatile("s_waitcnt vmcnt(" #n ")" ::: "memory")
; #define PG8_WAIT_L(n) asm volatile("s_waitcnt lgkmcnt(" #n ")" ::: "memory")
; #define PG8_BAR __builtin_amdgcn_s_barrier()
; #define PG8_SCHED __builtin_amdgcn_sched_barrier(0)
; template <class Epi, class Map>
; __device__ __forceinline__ void gemm_phase(LAS unsigned char* lds, const Gemm g, const Sched<Map>& S, const Epi& E) {
;     ...
;             PG8_LDA(At, 1, 1); PG8_STAGE(PG8_SB(1, 0), b3, voffB); PG8_STAGE(PG8_SB(1, 1), b3 + hstepB, voffB); PG8_STAGE(PG8_SA(1, 0), a3, voffA);
;             PG8_WAIT_V(8); PG8_WAIT_L(0); PG8_BAR; PG8_MMA(1, 0, At, B0); PG8_MMA(1, 1, At, B1); PG8_BAR; PG8_SCHED;
;         }
	s_add_i32 s36, s41, s0
	v_lshl_add_u64 v[138:139], v[138:139], 0, s[82:83]
	s_mov_b32 m0, s36
	ds_read_b128 v[204:207], v143 offset:49152
	ds_read_b128 v[208:211], v143 offset:50176
	ds_read_b128 v[212:215], v143 offset:51200
	ds_read_b128 v[216:219], v143 offset:52224
	ds_read_b128 v[220:223], v143 offset:53248
	ds_read_b128 v[224:227], v143 offset:54272
	ds_read_b128 v[228:231], v143 offset:55296
	ds_read_b128 v[232:235], v143 offset:56320
	global_load_lds_dwordx4 v[138:139], off
	s_add_i32 m0, s36, 0x2000
	s_add_u32 s34, s34, 0x80080
	v_lshl_add_u64 v[138:139], v[180:181], 0, s[82:83]
	s_addc_u32 s35, s35, 0
	s_add_i32 s36, s44, s0
	global_load_lds_dwordx4 v[138:139], off
	v_lshl_add_u64 v[138:139], s[34:35], 0, v[144:145]
	s_mov_b32 m0, s36
	s_nop 0
	global_load_lds_dwordx4 v[138:139], off
	v_lshl_add_u64 v[138:139], s[34:35], 0, v[128:129]
	s_add_i32 m0, s36, 0x2000
	s_nop 0
	global_load_lds_dwordx4 v[138:139], off
	v_lshl_add_u64 v[138:139], v[236:237], 0, s[82:83]
	s_mov_b32 m0, s6
	s_nop 0
	global_load_lds_dwordx4 v[138:139], off
	v_lshl_add_u64 v[138:139], v[238:239], 0, s[82:83]
	s_mov_b32 m0, s7
	s_nop 0
	global_load_lds_dwordx4 v[138:139], off
	s_waitcnt vmcnt(8)
	s_waitcnt lgkmcnt(0)
	s_barrier
	v_mfma_f32_16x16x32_bf16 v[60:63], v[160:163], v[204:207], v[60:63]
	v_mfma_f32_16x16x32_bf16 v[56:59], v[168:171], v[204:207], v[56:59]
	v_mfma_f32_16x16x32_bf16 v[44:47], v[160:163], v[212:215], v[44:47]
	v_mfma_f32_16x16x32_bf16 v[40:43], v[168:171], v[212:215], v[40:43]
	v_mfma_f32_16x16x32_bf16 v[28:31], v[160:163], v[220:223], v[28:31]
	v_mfma_f32_16x16x32_bf16 v[24:27], v[168:171], v[220:223], v[24:27]
	v_mfma_f32_16x16x32_bf16 v[12:15], v[160:163], v[228:231], v[12:15]
	v_mfma_f32_16x16x32_bf16 v[8:11], v[168:171], v[228:231], v[8:11]
	v_mfma_f32_16x16x32_bf16 v[60:63], v[164:167], v[208:211], v[60:63]
	v_mfma_f32_16x16x32_bf16 v[56:59], v[172:175], v[208:211], v[56:59]
	v_mfma_f32_16x16x32_bf16 v[44:47], v[164:167], v[216:219], v[44:47]
	v_mfma_f32_16x16x32_bf16 v[40:43], v[172:175], v[216:219], v[40:43]
	v_mfma_f32_16x16x32_bf16 v[28:31], v[164:167], v[224:227], v[28:31]
	v_mfma_f32_16x16x32_bf16 v[24:27], v[172:175], v[224:227], v[24:27]
	v_mfma_f32_16x16x32_bf16 v[12:15], v[164:167], v[232:235], v[12:15]
	v_mfma_f32_16x16x32_bf16 v[8:11], v[172:175], v[232:235], v[8:11]
	v_mfma_f32_16x16x32_bf16 v[52:55], v[176:179], v[204:207], v[52:55]
	v_mfma_f32_16x16x32_bf16 v[48:51], v[196:199], v[204:207], v[48:51]
	v_mfma_f32_16x16x32_bf16 v[36:39], v[176:179], v[212:215], v[36:39]
	v_mfma_f32_16x16x32_bf16 v[32:35], v[196:199], v[212:215], v[32:35]
	v_mfma_f32_16x16x32_bf16 v[20:23], v[176:179], v[220:223], v[20:23]
	v_mfma_f32_16x16x32_bf16 v[16:19], v[196:199], v[220:223], v[16:19]
	v_mfma_f32_16x16x32_bf16 v[4:7], v[176:179], v[228:231], v[4:7]
	v_mfma_f32_16x16x32_bf16 v[0:3], v[196:199], v[228:231], v[0:3]
	v_mfma_f32_16x16x32_bf16 v[52:55], v[192:195], v[208:211], v[52:55]
	v_mfma_f32_16x16x32_bf16 v[48:51], v[200:203], v[208:211], v[48:51]
	v_mfma_f32_16x16x32_bf16 v[36:39], v[192:195], v[216:219], v[36:39]
	v_mfma_f32_16x16x32_bf16 v[32:35], v[200:203], v[216:219], v[32:35]
	v_mfma_f32_16x16x32_bf16 v[20:23], v[192:195], v[224:227], v[20:23]
	v_mfma_f32_16x16x32_bf16 v[16:19], v[200:203], v[224:227], v[16:19]
	v_mfma_f32_16x16x32_bf16 v[4:7], v[192:195], v[232:235], v[4:7]
	v_mfma_f32_16x16x32_bf16 v[0:3], v[200:203], v[232:235], v[0:3]
	s_barrier
	s_add_i32 s40, s40, 2
	s_add_u32 s30, s30, 0x100
	s_addc_u32 s31, s31, 0
	s_add_u32 s21, s21, 0x100
	s_addc_u32 s33, s33, 0
	s_cmp_gt_u32 s40, 29
	s_cbranch_scc0 .LBB0_1088
	s_and_b64 vcc, exec, s[18:19]
	s_cbranch_vccz .LBB0_1091

; #define PG8_STAGE(bufoff, gbase, voff) do { _Pragma("unroll") for (int _i = 0; _i < 2; ++_i) \
;         __builtin_amdgcn_global_load_lds((const unsigned*)((const char*)(gbase) + (voff)[_i]), (LAS unsigned*)(lds + (bufoff) + ldsw + _i * 8192), 16, 0, 0); } while (0)
; #define PG8_LDA(dst, b, h) do { _Pragma("unroll") for (int m = 0; m < 4; ++m) _Pragma("unroll") for (int k = 0; k < 2; ++k) dst[m][k] = *(const LAS bf16x8*)(lds + PG8_SA(b, h) + aoff + m * 2048 + k * 1024); } while (0)
; #define PG8_LDB(dst, b, h) do { _Pragma("unroll") for (int n = 0; n < 2; ++n) _Pragma("unroll") for (int k = 0; k < 2; ++k) dst[n][k] = *(const LAS bf16x8*)(lds + PG8_SB(b, h) + boff + n * 2048 + k * 1024); } while (0)
; #define PG8_MMA(ai, bj, At, Bt) do { __builtin_amdgcn_s_setprio(1); _Pragma("unroll") for (int m = 0; m < 4; ++m) _Pragma("unroll") for (int n = 0; n < 2; ++n) _Pragma("unroll") for (int k = 0; k < 2; ++k) \
;         acc[ai][bj][m][n] = __builtin_amdgcn_mfma_f32_16x16x32_bf16(Bt[n][k], At[m][k], acc[ai][bj][m][n], 0, 0, 0); __builtin_amdgcn_s_setprio(0); } while (0)
; #define PG8_WAIT_V(n) asm volatile("s_waitcnt vmcnt(" #n ")" ::: "memory")
; #define PG8_WAIT_L(n) asm volatile("s_waitcnt lgkmcnt(" #n ")" ::: "memory")
; #define PG8_BAR __builtin_amdgcn_s_barrier()
; #define PG8_SCHED __builtin_amdgcn_sched_barrier(0)
; template <class Epi, class Map>
; __device__ __forceinline__ void gemm_phase(LAS unsigned char* lds, const Gemm g, const Sched<Map>& S, const Epi& E) {
;     ...
;         for (int t = 0; t < nt; t += 2) {
;             const bool last = (t == nt - 2);
;             const char* a1 = cA + (size_t)(t + 1) * kstep;
;             const char* a2 = last ? nA : cA + (size_t)(t + 2) * kstep; const char* b2 = last ? nB : cB + (size_t)(t + 2) * kstep;
;             const char* a3 = a2 + kstep; const char* b3 = b2 + kstep;
;             PG8_LDB(B0, 0, 0); PG8_LDB(B1, 0, 1); PG8_SCHED; PG8_LDA(At, 0, 0); PG8_STAGE(PG8_SA(1, 1), a1 + hstepA, voffA);
;             PG8_WAIT_V(8); PG8_WAIT_L(0); PG8_BAR; PG8_MMA(0, 0, At, B0); PG8_MMA(0, 1, At, B1); PG8_BAR; PG8_SCHED;
;             PG8_LDA(At, 0, 1); PG8_STAGE(PG8_SB(0, 0), b2, voffB); PG8_STAGE(PG8_SB(0, 1), b2 + hstepB, voffB); PG8_STAGE(PG8_SA(0, 0), a2, voffA);
;             PG8_WAIT_V(8); PG8_WAIT_L(0); PG8_BAR; PG8_MMA(1, 0, At, B0); PG8_MMA(1, 1, At, B1); PG8_BAR; PG8_SCHED;
.LBB0_1161:
	s_add_u32 s30, s28, 0xffe00080
	s_addc_u32 s31, s29, -1
	s_add_i32 s50, 0, 0x10000
	s_cmpk_eq_i32 s49, 0x7c
	s_cselect_b32 s35, s37, s31
	s_cselect_b32 s34, s44, s30
	s_cselect_b32 s31, s45, s48
	s_cselect_b32 s30, s46, s47
	s_add_i32 s52, 0, 0x14000
	v_add_u32_e32 v116, s50, v173
	v_add_u32_e32 v170, s52, v173
	ds_read_b128 v[104:107], v116
	ds_read_b128 v[108:111], v116 offset:1024
	ds_read_b128 v[112:115], v116 offset:2048
	ds_read_b128 v[116:119], v116 offset:3072
	ds_read_b128 v[176:179], v170
	ds_read_b128 v[192:195], v170 offset:1024
	ds_read_b128 v[196:199], v170 offset:2048
	ds_read_b128 v[200:203], v170 offset:3072
	v_lshl_add_u64 v[170:171], s[28:29], 0, v[166:167]
	s_add_i32 m0, s3, 0xc000
	ds_read_b128 v[204:207], v174
	ds_read_b128 v[208:211], v174 offset:1024
	ds_read_b128 v[212:215], v174 offset:2048
	ds_read_b128 v[216:219], v174 offset:3072
	ds_read_b128 v[220:223], v174 offset:4096
	ds_read_b128 v[224:227], v174 offset:5120
	ds_read_b128 v[228:231], v174 offset:6144
	ds_read_b128 v[232:235], v174 offset:7168
	global_load_lds_dwordx4 v[170:171], off
	v_lshl_add_u64 v[170:171], s[28:29], 0, v[168:169]
	s_add_i32 m0, s3, 0xe000
	s_nop 0
	global_load_lds_dwordx4 v[170:171], off
	s_waitcnt vmcnt(8)
	s_waitcnt lgkmcnt(0)
	s_barrier
	v_mfma_f32_16x16x32_bf16 v[140:143], v[104:107], v[204:207], v[140:143]
	v_mfma_f32_16x16x32_bf16 v[136:139], v[112:115], v[204:207], v[136:139]
	v_mfma_f32_16x16x32_bf16 v[132:135], v[104:107], v[212:215], v[132:135]
	v_mfma_f32_16x16x32_bf16 v[128:131], v[112:115], v[212:215], v[128:131]
	v_mfma_f32_16x16x32_bf16 v[100:103], v[104:107], v[220:223], v[100:103]
	v_mfma_f32_16x16x32_bf16 v[96:99], v[112:115], v[220:223], v[96:99]
	v_mfma_f32_16x16x32_bf16 v[76:79], v[104:107], v[228:231], v[76:79]
	v_mfma_f32_16x16x32_bf16 v[72:75], v[112:115], v[228:231], v[72:75]
	v_mfma_f32_16x16x32_bf16 v[140:143], v[108:111], v[208:211], v[140:143]
	v_mfma_f32_16x16x32_bf16 v[136:139], v[116:119], v[208:211], v[136:139]
	v_mfma_f32_16x16x32_bf16 v[132:135], v[108:111], v[216:219], v[132:135]
	v_mfma_f32_16x16x32_bf16 v[128:131], v[116:119], v[216:219], v[128:131]
	v_mfma_f32_16x16x32_bf16 v[100:103], v[108:111], v[224:227], v[100:103]
	v_mfma_f32_16x16x32_bf16 v[96:99], v[116:119], v[224:227], v[96:99]
	v_mfma_f32_16x16x32_bf16 v[76:79], v[108:111], v[232:235], v[76:79]
	v_mfma_f32_16x16x32_bf16 v[72:75], v[116:119], v[232:235], v[72:75]
	v_mfma_f32_16x16x32_bf16 v[124:127], v[176:179], v[204:207], v[124:127]
	v_mfma_f32_16x16x32_bf16 v[120:123], v[196:199], v[204:207], v[120:123]
	v_mfma_f32_16x16x32_bf16 v[92:95], v[176:179], v[212:215], v[92:95]
	v_mfma_f32_16x16x32_bf16 v[88:91], v[196:199], v[212:215], v[88:91]
	v_mfma_f32_16x16x32_bf16 v[84:87], v[176:179], v[220:223], v[84:87]
	v_mfma_f32_16x16x32_bf16 v[80:83], v[196:199], v[220:223], v[80:83]
	v_mfma_f32_16x16x32_bf16 v[68:71], v[176:179], v[228:231], v[68:71]
	v_mfma_f32_16x16x32_bf16 v[64:67], v[196:199], v[228:231], v[64:67]
	v_mfma_f32_16x16x32_bf16 v[124:127], v[192:195], v[208:211], v[124:127]
	v_mfma_f32_16x16x32_bf16 v[120:123], v[200:203], v[208:211], v[120:123]
	v_mfma_f32_16x16x32_bf16 v[92:95], v[192:195], v[216:219], v[92:95]
	v_mfma_f32_16x16x32_bf16 v[88:91], v[200:203], v[216:219], v[88:91]
	v_mfma_f32_16x16x32_bf16 v[84:87], v[192:195], v[224:227], v[84:87]
	v_mfma_f32_16x16x32_bf16 v[80:83], v[200:203], v[224:227], v[80:83]
	v_mfma_f32_16x16x32_bf16 v[68:71], v[192:195], v[232:235], v[68:71]
	v_mfma_f32_16x16x32_bf16 v[64:67], v[200:203], v[232:235], v[64:67]
	s_barrier
	s_add_i32 s50, s50, s2
	v_lshl_add_u64 v[170:171], s[30:31], 0, v[144:145]
	s_mov_b32 m0, s50
	ds_read_b128 v[204:207], v174 offset:16384
	ds_read_b128 v[208:211], v174 offset:17408
	ds_read_b128 v[212:215], v174 offset:18432
	ds_read_b128 v[216:219], v174 offset:19456
	ds_read_b128 v[220:223], v174 offset:20480
	ds_read_b128 v[224:227], v174 offset:21504
	ds_read_b128 v[228:231], v174 offset:22528
	ds_read_b128 v[232:235], v174 offset:23552
	global_load_lds_dwordx4 v[170:171], off
	s_add_i32 m0, s50, 0x2000
	s_add_u32 s50, s30, 0x200000
	v_lshl_add_u64 v[180:181], s[30:31], 0, v[160:161]
	s_addc_u32 s51, s31, 0
	s_add_i32 s52, s52, s2
	global_load_lds_dwordx4 v[180:181], off
	v_lshl_add_u64 v[236:237], s[50:51], 0, v[144:145]
	s_mov_b32 m0, s52
	v_lshl_add_u64 v[238:239], s[34:35], 0, v[162:163]
	global_load_lds_dwordx4 v[236:237], off
	v_lshl_add_u64 v[236:237], s[50:51], 0, v[160:161]
	s_add_i32 m0, s52, 0x2000
	s_nop 0
	global_load_lds_dwordx4 v[236:237], off
	v_lshl_add_u64 v[236:237], s[34:35], 0, v[164:165]
	s_mov_b32 m0, s3
	s_nop 0
	global_load_lds_dwordx4 v[236:237], off
	s_mov_b32 m0, s4
	s_nop 0
	global_load_lds_dwordx4 v[238:239], off
	s_waitcnt vmcnt(8)
	s_waitcnt lgkmcnt(0)
	s_barrier
; #define PG8_STAGE(bufoff, gbase, voff) do { _Pragma("unroll") for (int _i = 0; _i < 2; ++_i) \
;         __builtin_amdgcn_global_load_lds((const unsigned*)((const char*)(gbase) + (voff)[_i]), (LAS unsigned*)(lds + (bufoff) + ldsw + _i * 8192), 16, 0, 0); } while (0)
; #define PG8_LDA(dst, b, h) do { _Pragma("unroll") for (int m = 0; m < 4; ++m) _Pragma("unroll") for (int k = 0; k < 2; ++k) dst[m][k] = *(const LAS bf16x8*)(lds + PG8_SA(b, h) + aoff + m * 2048 + k * 1024); } while (0)
; #define PG8_LDB(dst, b, h) do { _Pragma("unroll") for (int n = 0; n < 2; ++n) _Pragma("unroll") for (int k = 0; k < 2; ++k) dst[n][k] = *(const LAS bf16x8*)(lds + PG8_SB(b, h) + boff + n * 2048 + k * 1024); } while (0)
; #define PG8_MMA(ai, bj, At, Bt) do { __builtin_amdgcn_s_setprio(1); _Pragma("unroll") for (int m = 0; m < 4; ++m) _Pragma("unroll") for (int n = 0; n < 2; ++n) _Pragma("unroll") for (int k = 0; k < 2; ++k) \
;         acc[ai][bj][m][n] = __builtin_amdgcn_mfma_f32_16x16x32_bf16(Bt[n][k], At[m][k], acc[ai][bj][m][n], 0, 0, 0); __builtin_amdgcn_s_setprio(0); } while (0)
; #define PG8_WAIT_V(n) asm volatile("s_waitcnt vmcnt(" #n ")" ::: "memory")
; #define PG8_WAIT_L(n) asm volatile("s_waitcnt lgkmcnt(" #n ")" ::: "memory")
; #define PG8_BAR __builtin_amdgcn_s_barrier()
; #define PG8_SCHED __builtin_amdgcn_sched_barrier(0)
; template <class Epi, class Map>
; __device__ __forceinline__ void gemm_phase(LAS unsigned char* lds, const Gemm g, const Sched<Map>& S, const Epi& E) {
;     ...
;             PG8_WAIT_V(8); PG8_WAIT_L(0); PG8_BAR; PG8_MMA(0, 0, At, B0); PG8_MMA(0, 1, At, B1); PG8_BAR; PG8_SCHED;
;             PG8_LDA(At, 0, 1); PG8_STAGE(PG8_SB(0, 0), b2, voffB); PG8_STAGE(PG8_SB(0, 1), b2 + hstepB, voffB); PG8_STAGE(PG8_SA(0, 0), a2, voffA);
;             PG8_WAIT_V(8); PG8_WAIT_L(0); PG8_BAR; PG8_MMA(1, 0, At, B0); PG8_MMA(1, 1, At, B1); PG8_BAR; PG8_SCHED;
;             PG8_LDB(B0, 1, 0); PG8_LDB(B1, 1, 1); PG8_SCHED; PG8_LDA(At, 1, 0); PG8_STAGE(PG8_SA(0, 1), a2 + hstepA, voffA);
;             PG8_WAIT_V(8); PG8_WAIT_L(0); PG8_BAR; PG8_MMA(0, 0, At, B0); PG8_MMA(0, 1, At, B1); PG8_BAR; PG8_SCHED;
	v_mfma_f32_16x16x32_bf16 v[60:63], v[104:107], v[204:207], v[60:63]
	v_mfma_f32_16x16x32_bf16 v[56:59], v[112:115], v[204:207], v[56:59]
	v_mfma_f32_16x16x32_bf16 v[48:51], v[104:107], v[212:215], v[48:51]
	v_mfma_f32_16x16x32_bf16 v[40:43], v[112:115], v[212:215], v[40:43]
	v_mfma_f32_16x16x32_bf16 v[32:35], v[104:107], v[220:223], v[32:35]
	v_mfma_f32_16x16x32_bf16 v[24:27], v[112:115], v[220:223], v[24:27]
	v_mfma_f32_16x16x32_bf16 v[16:19], v[104:107], v[228:231], v[16:19]
	v_mfma_f32_16x16x32_bf16 v[8:11], v[112:115], v[228:231], v[8:11]
	v_mfma_f32_16x16x32_bf16 v[60:63], v[108:111], v[208:211], v[60:63]
	v_mfma_f32_16x16x32_bf16 v[56:59], v[116:119], v[208:211], v[56:59]
	v_mfma_f32_16x16x32_bf16 v[48:51], v[108:111], v[216:219], v[48:51]
	v_mfma_f32_16x16x32_bf16 v[40:43], v[116:119], v[216:219], v[40:43]
	v_mfma_f32_16x16x32_bf16 v[32:35], v[108:111], v[224:227], v[32:35]
	v_mfma_f32_16x16x32_bf16 v[24:27], v[116:119], v[224:227], v[24:27]
	v_mfma_f32_16x16x32_bf16 v[16:19], v[108:111], v[232:235], v[16:19]
	v_mfma_f32_16x16x32_bf16 v[8:11], v[116:119], v[232:235], v[8:11]
	v_mfma_f32_16x16x32_bf16 v[52:55], v[176:179], v[204:207], v[52:55]
	v_mfma_f32_16x16x32_bf16 v[44:47], v[196:199], v[204:207], v[44:47]
	v_mfma_f32_16x16x32_bf16 v[36:39], v[176:179], v[212:215], v[36:39]
	v_mfma_f32_16x16x32_bf16 v[28:31], v[196:199], v[212:215], v[28:31]
	v_mfma_f32_16x16x32_bf16 v[20:23], v[176:179], v[220:223], v[20:23]
	v_mfma_f32_16x16x32_bf16 v[12:15], v[196:199], v[220:223], v[12:15]
	v_mfma_f32_16x16x32_bf16 v[4:7], v[176:179], v[228:231], v[4:7]
	v_mfma_f32_16x16x32_bf16 v[0:3], v[196:199], v[228:231], v[0:3]
	v_mfma_f32_16x16x32_bf16 v[52:55], v[192:195], v[208:211], v[52:55]
	v_mfma_f32_16x16x32_bf16 v[44:47], v[200:203], v[208:211], v[44:47]
	v_mfma_f32_16x16x32_bf16 v[36:39], v[192:195], v[216:219], v[36:39]
	v_mfma_f32_16x16x32_bf16 v[28:31], v[200:203], v[216:219], v[28:31]
	v_mfma_f32_16x16x32_bf16 v[20:23], v[192:195], v[224:227], v[20:23]
	v_mfma_f32_16x16x32_bf16 v[12:15], v[200:203], v[224:227], v[12:15]
	v_mfma_f32_16x16x32_bf16 v[4:7], v[192:195], v[232:235], v[4:7]
	v_mfma_f32_16x16x32_bf16 v[0:3], v[200:203], v[232:235], v[0:3]
	s_barrier
	s_add_i32 s50, 0, 0x18000
	s_add_i32 s51, 0, 0x1c000
	v_add_u32_e32 v116, s50, v173
	v_add_u32_e32 v175, s51, v173
	ds_read_b128 v[104:107], v116
	ds_read_b128 v[108:111], v116 offset:1024
	ds_read_b128 v[112:115], v116 offset:2048
	ds_read_b128 v[116:119], v116 offset:3072
	ds_read_b128 v[176:179], v175
	ds_read_b128 v[192:195], v175 offset:1024
	ds_read_b128 v[196:199], v175 offset:2048
	ds_read_b128 v[200:203], v175 offset:3072
	s_add_u32 s34, s34, 0x200000
	s_addc_u32 s35, s35, 0
	s_mov_b32 m0, s5
	v_lshl_add_u64 v[240:241], s[34:35], 0, v[164:165]
	ds_read_b128 v[204:207], v174 offset:32768
	ds_read_b128 v[208:211], v174 offset:33792
	ds_read_b128 v[212:215], v174 offset:34816
	ds_read_b128 v[216:219], v174 offset:35840
	ds_read_b128 v[220:223], v174 offset:36864
	ds_read_b128 v[224:227], v174 offset:37888
	ds_read_b128 v[228:231], v174 offset:38912
	ds_read_b128 v[232:235], v174 offset:39936
	global_load_lds_dwordx4 v[240:241], off
	v_lshl_add_u64 v[240:241], s[34:35], 0, v[162:163]
	s_mov_b32 m0, s6
	s_nop 0
	global_load_lds_dwordx4 v[240:241], off
	s_waitcnt vmcnt(8)
	s_waitcnt lgkmcnt(0)
	s_barrier
	v_mfma_f32_16x16x32_bf16 v[140:143], v[104:107], v[204:207], v[140:143]
	v_mfma_f32_16x16x32_bf16 v[136:139], v[112:115], v[204:207], v[136:139]
	v_mfma_f32_16x16x32_bf16 v[132:135], v[104:107], v[212:215], v[132:135]
	v_mfma_f32_16x16x32_bf16 v[128:131], v[112:115], v[212:215], v[128:131]
	v_mfma_f32_16x16x32_bf16 v[100:103], v[104:107], v[220:223], v[100:103]
	v_mfma_f32_16x16x32_bf16 v[96:99], v[112:115], v[220:223], v[96:99]
	v_mfma_f32_16x16x32_bf16 v[76:79], v[104:107], v[228:231], v[76:79]
	v_mfma_f32_16x16x32_bf16 v[72:75], v[112:115], v[228:231], v[72:75]
	v_mfma_f32_16x16x32_bf16 v[140:143], v[108:111], v[208:211], v[140:143]
	v_mfma_f32_16x16x32_bf16 v[136:139], v[116:119], v[208:211], v[136:139]
	v_mfma_f32_16x16x32_bf16 v[132:135], v[108:111], v[216:219], v[132:135]
	v_mfma_f32_16x16x32_bf16 v[128:131], v[116:119], v[216:219], v[128:131]
	v_mfma_f32_16x16x32_bf16 v[100:103], v[108:111], v[224:227], v[100:103]
	v_mfma_f32_16x16x32_bf16 v[96:99], v[116:119], v[224:227], v[96:99]
	v_mfma_f32_16x16x32_bf16 v[76:79], v[108:111], v[232:235], v[76:79]
	v_mfma_f32_16x16x32_bf16 v[72:75], v[116:119], v[232:235], v[72:75]
	v_mfma_f32_16x16x32_bf16 v[124:127], v[176:179], v[204:207], v[124:127]
	v_mfma_f32_16x16x32_bf16 v[120:123], v[196:199], v[204:207], v[120:123]
	v_mfma_f32_16x16x32_bf16 v[92:95], v[176:179], v[212:215], v[92:95]
	v_mfma_f32_16x16x32_bf16 v[88:91], v[196:199], v[212:215], v[88:91]
	v_mfma_f32_16x16x32_bf16 v[84:87], v[176:179], v[220:223], v[84:87]
	v_mfma_f32_16x16x32_bf16 v[80:83], v[196:199], v[220:223], v[80:83]
	v_mfma_f32_16x16x32_bf16 v[68:71], v[176:179], v[228:231], v[68:71]
	v_mfma_f32_16x16x32_bf16 v[64:67], v[196:199], v[228:231], v[64:67]
	v_mfma_f32_16x16x32_bf16 v[124:127], v[192:195], v[208:211], v[124:127]
	v_mfma_f32_16x16x32_bf16 v[120:123], v[200:203], v[208:211], v[120:123]
	v_mfma_f32_16x16x32_bf16 v[92:95], v[192:195], v[216:219], v[92:95]
	v_mfma_f32_16x16x32_bf16 v[88:91], v[200:203], v[216:219], v[88:91]
	v_mfma_f32_16x16x32_bf16 v[84:87], v[192:195], v[224:227], v[84:87]
	v_mfma_f32_16x16x32_bf16 v[80:83], v[200:203], v[224:227], v[80:83]
	v_mfma_f32_16x16x32_bf16 v[68:71], v[192:195], v[232:235], v[68:71]
	v_mfma_f32_16x16x32_bf16 v[64:67], v[200:203], v[232:235], v[64:67]
	s_barrier
; #define PG8_STAGE(bufoff, gbase, voff) do { _Pragma("unroll") for (int _i = 0; _i < 2; ++_i) \
;         __builtin_amdgcn_global_load_lds((const unsigned*)((const char*)(gbase) + (voff)[_i]), (LAS unsigned*)(lds + (bufoff) + ldsw + _i * 8192), 16, 0, 0); } while (0)
; #define PG8_LDA(dst, b, h) do { _Pragma("unroll") for (int m = 0; m < 4; ++m) _Pragma("unroll") for (int k = 0; k < 2; ++k) dst[m][k] = *(const LAS bf16x8*)(lds + PG8_SA(b, h) + aoff + m * 2048 + k * 1024); } while (0)
; #define PG8_MMA(ai, bj, At, Bt) do { __builtin_amdgcn_s_setprio(1); _Pragma("unroll") for (int m = 0; m < 4; ++m) _Pragma("unroll") for (int n = 0; n < 2; ++n) _Pragma("unroll") for (int k = 0; k < 2; ++k) \
;         acc[ai][bj][m][n] = __builtin_amdgcn_mfma_f32_16x16x32_bf16(Bt[n][k], At[m][k], acc[ai][bj][m][n], 0, 0, 0); __builtin_amdgcn_s_setprio(0); } while (0)
; #define PG8_WAIT_V(n) asm volatile("s_waitcnt vmcnt(" #n ")" ::: "memory")
; #define PG8_WAIT_L(n) asm volatile("s_waitcnt lgkmcnt(" #n ")" ::: "memory")
; #define PG8_BAR __builtin_amdgcn_s_barrier()
; #define PG8_SCHED __builtin_amdgcn_sched_barrier(0)
; template <class Epi, class Map>
; __device__ __forceinline__ void gemm_phase(LAS unsigned char* lds, const Gemm g, const Sched<Map>& S, const Epi& E) {
;     ...
;             PG8_LDA(At, 1, 1); PG8_STAGE(PG8_SB(1, 0), b3, voffB); PG8_STAGE(PG8_SB(1, 1), b3 + hstepB, voffB); PG8_STAGE(PG8_SA(1, 0), a3, voffA);
;             PG8_WAIT_V(8); PG8_WAIT_L(0); PG8_BAR; PG8_MMA(1, 0, At, B0); PG8_MMA(1, 1, At, B1); PG8_BAR; PG8_SCHED;
;         }
	s_add_i32 s34, s50, s2
	v_lshl_add_u64 v[170:171], v[170:171], 0, s[82:83]
	s_mov_b32 m0, s34
	ds_read_b128 v[204:207], v174 offset:49152
	ds_read_b128 v[208:211], v174 offset:50176
	ds_read_b128 v[212:215], v174 offset:51200
	ds_read_b128 v[216:219], v174 offset:52224
	ds_read_b128 v[220:223], v174 offset:53248
	ds_read_b128 v[224:227], v174 offset:54272
	ds_read_b128 v[228:231], v174 offset:55296
	ds_read_b128 v[232:235], v174 offset:56320
	global_load_lds_dwordx4 v[170:171], off
	s_add_i32 m0, s34, 0x2000
	s_add_u32 s30, s30, 0x200080
	v_lshl_add_u64 v[170:171], v[180:181], 0, s[82:83]
	s_addc_u32 s31, s31, 0
	s_add_i32 s34, s51, s2
	global_load_lds_dwordx4 v[170:171], off
	v_lshl_add_u64 v[170:171], s[30:31], 0, v[144:145]
	s_mov_b32 m0, s34
	s_nop 0
	global_load_lds_dwordx4 v[170:171], off
	v_lshl_add_u64 v[170:171], s[30:31], 0, v[160:161]
	s_add_i32 m0, s34, 0x2000
	s_nop 0
	global_load_lds_dwordx4 v[170:171], off
	v_lshl_add_u64 v[170:171], v[236:237], 0, s[82:83]
	s_mov_b32 m0, s9
	s_nop 0
	global_load_lds_dwordx4 v[170:171], off
	v_lshl_add_u64 v[170:171], v[238:239], 0, s[82:83]
	s_mov_b32 m0, s10
	s_nop 0
	global_load_lds_dwordx4 v[170:171], off
	s_waitcnt vmcnt(8)
	s_waitcnt lgkmcnt(0)
	s_barrier
	v_mfma_f32_16x16x32_bf16 v[60:63], v[104:107], v[204:207], v[60:63]
	v_mfma_f32_16x16x32_bf16 v[56:59], v[112:115], v[204:207], v[56:59]
	v_mfma_f32_16x16x32_bf16 v[48:51], v[104:107], v[212:215], v[48:51]
	v_mfma_f32_16x16x32_bf16 v[40:43], v[112:115], v[212:215], v[40:43]
	v_mfma_f32_16x16x32_bf16 v[32:35], v[104:107], v[220:223], v[32:35]
	v_mfma_f32_16x16x32_bf16 v[24:27], v[112:115], v[220:223], v[24:27]
	v_mfma_f32_16x16x32_bf16 v[16:19], v[104:107], v[228:231], v[16:19]
	v_mfma_f32_16x16x32_bf16 v[8:11], v[112:115], v[228:231], v[8:11]
	v_mfma_f32_16x16x32_bf16 v[60:63], v[108:111], v[208:211], v[60:63]
	v_mfma_f32_16x16x32_bf16 v[56:59], v[116:119], v[208:211], v[56:59]
	v_mfma_f32_16x16x32_bf16 v[48:51], v[108:111], v[216:219], v[48:51]
	v_mfma_f32_16x16x32_bf16 v[40:43], v[116:119], v[216:219], v[40:43]
	v_mfma_f32_16x16x32_bf16 v[32:35], v[108:111], v[224:227], v[32:35]
	v_mfma_f32_16x16x32_bf16 v[24:27], v[116:119], v[224:227], v[24:27]
	v_mfma_f32_16x16x32_bf16 v[16:19], v[108:111], v[232:235], v[16:19]
	v_mfma_f32_16x16x32_bf16 v[8:11], v[116:119], v[232:235], v[8:11]
	v_mfma_f32_16x16x32_bf16 v[52:55], v[176:179], v[204:207], v[52:55]
	v_mfma_f32_16x16x32_bf16 v[44:47], v[196:199], v[204:207], v[44:47]
	v_mfma_f32_16x16x32_bf16 v[36:39], v[176:179], v[212:215], v[36:39]
	v_mfma_f32_16x16x32_bf16 v[28:31], v[196:199], v[212:215], v[28:31]
	v_mfma_f32_16x16x32_bf16 v[20:23], v[176:179], v[220:223], v[20:23]
	v_mfma_f32_16x16x32_bf16 v[12:15], v[196:199], v[220:223], v[12:15]
	v_mfma_f32_16x16x32_bf16 v[4:7], v[176:179], v[228:231], v[4:7]
	v_mfma_f32_16x16x32_bf16 v[0:3], v[196:199], v[228:231], v[0:3]
	v_mfma_f32_16x16x32_bf16 v[52:55], v[192:195], v[208:211], v[52:55]
	v_mfma_f32_16x16x32_bf16 v[44:47], v[200:203], v[208:211], v[44:47]
	v_mfma_f32_16x16x32_bf16 v[36:39], v[192:195], v[216:219], v[36:39]
	v_mfma_f32_16x16x32_bf16 v[28:31], v[200:203], v[216:219], v[28:31]
	v_mfma_f32_16x16x32_bf16 v[20:23], v[192:195], v[224:227], v[20:23]
	v_mfma_f32_16x16x32_bf16 v[12:15], v[200:203], v[224:227], v[12:15]
	v_mfma_f32_16x16x32_bf16 v[4:7], v[192:195], v[232:235], v[4:7]
	v_mfma_f32_16x16x32_bf16 v[0:3], v[200:203], v[232:235], v[0:3]
	s_barrier
	s_add_i32 s49, s49, 2
	s_add_u32 s28, s28, 0x100
	s_addc_u32 s29, s29, 0
	s_add_u32 s47, s47, 0x100
	s_addc_u32 s48, s48, 0
	s_cmpk_gt_u32 s49, 0x7d
	s_cbranch_scc0 .LBB0_1161
	s_and_b64 vcc, exec, s[18:19]
	s_cbranch_vccz .LBB0_1164

; #define PG8_STAGE(bufoff, gbase, voff) do { _Pragma("unroll") for (int _i = 0; _i < 2; ++_i) \
;         __builtin_amdgcn_global_load_lds((const unsigned*)((const char*)(gbase) + (voff)[_i]), (LAS unsigned*)(lds + (bufoff) + ldsw + _i * 8192), 16, 0, 0); } while (0)
; #define PG8_LDA(dst, b, h) do { _Pragma("unroll") for (int m = 0; m < 4; ++m) _Pragma("unroll") for (int k = 0; k < 2; ++k) dst[m][k] = *(const LAS bf16x8*)(lds + PG8_SA(b, h) + aoff + m * 2048 + k * 1024); } while (0)
; #define PG8_LDB(dst, b, h) do { _Pragma("unroll") for (int n = 0; n < 2; ++n) _Pragma("unroll") for (int k = 0; k < 2; ++k) dst[n][k] = *(const LAS bf16x8*)(lds + PG8_SB(b, h) + boff + n * 2048 + k * 1024); } while (0)
; #define PG8_MMA(ai, bj, At, Bt) do { __builtin_amdgcn_s_setprio(1); _Pragma("unroll") for (int m = 0; m < 4; ++m) _Pragma("unroll") for (int n = 0; n < 2; ++n) _Pragma("unroll") for (int k = 0; k < 2; ++k) \
;         acc[ai][bj][m][n] = __builtin_amdgcn_mfma_f32_16x16x32_bf16(Bt[n][k], At[m][k], acc[ai][bj][m][n], 0, 0, 0); __builtin_amdgcn_s_setprio(0); } while (0)
; #define PG8_WAIT_V(n) asm volatile("s_waitcnt vmcnt(" #n ")" ::: "memory")
; #define PG8_WAIT_L(n) asm volatile("s_waitcnt lgkmcnt(" #n ")" ::: "memory")
; #define PG8_BAR __builtin_amdgcn_s_barrier()
; #define PG8_SCHED __builtin_amdgcn_sched_barrier(0)
; template <class Epi, class Map>
; __device__ __forceinline__ void gemm_phase(LAS unsigned char* lds, const Gemm g, const Sched<Map>& S, const Epi& E) {
;     ...
;         for (int t = 0; t < nt; t += 2) {
;             const bool last = (t == nt - 2);
;             const char* a1 = cA + (size_t)(t + 1) * kstep;
;             const char* a2 = last ? nA : cA + (size_t)(t + 2) * kstep; const char* b2 = last ? nB : cB + (size_t)(t + 2) * kstep;
;             const char* a3 = a2 + kstep; const char* b3 = b2 + kstep;
;             PG8_LDB(B0, 0, 0); PG8_LDB(B1, 0, 1); PG8_SCHED; PG8_LDA(At, 0, 0); PG8_STAGE(PG8_SA(1, 1), a1 + hstepA, voffA);
;             PG8_WAIT_V(8); PG8_WAIT_L(0); PG8_BAR; PG8_MMA(0, 0, At, B0); PG8_MMA(0, 1, At, B1); PG8_BAR; PG8_SCHED;
;             PG8_LDA(At, 0, 1); PG8_STAGE(PG8_SB(0, 0), b2, voffB); PG8_STAGE(PG8_SB(0, 1), b2 + hstepB, voffB); PG8_STAGE(PG8_SA(0, 0), a2, voffA);
.LBB0_1183:
	s_add_u32 s30, s28, 0xffe00080
	s_addc_u32 s31, s29, -1
	s_add_i32 s48, 0, 0x10000
	s_cmpk_eq_i32 s47, 0x7c
	s_cselect_b32 s35, s37, s31
	s_cselect_b32 s34, s40, s30
	s_cselect_b32 s31, s41, s46
	s_cselect_b32 s30, s44, s45
	s_add_i32 s50, 0, 0x14000
	v_add_u32_e32 v108, s48, v173
	v_add_u32_e32 v170, s50, v173
	ds_read_b128 v[64:67], v108
	ds_read_b128 v[68:71], v108 offset:1024
	ds_read_b128 v[72:75], v108 offset:2048
	ds_read_b128 v[108:111], v108 offset:3072
	ds_read_b128 v[166:169], v170
	ds_read_b128 v[176:179], v170 offset:1024
	ds_read_b128 v[192:195], v170 offset:2048
	ds_read_b128 v[196:199], v170 offset:3072
	v_lshl_add_u64 v[170:171], s[28:29], 0, v[162:163]
	s_add_i32 m0, s3, 0xc000
	ds_read_b128 v[200:203], v174
	ds_read_b128 v[204:207], v174 offset:1024
	ds_read_b128 v[208:211], v174 offset:2048
	ds_read_b128 v[212:215], v174 offset:3072
	ds_read_b128 v[216:219], v174 offset:4096
	ds_read_b128 v[220:223], v174 offset:5120
	ds_read_b128 v[224:227], v174 offset:6144
	ds_read_b128 v[228:231], v174 offset:7168
	global_load_lds_dwordx4 v[170:171], off
	v_lshl_add_u64 v[170:171], s[28:29], 0, v[164:165]
	s_add_i32 m0, s3, 0xe000
	s_nop 0
	global_load_lds_dwordx4 v[170:171], off
	s_waitcnt vmcnt(8)
	s_waitcnt lgkmcnt(0)
	s_barrier
	v_mfma_f32_16x16x32_bf16 v[140:143], v[64:67], v[200:203], v[140:143]
	v_mfma_f32_16x16x32_bf16 v[136:139], v[72:75], v[200:203], v[136:139]
	v_mfma_f32_16x16x32_bf16 v[132:135], v[64:67], v[208:211], v[132:135]
	v_mfma_f32_16x16x32_bf16 v[128:131], v[72:75], v[208:211], v[128:131]
	v_mfma_f32_16x16x32_bf16 v[104:107], v[64:67], v[216:219], v[104:107]
	v_mfma_f32_16x16x32_bf16 v[100:103], v[72:75], v[216:219], v[100:103]
	v_mfma_f32_16x16x32_bf16 v[96:99], v[64:67], v[224:227], v[96:99]
	v_mfma_f32_16x16x32_bf16 v[92:95], v[72:75], v[224:227], v[92:95]
	v_mfma_f32_16x16x32_bf16 v[140:143], v[68:71], v[204:207], v[140:143]
	v_mfma_f32_16x16x32_bf16 v[136:139], v[108:111], v[204:207], v[136:139]
	v_mfma_f32_16x16x32_bf16 v[132:135], v[68:71], v[212:215], v[132:135]
	v_mfma_f32_16x16x32_bf16 v[128:131], v[108:111], v[212:215], v[128:131]
	v_mfma_f32_16x16x32_bf16 v[104:107], v[68:71], v[220:223], v[104:107]
	v_mfma_f32_16x16x32_bf16 v[100:103], v[108:111], v[220:223], v[100:103]
	v_mfma_f32_16x16x32_bf16 v[96:99], v[68:71], v[228:231], v[96:99]
	v_mfma_f32_16x16x32_bf16 v[92:95], v[108:111], v[228:231], v[92:95]
	v_mfma_f32_16x16x32_bf16 v[124:127], v[166:169], v[200:203], v[124:127]
	v_mfma_f32_16x16x32_bf16 v[120:123], v[192:195], v[200:203], v[120:123]
	v_mfma_f32_16x16x32_bf16 v[116:119], v[166:169], v[208:211], v[116:119]
	v_mfma_f32_16x16x32_bf16 v[112:115], v[192:195], v[208:211], v[112:115]
	v_mfma_f32_16x16x32_bf16 v[88:91], v[166:169], v[216:219], v[88:91]
	v_mfma_f32_16x16x32_bf16 v[84:87], v[192:195], v[216:219], v[84:87]
	v_mfma_f32_16x16x32_bf16 v[80:83], v[166:169], v[224:227], v[80:83]
	v_mfma_f32_16x16x32_bf16 v[76:79], v[192:195], v[224:227], v[76:79]
	v_mfma_f32_16x16x32_bf16 v[124:127], v[176:179], v[204:207], v[124:127]
	v_mfma_f32_16x16x32_bf16 v[120:123], v[196:199], v[204:207], v[120:123]
	v_mfma_f32_16x16x32_bf16 v[116:119], v[176:179], v[212:215], v[116:119]
	v_mfma_f32_16x16x32_bf16 v[112:115], v[196:199], v[212:215], v[112:115]
	v_mfma_f32_16x16x32_bf16 v[88:91], v[176:179], v[220:223], v[88:91]
	v_mfma_f32_16x16x32_bf16 v[84:87], v[196:199], v[220:223], v[84:87]
	v_mfma_f32_16x16x32_bf16 v[80:83], v[176:179], v[228:231], v[80:83]
	v_mfma_f32_16x16x32_bf16 v[76:79], v[196:199], v[228:231], v[76:79]
	s_barrier
	s_add_i32 s48, s48, s2
	v_lshl_add_u64 v[170:171], s[30:31], 0, v[144:145]
	s_mov_b32 m0, s48
	ds_read_b128 v[200:203], v174 offset:16384
	ds_read_b128 v[204:207], v174 offset:17408
	ds_read_b128 v[208:211], v174 offset:18432
	ds_read_b128 v[212:215], v174 offset:19456
	ds_read_b128 v[216:219], v174 offset:20480
	ds_read_b128 v[220:223], v174 offset:21504
	ds_read_b128 v[224:227], v174 offset:22528
	ds_read_b128 v[228:231], v174 offset:23552
	global_load_lds_dwordx4 v[170:171], off
	s_add_i32 m0, s48, 0x2000
	s_add_u32 s48, s30, 0x200000
	v_lshl_add_u64 v[180:181], s[30:31], 0, v[160:161]
	s_addc_u32 s49, s31, 0
	s_add_i32 s50, s50, s2
	global_load_lds_dwordx4 v[180:181], off
	v_lshl_add_u64 v[232:233], s[48:49], 0, v[144:145]
	s_mov_b32 m0, s50
	v_lshl_add_u64 v[234:235], s[34:35], 0, v[160:161]
	global_load_lds_dwordx4 v[232:233], off
	v_lshl_add_u64 v[232:233], s[48:49], 0, v[160:161]
	s_add_i32 m0, s50, 0x2000
	s_nop 0
	global_load_lds_dwordx4 v[232:233], off
	v_lshl_add_u64 v[232:233], s[34:35], 0, v[144:145]
	s_mov_b32 m0, s3
	s_nop 0
	global_load_lds_dwordx4 v[232:233], off
	s_mov_b32 m0, s4
	s_nop 0
	global_load_lds_dwordx4 v[234:235], off
	s_waitcnt vmcnt(8)
	s_waitcnt lgkmcnt(0)
	s_barrier
; #define PG8_STAGE(bufoff, gbase, voff) do { _Pragma("unroll") for (int _i = 0; _i < 2; ++_i) \
;         __builtin_amdgcn_global_load_lds((const unsigned*)((const char*)(gbase) + (voff)[_i]), (LAS unsigned*)(lds + (bufoff) + ldsw + _i * 8192), 16, 0, 0); } while (0)
; #define PG8_LDA(dst, b, h) do { _Pragma("unroll") for (int m = 0; m < 4; ++m) _Pragma("unroll") for (int k = 0; k < 2; ++k) dst[m][k] = *(const LAS bf16x8*)(lds + PG8_SA(b, h) + aoff + m * 2048 + k * 1024); } while (0)
; #define PG8_LDB(dst, b, h) do { _Pragma("unroll") for (int n = 0; n < 2; ++n) _Pragma("unroll") for (int k = 0; k < 2; ++k) dst[n][k] = *(const LAS bf16x8*)(lds + PG8_SB(b, h) + boff + n * 2048 + k * 1024); } while (0)
; #define PG8_MMA(ai, bj, At, Bt) do { __builtin_amdgcn_s_setprio(1); _Pragma("unroll") for (int m = 0; m < 4; ++m) _Pragma("unroll") for (int n = 0; n < 2; ++n) _Pragma("unroll") for (int k = 0; k < 2; ++k) \
;         acc[ai][bj][m][n] = __builtin_amdgcn_mfma_f32_16x16x32_bf16(Bt[n][k], At[m][k], acc[ai][bj][m][n], 0, 0, 0); __builtin_amdgcn_s_setprio(0); } while (0)
; #define PG8_WAIT_V(n) asm volatile("s_waitcnt vmcnt(" #n ")" ::: "memory")
; #define PG8_WAIT_L(n) asm volatile("s_waitcnt lgkmcnt(" #n ")" ::: "memory")
; #define PG8_BAR __builtin_amdgcn_s_barrier()
; #define PG8_SCHED __builtin_amdgcn_sched_barrier(0)
; template <class Epi, class Map>
; __device__ __forceinline__ void gemm_phase(LAS unsigned char* lds, const Gemm g, const Sched<Map>& S, const Epi& E) {
;     ...
;             PG8_WAIT_V(8); PG8_WAIT_L(0); PG8_BAR; PG8_MMA(1, 0, At, B0); PG8_MMA(1, 1, At, B1); PG8_BAR; PG8_SCHED;
;             PG8_LDB(B0, 1, 0); PG8_LDB(B1, 1, 1); PG8_SCHED; PG8_LDA(At, 1, 0); PG8_STAGE(PG8_SA(0, 1), a2 + hstepA, voffA);
;             PG8_WAIT_V(8); PG8_WAIT_L(0); PG8_BAR; PG8_MMA(0, 0, At, B0); PG8_MMA(0, 1, At, B1); PG8_BAR; PG8_SCHED;
	v_mfma_f32_16x16x32_bf16 v[60:63], v[64:67], v[200:203], v[60:63]
	v_mfma_f32_16x16x32_bf16 v[56:59], v[72:75], v[200:203], v[56:59]
	v_mfma_f32_16x16x32_bf16 v[52:55], v[64:67], v[208:211], v[52:55]
	v_mfma_f32_16x16x32_bf16 v[48:51], v[72:75], v[208:211], v[48:51]
	v_mfma_f32_16x16x32_bf16 v[28:31], v[64:67], v[216:219], v[28:31]
	v_mfma_f32_16x16x32_bf16 v[24:27], v[72:75], v[216:219], v[24:27]
	v_mfma_f32_16x16x32_bf16 v[20:23], v[64:67], v[224:227], v[20:23]
	v_mfma_f32_16x16x32_bf16 v[8:11], v[72:75], v[224:227], v[8:11]
	v_mfma_f32_16x16x32_bf16 v[60:63], v[68:71], v[204:207], v[60:63]
	v_mfma_f32_16x16x32_bf16 v[56:59], v[108:111], v[204:207], v[56:59]
	v_mfma_f32_16x16x32_bf16 v[52:55], v[68:71], v[212:215], v[52:55]
	v_mfma_f32_16x16x32_bf16 v[48:51], v[108:111], v[212:215], v[48:51]
	v_mfma_f32_16x16x32_bf16 v[28:31], v[68:71], v[220:223], v[28:31]
	v_mfma_f32_16x16x32_bf16 v[24:27], v[108:111], v[220:223], v[24:27]
	v_mfma_f32_16x16x32_bf16 v[20:23], v[68:71], v[228:231], v[20:23]
	v_mfma_f32_16x16x32_bf16 v[8:11], v[108:111], v[228:231], v[8:11]
	v_mfma_f32_16x16x32_bf16 v[44:47], v[166:169], v[200:203], v[44:47]
	v_mfma_f32_16x16x32_bf16 v[40:43], v[192:195], v[200:203], v[40:43]
	v_mfma_f32_16x16x32_bf16 v[36:39], v[166:169], v[208:211], v[36:39]
	v_mfma_f32_16x16x32_bf16 v[32:35], v[192:195], v[208:211], v[32:35]
	v_mfma_f32_16x16x32_bf16 v[16:19], v[166:169], v[216:219], v[16:19]
	v_mfma_f32_16x16x32_bf16 v[12:15], v[192:195], v[216:219], v[12:15]
	v_mfma_f32_16x16x32_bf16 v[4:7], v[166:169], v[224:227], v[4:7]
	v_mfma_f32_16x16x32_bf16 v[0:3], v[192:195], v[224:227], v[0:3]
	v_mfma_f32_16x16x32_bf16 v[44:47], v[176:179], v[204:207], v[44:47]
	v_mfma_f32_16x16x32_bf16 v[40:43], v[196:199], v[204:207], v[40:43]
	v_mfma_f32_16x16x32_bf16 v[36:39], v[176:179], v[212:215], v[36:39]
	v_mfma_f32_16x16x32_bf16 v[32:35], v[196:199], v[212:215], v[32:35]
	v_mfma_f32_16x16x32_bf16 v[16:19], v[176:179], v[220:223], v[16:19]
	v_mfma_f32_16x16x32_bf16 v[12:15], v[196:199], v[220:223], v[12:15]
	v_mfma_f32_16x16x32_bf16 v[4:7], v[176:179], v[228:231], v[4:7]
	v_mfma_f32_16x16x32_bf16 v[0:3], v[196:199], v[228:231], v[0:3]
	s_barrier
	s_add_i32 s48, 0, 0x18000
	s_add_i32 s49, 0, 0x1c000
	v_add_u32_e32 v108, s48, v173
	v_add_u32_e32 v175, s49, v173
	ds_read_b128 v[64:67], v108
	ds_read_b128 v[68:71], v108 offset:1024
	ds_read_b128 v[72:75], v108 offset:2048
	ds_read_b128 v[108:111], v108 offset:3072
	ds_read_b128 v[166:169], v175
	ds_read_b128 v[176:179], v175 offset:1024
	ds_read_b128 v[192:195], v175 offset:2048
	ds_read_b128 v[196:199], v175 offset:3072
	s_add_u32 s34, s34, 0x200000
	s_addc_u32 s35, s35, 0
	s_mov_b32 m0, s5
	v_lshl_add_u64 v[236:237], s[34:35], 0, v[144:145]
	ds_read_b128 v[200:203], v174 offset:32768
	ds_read_b128 v[204:207], v174 offset:33792
	ds_read_b128 v[208:211], v174 offset:34816
	ds_read_b128 v[212:215], v174 offset:35840
	ds_read_b128 v[216:219], v174 offset:36864
	ds_read_b128 v[220:223], v174 offset:37888
	ds_read_b128 v[224:227], v174 offset:38912
	ds_read_b128 v[228:231], v174 offset:39936
	global_load_lds_dwordx4 v[236:237], off
	v_lshl_add_u64 v[236:237], s[34:35], 0, v[160:161]
	s_mov_b32 m0, s6
	s_nop 0
	global_load_lds_dwordx4 v[236:237], off
	s_waitcnt vmcnt(8)
	s_waitcnt lgkmcnt(0)
	s_barrier
	v_mfma_f32_16x16x32_bf16 v[140:143], v[64:67], v[200:203], v[140:143]
	v_mfma_f32_16x16x32_bf16 v[136:139], v[72:75], v[200:203], v[136:139]
	v_mfma_f32_16x16x32_bf16 v[132:135], v[64:67], v[208:211], v[132:135]
	v_mfma_f32_16x16x32_bf16 v[128:131], v[72:75], v[208:211], v[128:131]
	v_mfma_f32_16x16x32_bf16 v[104:107], v[64:67], v[216:219], v[104:107]
	v_mfma_f32_16x16x32_bf16 v[100:103], v[72:75], v[216:219], v[100:103]
	v_mfma_f32_16x16x32_bf16 v[96:99], v[64:67], v[224:227], v[96:99]
	v_mfma_f32_16x16x32_bf16 v[92:95], v[72:75], v[224:227], v[92:95]
	v_mfma_f32_16x16x32_bf16 v[140:143], v[68:71], v[204:207], v[140:143]
	v_mfma_f32_16x16x32_bf16 v[136:139], v[108:111], v[204:207], v[136:139]
	v_mfma_f32_16x16x32_bf16 v[132:135], v[68:71], v[212:215], v[132:135]
	v_mfma_f32_16x16x32_bf16 v[128:131], v[108:111], v[212:215], v[128:131]
	v_mfma_f32_16x16x32_bf16 v[104:107], v[68:71], v[220:223], v[104:107]
	v_mfma_f32_16x16x32_bf16 v[100:103], v[108:111], v[220:223], v[100:103]
	v_mfma_f32_16x16x32_bf16 v[96:99], v[68:71], v[228:231], v[96:99]
	v_mfma_f32_16x16x32_bf16 v[92:95], v[108:111], v[228:231], v[92:95]
	v_mfma_f32_16x16x32_bf16 v[124:127], v[166:169], v[200:203], v[124:127]
	v_mfma_f32_16x16x32_bf16 v[120:123], v[192:195], v[200:203], v[120:123]
	v_mfma_f32_16x16x32_bf16 v[116:119], v[166:169], v[208:211], v[116:119]
	v_mfma_f32_16x16x32_bf16 v[112:115], v[192:195], v[208:211], v[112:115]
	v_mfma_f32_16x16x32_bf16 v[88:91], v[166:169], v[216:219], v[88:91]
	v_mfma_f32_16x16x32_bf16 v[84:87], v[192:195], v[216:219], v[84:87]
	v_mfma_f32_16x16x32_bf16 v[80:83], v[166:169], v[224:227], v[80:83]
	v_mfma_f32_16x16x32_bf16 v[76:79], v[192:195], v[224:227], v[76:79]
	v_mfma_f32_16x16x32_bf16 v[124:127], v[176:179], v[204:207], v[124:127]
	v_mfma_f32_16x16x32_bf16 v[120:123], v[196:199], v[204:207], v[120:123]
	v_mfma_f32_16x16x32_bf16 v[116:119], v[176:179], v[212:215], v[116:119]
	v_mfma_f32_16x16x32_bf16 v[112:115], v[196:199], v[212:215], v[112:115]
	v_mfma_f32_16x16x32_bf16 v[88:91], v[176:179], v[220:223], v[88:91]
	v_mfma_f32_16x16x32_bf16 v[84:87], v[196:199], v[220:223], v[84:87]
	v_mfma_f32_16x16x32_bf16 v[80:83], v[176:179], v[228:231], v[80:83]
	v_mfma_f32_16x16x32_bf16 v[76:79], v[196:199], v[228:231], v[76:79]
	s_barrier
; #define PG8_STAGE(bufoff, gbase, voff) do { _Pragma("unroll") for (int _i = 0; _i < 2; ++_i) \
;         __builtin_amdgcn_global_load_lds((const unsigned*)((const char*)(gbase) + (voff)[_i]), (LAS unsigned*)(lds + (bufoff) + ldsw + _i * 8192), 16, 0, 0); } while (0)
; #define PG8_LDA(dst, b, h) do { _Pragma("unroll") for (int m = 0; m < 4; ++m) _Pragma("unroll") for (int k = 0; k < 2; ++k) dst[m][k] = *(const LAS bf16x8*)(lds + PG8_SA(b, h) + aoff + m * 2048 + k * 1024); } while (0)
; #define PG8_MMA(ai, bj, At, Bt) do { __builtin_amdgcn_s_setprio(1); _Pragma("unroll") for (int m = 0; m < 4; ++m) _Pragma("unroll") for (int n = 0; n < 2; ++n) _Pragma("unroll") for (int k = 0; k < 2; ++k) \
;         acc[ai][bj][m][n] = __builtin_amdgcn_mfma_f32_16x16x32_bf16(Bt[n][k], At[m][k], acc[ai][bj][m][n], 0, 0, 0); __builtin_amdgcn_s_setprio(0); } while (0)
; #define PG8_WAIT_V(n) asm volatile("s_waitcnt vmcnt(" #n ")" ::: "memory")
; #define PG8_WAIT_L(n) asm volatile("s_waitcnt lgkmcnt(" #n ")" ::: "memory")
; #define PG8_BAR __builtin_amdgcn_s_barrier()
; #define PG8_SCHED __builtin_amdgcn_sched_barrier(0)
; template <class Epi, class Map>
; __device__ __forceinline__ void gemm_phase(LAS unsigned char* lds, const Gemm g, const Sched<Map>& S, const Epi& E) {
;     ...
;             PG8_LDA(At, 1, 1); PG8_STAGE(PG8_SB(1, 0), b3, voffB); PG8_STAGE(PG8_SB(1, 1), b3 + hstepB, voffB); PG8_STAGE(PG8_SA(1, 0), a3, voffA);
;             PG8_WAIT_V(8); PG8_WAIT_L(0); PG8_BAR; PG8_MMA(1, 0, At, B0); PG8_MMA(1, 1, At, B1); PG8_BAR; PG8_SCHED;
;         }
;         if (wr == 0) PG8_BAR;
;         E(acc, cur, wr, wc, fr, fq);
;         if (!has_next) break;
	s_add_i32 s34, s48, s2
	v_lshl_add_u64 v[170:171], v[170:171], 0, s[82:83]
	s_mov_b32 m0, s34
	ds_read_b128 v[200:203], v174 offset:49152
	ds_read_b128 v[204:207], v174 offset:50176
	ds_read_b128 v[208:211], v174 offset:51200
	ds_read_b128 v[212:215], v174 offset:52224
	ds_read_b128 v[216:219], v174 offset:53248
	ds_read_b128 v[220:223], v174 offset:54272
	ds_read_b128 v[224:227], v174 offset:55296
	ds_read_b128 v[228:231], v174 offset:56320
	global_load_lds_dwordx4 v[170:171], off
	s_add_i32 m0, s34, 0x2000
	s_add_u32 s30, s30, 0x200080
	v_lshl_add_u64 v[170:171], v[180:181], 0, s[82:83]
	s_addc_u32 s31, s31, 0
	s_add_i32 s34, s49, s2
	global_load_lds_dwordx4 v[170:171], off
	v_lshl_add_u64 v[170:171], s[30:31], 0, v[144:145]
	s_mov_b32 m0, s34
	s_nop 0
	global_load_lds_dwordx4 v[170:171], off
	v_lshl_add_u64 v[170:171], s[30:31], 0, v[160:161]
	s_add_i32 m0, s34, 0x2000
	s_nop 0
	global_load_lds_dwordx4 v[170:171], off
	v_lshl_add_u64 v[170:171], v[232:233], 0, s[82:83]
	s_mov_b32 m0, s9
	s_nop 0
	global_load_lds_dwordx4 v[170:171], off
	v_lshl_add_u64 v[170:171], v[234:235], 0, s[82:83]
	s_mov_b32 m0, s10
	s_nop 0
	global_load_lds_dwordx4 v[170:171], off
	s_waitcnt vmcnt(8)
	s_waitcnt lgkmcnt(0)
	s_barrier
	v_mfma_f32_16x16x32_bf16 v[60:63], v[64:67], v[200:203], v[60:63]
	v_mfma_f32_16x16x32_bf16 v[56:59], v[72:75], v[200:203], v[56:59]
	v_mfma_f32_16x16x32_bf16 v[52:55], v[64:67], v[208:211], v[52:55]
	v_mfma_f32_16x16x32_bf16 v[48:51], v[72:75], v[208:211], v[48:51]
	v_mfma_f32_16x16x32_bf16 v[28:31], v[64:67], v[216:219], v[28:31]
	v_mfma_f32_16x16x32_bf16 v[24:27], v[72:75], v[216:219], v[24:27]
	v_mfma_f32_16x16x32_bf16 v[20:23], v[64:67], v[224:227], v[20:23]
	v_mfma_f32_16x16x32_bf16 v[8:11], v[72:75], v[224:227], v[8:11]
	v_mfma_f32_16x16x32_bf16 v[60:63], v[68:71], v[204:207], v[60:63]
	v_mfma_f32_16x16x32_bf16 v[56:59], v[108:111], v[204:207], v[56:59]
	v_mfma_f32_16x16x32_bf16 v[52:55], v[68:71], v[212:215], v[52:55]
	v_mfma_f32_16x16x32_bf16 v[48:51], v[108:111], v[212:215], v[48:51]
	v_mfma_f32_16x16x32_bf16 v[28:31], v[68:71], v[220:223], v[28:31]
	v_mfma_f32_16x16x32_bf16 v[24:27], v[108:111], v[220:223], v[24:27]
	v_mfma_f32_16x16x32_bf16 v[20:23], v[68:71], v[228:231], v[20:23]
	v_mfma_f32_16x16x32_bf16 v[8:11], v[108:111], v[228:231], v[8:11]
	v_mfma_f32_16x16x32_bf16 v[44:47], v[166:169], v[200:203], v[44:47]
	v_mfma_f32_16x16x32_bf16 v[40:43], v[192:195], v[200:203], v[40:43]
	v_mfma_f32_16x16x32_bf16 v[36:39], v[166:169], v[208:211], v[36:39]
	v_mfma_f32_16x16x32_bf16 v[32:35], v[192:195], v[208:211], v[32:35]
	v_mfma_f32_16x16x32_bf16 v[16:19], v[166:169], v[216:219], v[16:19]
	v_mfma_f32_16x16x32_bf16 v[12:15], v[192:195], v[216:219], v[12:15]
	v_mfma_f32_16x16x32_bf16 v[4:7], v[166:169], v[224:227], v[4:7]
	v_mfma_f32_16x16x32_bf16 v[0:3], v[192:195], v[224:227], v[0:3]
	v_mfma_f32_16x16x32_bf16 v[44:47], v[176:179], v[204:207], v[44:47]
	v_mfma_f32_16x16x32_bf16 v[40:43], v[196:199], v[204:207], v[40:43]
	v_mfma_f32_16x16x32_bf16 v[36:39], v[176:179], v[212:215], v[36:39]
	v_mfma_f32_16x16x32_bf16 v[32:35], v[196:199], v[212:215], v[32:35]
	v_mfma_f32_16x16x32_bf16 v[16:19], v[176:179], v[220:223], v[16:19]
	v_mfma_f32_16x16x32_bf16 v[12:15], v[196:199], v[220:223], v[12:15]
	v_mfma_f32_16x16x32_bf16 v[4:7], v[176:179], v[228:231], v[4:7]
	v_mfma_f32_16x16x32_bf16 v[0:3], v[196:199], v[228:231], v[0:3]
	s_barrier
	s_add_i32 s47, s47, 2
	s_add_u32 s28, s28, 0x100
	s_addc_u32 s29, s29, 0
	s_add_u32 s45, s45, 0x100
	s_addc_u32 s46, s46, 0
	s_cmpk_gt_u32 s47, 0x7d
	s_cbranch_scc0 .LBB0_1183
	s_and_b64 vcc, exec, s[18:19]
	s_cbranch_vccz .LBB0_1186
